# scanner registers arranged against VGPR bank conflicts; rwkv prep step 1: previous-row load no longer waited inside its branch, token-shift coefficient kept in a register
# baseline (speedup 1.0000x reference)
; __device__ __forceinline__ unsigned pk2(float lo, float hi) { f32x2_t v = {lo, hi}; bf16x2_t b = __builtin_convertvector(v, bf16x2_t); return __builtin_bit_cast(unsigned, b); }
; __device__ __forceinline__ void rwkv_prep_part(const Args& a, int l, unsigned char* lds) {
;     ...
;     const int lane = tid & 63, c = tid & 255, half = tid >> 8, h = c >> 6, cc = c & 63;
;     const float* mu = in_I_MU + (size_t)l * RW;
;     const float mur = mu[c], muk = mu[256 + c], muv = mu[512 + c];
;     const float w0c = in_I_W0[l * 256 + c], a0c = in_I_A0[l * 256 + c], kkc = in_I_KK[l * 256 + c], kac = in_I_KA[l * 256 + c], rkc = in_I_RK[l * 256 + c];
;     unsigned w2p[16], a2p[16], g2p[32];
; #pragma unroll
;     for (int i = 0; i < 16; ++i) { w2p[i] = pk2(in_I_W2[(size_t)(l * 32 + 2 * i) * 256 + c], in_I_W2[(size_t)(l * 32 + 2 * i + 1) * 256 + c]);
;                                    a2p[i] = pk2(in_I_A2[(size_t)(l * 32 + 2 * i) * 256 + c], in_I_A2[(size_t)(l * 32 + 2 * i + 1) * 256 + c]); }
.LBB0_487:
	s_or_b64 exec, exec, s[4:5]
	v_readlane_b32 s4, v255, 4
	v_readlane_b32 s5, v255, 5
	v_readlane_b32 s6, v253, 38
	s_lshl_b32 s50, s4, 8
	s_lshl_b32 s51, s4, 14
	v_readlane_b32 s4, v253, 2
	v_readlane_b32 s7, v253, 39
	v_mov_b32_e32 v10, v172
	v_readlane_b32 s5, v253, 3
	s_andn2_b64 vcc, exec, s[6:7]
	s_cbranch_vccnz .LBB0_587
	s_load_dwordx4 s[28:31], s[4:5], 0xe0
	s_load_dwordx16 s[12:27], s[4:5], 0x80
	v_readlane_b32 s6, v255, 4
	s_mul_i32 s78, s6, 0x380
	s_load_dwordx2 s[10:11], s[4:5], 0xc0
	s_load_dwordx2 s[8:9], s[4:5], 0x28
	s_lshl_b64 s[4:5], s[78:79], 2
	v_readlane_b32 s7, v255, 5
	s_mov_b32 s0, s6
	v_and_b32_e32 v0, 0xff, v10
	s_waitcnt lgkmcnt(0)
	s_add_u32 s6, s12, s4
	s_addc_u32 s7, s13, s5
	v_lshlrev_b32_e32 v4, 2, v0
	v_or_b32_e32 v140, s50, v0
	global_load_dword v1, v4, s[6:7]
	global_load_dword v24, v4, s[6:7] offset:1024
	global_load_dword v25, v4, s[6:7] offset:2048
	v_lshlrev_b64 v[4:5], 2, v[140:141]
	v_lshl_add_u64 v[6:7], s[14:15], 0, v[4:5]
	global_load_dword v26, v[6:7], off
	v_lshl_add_u64 v[6:7], s[18:19], 0, v[4:5]
	global_load_dword v27, v[6:7], off
	v_lshl_add_u64 v[6:7], s[24:25], 0, v[4:5]
	global_load_dword v28, v[6:7], off
	v_lshl_add_u64 v[6:7], s[26:27], 0, v[4:5]
	v_lshl_add_u64 v[4:5], s[10:11], 0, v[4:5]
	v_lshl_or_b32 v140, s0, 13, v0
	global_load_dword v30, v[4:5], off
	v_lshlrev_b64 v[4:5], 2, v[140:141]
	global_load_dword v29, v[6:7], off
	v_lshl_add_u64 v[6:7], s[16:17], 0, v[4:5]
	global_load_dword v204, v[6:7], off
	global_load_dword v205, v[6:7], off offset:1024
	v_lshl_add_u64 v[4:5], s[20:21], 0, v[4:5]
	v_mov_b32_e32 v2, s22
	v_mov_b32_e32 v3, s23
	s_movk_i32 s0, 0x1000
	s_add_u32 s4, s30, 0x9180000
	s_addc_u32 s5, s31, 0
	v_bfe_u32 v94, v10, 6, 2
	v_add_u32_e32 v13, 0x200, v10
	v_ashrrev_i32_e32 v12, 5, v10
	v_ashrrev_i32_e32 v97, 7, v10
	v_lshl_add_u32 v99, v10, 1, 0
	v_ashrrev_i32_e32 v100, 7, v13
	v_add_u32_e32 v13, 0x400, v10
	v_and_b32_e32 v95, -8, v12
	v_and_b32_e32 v96, 8, v12
	v_ashrrev_i32_e32 v102, 7, v13
	v_lshl_or_b32 v14, v12, 8, v181
	v_and_b32_e32 v98, 15, v97
	v_and_b32_e32 v101, 15, v100
	v_and_b32_e32 v103, 15, v102
	v_lshl_add_u32 v106, v95, 8, 0
	v_add_u32_e32 v107, 0, v14
	v_readlane_b32 s24, v254, 19
	global_load_dword v206, v[4:5], off
	global_load_dword v207, v[4:5], off offset:1024
	global_load_dword v208, v[6:7], off offset:2048
	s_nop 0
	global_load_dword v209, v[6:7], off offset:3072
	global_load_dword v210, v[4:5], off offset:2048
	s_nop 0
	global_load_dword v211, v[4:5], off offset:3072
	v_mov_b32_e32 v5, v141
	v_or_b32_e32 v4, 0x400, v140
	v_lshlrev_b64 v[4:5], 2, v[4:5]
	v_lshl_add_u64 v[6:7], s[16:17], 0, v[4:5]
	global_load_dword v212, v[6:7], off
	v_or_b32_e32 v6, 0x500, v140
	v_mov_b32_e32 v7, v141
	v_lshlrev_b64 v[6:7], 2, v[6:7]
	v_lshl_add_u64 v[8:9], s[16:17], 0, v[6:7]
	global_load_dword v213, v[8:9], off
	v_lshl_add_u64 v[4:5], s[20:21], 0, v[4:5]
	global_load_dword v214, v[4:5], off
	v_lshl_add_u64 v[4:5], s[20:21], 0, v[6:7]
	global_load_dword v215, v[4:5], off
	v_mov_b32_e32 v5, v141
	v_or_b32_e32 v4, 0x600, v140
	v_lshlrev_b64 v[4:5], 2, v[4:5]
	v_lshl_add_u64 v[6:7], s[16:17], 0, v[4:5]
	global_load_dword v216, v[6:7], off
	v_or_b32_e32 v6, 0x700, v140
	v_mov_b32_e32 v7, v141
	v_lshlrev_b64 v[6:7], 2, v[6:7]
	v_lshl_add_u64 v[8:9], s[16:17], 0, v[6:7]
	global_load_dword v217, v[8:9], off
	v_lshl_add_u64 v[4:5], s[20:21], 0, v[4:5]
	global_load_dword v218, v[4:5], off
	v_lshl_add_u64 v[4:5], s[20:21], 0, v[6:7]
	global_load_dword v219, v[4:5], off
	v_mov_b32_e32 v5, v141
	v_or_b32_e32 v4, 0x800, v140
	v_lshlrev_b64 v[4:5], 2, v[4:5]
	v_lshl_add_u64 v[6:7], s[16:17], 0, v[4:5]
	global_load_dword v220, v[6:7], off
	v_or_b32_e32 v6, 0x900, v140
	v_mov_b32_e32 v7, v141
	v_lshlrev_b64 v[6:7], 2, v[6:7]
	v_lshl_add_u64 v[8:9], s[16:17], 0, v[6:7]
	global_load_dword v221, v[8:9], off
	v_lshl_add_u64 v[4:5], s[20:21], 0, v[4:5]
	global_load_dword v222, v[4:5], off
	v_lshl_add_u64 v[4:5], s[20:21], 0, v[6:7]
	global_load_dword v223, v[4:5], off
	v_mov_b32_e32 v5, v141
	v_or_b32_e32 v4, 0xa00, v140
	v_lshlrev_b64 v[4:5], 2, v[4:5]
	v_lshl_add_u64 v[6:7], s[16:17], 0, v[4:5]
	global_load_dword v224, v[6:7], off
	v_or_b32_e32 v6, 0xb00, v140
	v_mov_b32_e32 v7, v141
	v_lshlrev_b64 v[6:7], 2, v[6:7]
	v_lshl_add_u64 v[8:9], s[16:17], 0, v[6:7]
	global_load_dword v225, v[8:9], off
	v_lshl_add_u64 v[4:5], s[20:21], 0, v[4:5]
	global_load_dword v226, v[4:5], off
	v_lshl_add_u64 v[4:5], s[20:21], 0, v[6:7]
	global_load_dword v227, v[4:5], off
	v_mov_b32_e32 v5, v141
	v_or_b32_e32 v4, 0xc00, v140
	v_lshlrev_b64 v[4:5], 2, v[4:5]
	v_lshl_add_u64 v[6:7], s[16:17], 0, v[4:5]
	global_load_dword v228, v[6:7], off
	v_or_b32_e32 v6, 0xd00, v140
	v_mov_b32_e32 v7, v141
	v_lshlrev_b64 v[6:7], 2, v[6:7]
	v_lshl_add_u64 v[8:9], s[16:17], 0, v[6:7]
	global_load_dword v229, v[8:9], off
	v_lshl_add_u64 v[4:5], s[20:21], 0, v[4:5]
	global_load_dword v230, v[4:5], off
	v_lshl_add_u64 v[4:5], s[20:21], 0, v[6:7]
	global_load_dword v231, v[4:5], off
	v_mov_b32_e32 v5, v141
	v_or_b32_e32 v4, 0xe00, v140
	v_lshlrev_b64 v[4:5], 2, v[4:5]
	v_lshl_add_u64 v[6:7], s[16:17], 0, v[4:5]
	global_load_dword v232, v[6:7], off
	v_or_b32_e32 v6, 0xf00, v140
	v_mov_b32_e32 v7, v141
	v_lshlrev_b64 v[6:7], 2, v[6:7]
	v_lshl_add_u64 v[8:9], s[16:17], 0, v[6:7]
	global_load_dword v233, v[8:9], off
	v_lshl_add_u64 v[4:5], s[20:21], 0, v[4:5]
	global_load_dword v234, v[4:5], off
	v_lshl_add_u64 v[4:5], s[20:21], 0, v[6:7]
	global_load_dword v235, v[4:5], off
	v_mov_b32_e32 v5, v141
	s_waitcnt vmcnt(0)
; __device__ __forceinline__ unsigned pk2(float lo, float hi) { f32x2_t v = {lo, hi}; bf16x2_t b = __builtin_convertvector(v, bf16x2_t); return __builtin_bit_cast(unsigned, b); }
; __device__ __forceinline__ void rwkv_prep_part(const Args& a, int l, unsigned char* lds) {
;     ...
;     unsigned w2p[16], a2p[16], g2p[32];
; #pragma unroll
;     for (int i = 0; i < 16; ++i) { w2p[i] = pk2(in_I_W2[(size_t)(l * 32 + 2 * i) * 256 + c], in_I_W2[(size_t)(l * 32 + 2 * i + 1) * 256 + c]);
;                                    a2p[i] = pk2(in_I_A2[(size_t)(l * 32 + 2 * i) * 256 + c], in_I_A2[(size_t)(l * 32 + 2 * i + 1) * 256 + c]); }
; #pragma unroll
;     for (int i = 0; i < 32; ++i) g2p[i] = pk2(in_I_G2[(size_t)(l * 64 + 2 * i) * 256 + c], in_I_G2[(size_t)(l * 64 + 2 * i + 1) * 256 + c]);
	v_cvt_pk_bf16_f32 v31, v204, v205
	v_cvt_pk_bf16_f32 v32, v206, v207
	v_cvt_pk_bf16_f32 v33, v208, v209
	v_cvt_pk_bf16_f32 v34, v210, v211
	v_cvt_pk_bf16_f32 v35, v212, v213
	v_cvt_pk_bf16_f32 v36, v214, v215
	v_cvt_pk_bf16_f32 v37, v216, v217
	v_cvt_pk_bf16_f32 v38, v218, v219
	v_cvt_pk_bf16_f32 v39, v220, v221
	v_cvt_pk_bf16_f32 v40, v222, v223
	v_cvt_pk_bf16_f32 v41, v224, v225
	v_cvt_pk_bf16_f32 v42, v226, v227
	v_cvt_pk_bf16_f32 v43, v228, v229
	v_cvt_pk_bf16_f32 v44, v230, v231
	v_cvt_pk_bf16_f32 v45, v232, v233
	v_cvt_pk_bf16_f32 v46, v234, v235
	v_or_b32_e32 v4, 0x1000, v140
	v_lshlrev_b64 v[4:5], 2, v[4:5]
	v_lshl_add_u64 v[6:7], s[16:17], 0, v[4:5]
	global_load_dword v204, v[6:7], off
	v_or_b32_e32 v6, 0x1100, v140
	v_mov_b32_e32 v7, v141
	v_lshlrev_b64 v[6:7], 2, v[6:7]
	v_lshl_add_u64 v[8:9], s[16:17], 0, v[6:7]
	global_load_dword v205, v[8:9], off
	v_lshl_add_u64 v[4:5], s[20:21], 0, v[4:5]
	global_load_dword v206, v[4:5], off
	v_lshl_add_u64 v[4:5], s[20:21], 0, v[6:7]
	global_load_dword v207, v[4:5], off
	v_mov_b32_e32 v5, v141
	v_or_b32_e32 v4, 0x1200, v140
	v_lshlrev_b64 v[4:5], 2, v[4:5]
	v_lshl_add_u64 v[6:7], s[16:17], 0, v[4:5]
	global_load_dword v208, v[6:7], off
	v_or_b32_e32 v6, 0x1300, v140
	v_mov_b32_e32 v7, v141
	v_lshlrev_b64 v[6:7], 2, v[6:7]
	v_lshl_add_u64 v[8:9], s[16:17], 0, v[6:7]
	global_load_dword v209, v[8:9], off
	v_lshl_add_u64 v[4:5], s[20:21], 0, v[4:5]
	global_load_dword v210, v[4:5], off
	v_lshl_add_u64 v[4:5], s[20:21], 0, v[6:7]
	global_load_dword v211, v[4:5], off
	v_mov_b32_e32 v5, v141
	v_or_b32_e32 v4, 0x1400, v140
	v_lshlrev_b64 v[4:5], 2, v[4:5]
	v_lshl_add_u64 v[6:7], s[16:17], 0, v[4:5]
	global_load_dword v212, v[6:7], off
	v_or_b32_e32 v6, 0x1500, v140
	v_mov_b32_e32 v7, v141
	v_lshlrev_b64 v[6:7], 2, v[6:7]
	v_lshl_add_u64 v[8:9], s[16:17], 0, v[6:7]
	global_load_dword v213, v[8:9], off
	v_lshl_add_u64 v[4:5], s[20:21], 0, v[4:5]
	global_load_dword v214, v[4:5], off
	v_lshl_add_u64 v[4:5], s[20:21], 0, v[6:7]
	global_load_dword v215, v[4:5], off
	v_mov_b32_e32 v5, v141
	v_or_b32_e32 v4, 0x1600, v140
	v_lshlrev_b64 v[4:5], 2, v[4:5]
	v_lshl_add_u64 v[6:7], s[16:17], 0, v[4:5]
	global_load_dword v216, v[6:7], off
	v_or_b32_e32 v6, 0x1700, v140
	v_mov_b32_e32 v7, v141
	v_lshlrev_b64 v[6:7], 2, v[6:7]
	v_lshl_add_u64 v[8:9], s[16:17], 0, v[6:7]
	global_load_dword v217, v[8:9], off
	v_lshl_add_u64 v[4:5], s[20:21], 0, v[4:5]
	global_load_dword v218, v[4:5], off
	v_lshl_add_u64 v[4:5], s[20:21], 0, v[6:7]
	global_load_dword v219, v[4:5], off
	v_mov_b32_e32 v5, v141
	v_or_b32_e32 v4, 0x1800, v140
	v_lshlrev_b64 v[4:5], 2, v[4:5]
	v_lshl_add_u64 v[6:7], s[16:17], 0, v[4:5]
	global_load_dword v220, v[6:7], off
	v_or_b32_e32 v6, 0x1900, v140
	v_mov_b32_e32 v7, v141
	v_lshlrev_b64 v[6:7], 2, v[6:7]
	v_lshl_add_u64 v[8:9], s[16:17], 0, v[6:7]
	global_load_dword v221, v[8:9], off
	v_lshl_add_u64 v[4:5], s[20:21], 0, v[4:5]
	global_load_dword v222, v[4:5], off
	v_lshl_add_u64 v[4:5], s[20:21], 0, v[6:7]
	global_load_dword v223, v[4:5], off
	v_mov_b32_e32 v5, v141
	v_or_b32_e32 v4, 0x1a00, v140
	v_lshlrev_b64 v[4:5], 2, v[4:5]
	v_lshl_add_u64 v[6:7], s[16:17], 0, v[4:5]
	global_load_dword v224, v[6:7], off
	v_or_b32_e32 v6, 0x1b00, v140
	v_mov_b32_e32 v7, v141
	v_lshlrev_b64 v[6:7], 2, v[6:7]
	v_lshl_add_u64 v[8:9], s[16:17], 0, v[6:7]
	global_load_dword v225, v[8:9], off
	v_lshl_add_u64 v[4:5], s[20:21], 0, v[4:5]
	global_load_dword v226, v[4:5], off
	v_lshl_add_u64 v[4:5], s[20:21], 0, v[6:7]
	global_load_dword v227, v[4:5], off
	v_mov_b32_e32 v5, v141
	v_or_b32_e32 v4, 0x1c00, v140
	v_lshlrev_b64 v[4:5], 2, v[4:5]
	v_lshl_add_u64 v[6:7], s[16:17], 0, v[4:5]
	global_load_dword v228, v[6:7], off
	v_or_b32_e32 v6, 0x1d00, v140
	v_mov_b32_e32 v7, v141
	v_lshlrev_b64 v[6:7], 2, v[6:7]
	v_lshl_add_u64 v[8:9], s[16:17], 0, v[6:7]
	global_load_dword v229, v[8:9], off
	v_lshl_add_u64 v[4:5], s[20:21], 0, v[4:5]
	global_load_dword v230, v[4:5], off
	v_lshl_add_u64 v[4:5], s[20:21], 0, v[6:7]
	global_load_dword v231, v[4:5], off
	v_mov_b32_e32 v5, v141
	v_or_b32_e32 v4, 0x1e00, v140
	v_lshlrev_b64 v[4:5], 2, v[4:5]
	v_lshl_add_u64 v[6:7], s[16:17], 0, v[4:5]
	v_or_b32_e32 v140, 0x1f00, v140
	global_load_dword v232, v[6:7], off
	v_lshlrev_b64 v[6:7], 2, v[140:141]
	v_lshl_add_u64 v[8:9], s[16:17], 0, v[6:7]
	global_load_dword v233, v[8:9], off
	v_lshl_add_u64 v[4:5], s[20:21], 0, v[4:5]
	v_or_b32_e32 v140, s51, v0
	v_lshl_add_u64 v[2:3], v[140:141], 2, v[2:3]
	global_load_dword v234, v[4:5], off
	v_lshl_add_u64 v[4:5], s[20:21], 0, v[6:7]
	global_load_dword v235, v[4:5], off
	v_and_b32_e32 v11, 63, v10
	s_add_u32 s20, s28, 0x10352000
	s_addc_u32 s21, s29, 0
	v_cmp_eq_u32_e64 s[14:15], 0, v11
	s_add_u32 s22, s28, 0x10180000
	s_addc_u32 s23, s29, 0
	s_waitcnt vmcnt(0)
; __device__ __forceinline__ unsigned pk2(float lo, float hi) { f32x2_t v = {lo, hi}; bf16x2_t b = __builtin_convertvector(v, bf16x2_t); return __builtin_bit_cast(unsigned, b); }
; __device__ __forceinline__ void rwkv_prep_part(const Args& a, int l, unsigned char* lds) {
;     ...
;     for (int i = 0; i < 16; ++i) { w2p[i] = pk2(in_I_W2[(size_t)(l * 32 + 2 * i) * 256 + c], in_I_W2[(size_t)(l * 32 + 2 * i + 1) * 256 + c]);
;                                    a2p[i] = pk2(in_I_A2[(size_t)(l * 32 + 2 * i) * 256 + c], in_I_A2[(size_t)(l * 32 + 2 * i + 1) * 256 + c]); }
; #pragma unroll
;     for (int i = 0; i < 32; ++i) g2p[i] = pk2(in_I_G2[(size_t)(l * 64 + 2 * i) * 256 + c], in_I_G2[(size_t)(l * 64 + 2 * i + 1) * 256 + c]);
	v_cvt_pk_bf16_f32 v47, v204, v205
	v_cvt_pk_bf16_f32 v48, v206, v207
	v_cvt_pk_bf16_f32 v49, v208, v209
	v_cvt_pk_bf16_f32 v50, v210, v211
	v_cvt_pk_bf16_f32 v51, v212, v213
	v_cvt_pk_bf16_f32 v52, v214, v215
	v_cvt_pk_bf16_f32 v53, v216, v217
	v_cvt_pk_bf16_f32 v54, v218, v219
	v_cvt_pk_bf16_f32 v55, v220, v221
	v_cvt_pk_bf16_f32 v56, v222, v223
	v_cvt_pk_bf16_f32 v57, v224, v225
	v_cvt_pk_bf16_f32 v58, v226, v227
	v_cvt_pk_bf16_f32 v59, v228, v229
	v_cvt_pk_bf16_f32 v60, v230, v231
	v_cvt_pk_bf16_f32 v61, v232, v233
	v_cvt_pk_bf16_f32 v62, v234, v235
	global_load_dword v204, v[2:3], off
	global_load_dword v205, v[2:3], off offset:1024
	global_load_dword v206, v[2:3], off offset:2048
	global_load_dword v207, v[2:3], off offset:3072
	v_add_co_u32_e32 v4, vcc, s0, v2
	s_movk_i32 s0, 0x2000
	s_nop 0
	v_addc_co_u32_e32 v5, vcc, 0, v3, vcc
	v_add_co_u32_e32 v6, vcc, s0, v2
	s_movk_i32 s0, 0x3000
	s_nop 0
	v_addc_co_u32_e32 v7, vcc, 0, v3, vcc
	global_load_dword v208, v[6:7], off offset:-4096
	global_load_dword v209, v[4:5], off offset:1024
	global_load_dword v210, v[4:5], off offset:2048
	s_nop 0
	global_load_dword v211, v[4:5], off offset:3072
	global_load_dword v212, v[6:7], off
	global_load_dword v213, v[6:7], off offset:1024
	global_load_dword v214, v[6:7], off offset:2048
	global_load_dword v215, v[6:7], off offset:3072
	v_add_co_u32_e32 v4, vcc, s0, v2
	s_movk_i32 s0, 0x4000
	s_nop 0
	v_addc_co_u32_e32 v5, vcc, 0, v3, vcc
	v_add_co_u32_e32 v6, vcc, s0, v2
	s_movk_i32 s0, 0x5000
	s_nop 0
	v_addc_co_u32_e32 v7, vcc, 0, v3, vcc
	global_load_dword v216, v[6:7], off offset:-4096
	global_load_dword v217, v[4:5], off offset:1024
	global_load_dword v218, v[4:5], off offset:2048
	s_nop 0
	global_load_dword v219, v[4:5], off offset:3072
	global_load_dword v220, v[6:7], off
	global_load_dword v221, v[6:7], off offset:1024
	global_load_dword v222, v[6:7], off offset:2048
	global_load_dword v223, v[6:7], off offset:3072
	v_add_co_u32_e32 v4, vcc, s0, v2
	s_movk_i32 s0, 0x6000
	s_nop 0
	v_addc_co_u32_e32 v5, vcc, 0, v3, vcc
	v_add_co_u32_e32 v6, vcc, s0, v2
	s_movk_i32 s0, 0x7000
	s_nop 0
	v_addc_co_u32_e32 v7, vcc, 0, v3, vcc
	global_load_dword v224, v[6:7], off offset:-4096
	global_load_dword v225, v[4:5], off offset:1024
	global_load_dword v226, v[4:5], off offset:2048
	s_nop 0
	global_load_dword v227, v[4:5], off offset:3072
	global_load_dword v228, v[6:7], off
	global_load_dword v229, v[6:7], off offset:1024
	global_load_dword v230, v[6:7], off offset:2048
	global_load_dword v231, v[6:7], off offset:3072
	v_add_co_u32_e32 v4, vcc, s0, v2
	s_mov_b32 s0, 0x9000
	s_nop 0
	v_addc_co_u32_e32 v5, vcc, 0, v3, vcc
	v_add_co_u32_e32 v6, vcc, s90, v2
	s_nop 1
	v_addc_co_u32_e32 v7, vcc, 0, v3, vcc
	global_load_dword v232, v[6:7], off offset:-4096
	global_load_dword v233, v[4:5], off offset:1024
	global_load_dword v234, v[4:5], off offset:2048
	s_nop 0
	global_load_dword v235, v[4:5], off offset:3072
	s_waitcnt vmcnt(0)
; __device__ __forceinline__ unsigned pk2(float lo, float hi) { f32x2_t v = {lo, hi}; bf16x2_t b = __builtin_convertvector(v, bf16x2_t); return __builtin_bit_cast(unsigned, b); }
; __device__ __forceinline__ float ldbf(const bf16* p) { return bf2f((unsigned)*p); }
; __device__ __forceinline__ void rwkv_prep_part(const Args& a, int l, unsigned char* lds) {
;     ...
; #pragma unroll
;     for (int i = 0; i < 32; ++i) g2p[i] = pk2(in_I_G2[(size_t)(l * 64 + 2 * i) * 256 + c], in_I_G2[(size_t)(l * 64 + 2 * i + 1) * 256 + c]);
;     constexpr int TPI = 16, TPH = 8;
;     const bool x8 = (gridDim.x & 7) == 0;
;     constexpr int IPS = T / TPI;
;     const int xcd_ = (int)blockIdx.x & 7, j_ = x8 ? ((int)blockIdx.x >> 3) : (int)blockIdx.x, J_ = x8 ? ((int)gridDim.x >> 3) : (int)gridDim.x;
;     for (int n_ = j_; n_ < (x8 ? IPS + MS / TPI / NB : MR / TPI); n_ += J_) {
;     ...
;             const float cur = ldbf(U + (size_t)row * NU + URW + 768 + col);
;             const float prev = (t > 0) ? ldbf(U + (size_t)(row - 1) * NU + URW + 768 + col) : (shift ? shift[768 + col] : 0.f);
;             const float xs = cur + (prev - cur) * mu[768 + col];
	v_cvt_pk_bf16_f32 v63, v204, v205
	v_cvt_pk_bf16_f32 v64, v206, v207
	v_cvt_pk_bf16_f32 v65, v208, v209
	v_cvt_pk_bf16_f32 v66, v210, v211
	v_cvt_pk_bf16_f32 v67, v212, v213
	v_cvt_pk_bf16_f32 v68, v214, v215
	v_cvt_pk_bf16_f32 v69, v216, v217
	v_cvt_pk_bf16_f32 v70, v218, v219
	v_cvt_pk_bf16_f32 v71, v220, v221
	v_cvt_pk_bf16_f32 v72, v222, v223
	v_cvt_pk_bf16_f32 v73, v224, v225
	v_cvt_pk_bf16_f32 v74, v226, v227
	v_cvt_pk_bf16_f32 v75, v228, v229
	v_cvt_pk_bf16_f32 v76, v230, v231
	v_cvt_pk_bf16_f32 v77, v232, v233
	v_cvt_pk_bf16_f32 v78, v234, v235
	global_load_dword v204, v[6:7], off
	global_load_dword v205, v[6:7], off offset:1024
	global_load_dword v206, v[6:7], off offset:2048
	global_load_dword v207, v[6:7], off offset:3072
	v_add_co_u32_e32 v4, vcc, s0, v2
	s_mov_b32 s0, 0xa000
	s_nop 0
	v_addc_co_u32_e32 v5, vcc, 0, v3, vcc
	v_add_co_u32_e32 v6, vcc, s0, v2
	s_mov_b32 s0, 0xb000
	s_nop 0
	v_addc_co_u32_e32 v7, vcc, 0, v3, vcc
	global_load_dword v208, v[6:7], off offset:-4096
	global_load_dword v209, v[4:5], off offset:1024
	global_load_dword v210, v[4:5], off offset:2048
	s_nop 0
	global_load_dword v211, v[4:5], off offset:3072
	global_load_dword v212, v[6:7], off
	global_load_dword v213, v[6:7], off offset:1024
	global_load_dword v214, v[6:7], off offset:2048
	global_load_dword v215, v[6:7], off offset:3072
	v_add_co_u32_e32 v4, vcc, s0, v2
	s_mov_b32 s0, 0xc000
	s_nop 0
	v_addc_co_u32_e32 v5, vcc, 0, v3, vcc
	v_add_co_u32_e32 v6, vcc, s0, v2
	s_mov_b32 s0, 0xd000
	s_nop 0
	v_addc_co_u32_e32 v7, vcc, 0, v3, vcc
	global_load_dword v216, v[6:7], off offset:-4096
	global_load_dword v217, v[4:5], off offset:1024
	global_load_dword v218, v[4:5], off offset:2048
	s_nop 0
	global_load_dword v219, v[4:5], off offset:3072
	global_load_dword v220, v[6:7], off
	global_load_dword v221, v[6:7], off offset:1024
	global_load_dword v222, v[6:7], off offset:2048
	global_load_dword v223, v[6:7], off offset:3072
	v_add_co_u32_e32 v4, vcc, s0, v2
	s_mov_b32 s0, 0xe000
	s_nop 0
	v_addc_co_u32_e32 v5, vcc, 0, v3, vcc
	v_add_co_u32_e32 v6, vcc, s0, v2
	s_mov_b32 s0, 0xf000
	s_nop 0
	v_addc_co_u32_e32 v7, vcc, 0, v3, vcc
	global_load_dword v224, v[6:7], off offset:-4096
	global_load_dword v225, v[4:5], off offset:1024
	global_load_dword v226, v[4:5], off offset:2048
	s_nop 0
	global_load_dword v227, v[4:5], off offset:3072
	global_load_dword v228, v[6:7], off
	global_load_dword v229, v[6:7], off offset:1024
	global_load_dword v230, v[6:7], off offset:2048
	global_load_dword v231, v[6:7], off offset:3072
	v_add_co_u32_e32 v4, vcc, s0, v2
	s_nop 1
	v_addc_co_u32_e32 v5, vcc, 0, v3, vcc
	global_load_dword v232, v[4:5], off
	global_load_dword v233, v[4:5], off offset:1024
	global_load_dword v234, v[4:5], off offset:2048
	s_nop 0
	global_load_dword v235, v[4:5], off offset:3072
	s_waitcnt vmcnt(0)
	v_cvt_pk_bf16_f32 v79, v204, v205
	v_cvt_pk_bf16_f32 v80, v206, v207
	v_cvt_pk_bf16_f32 v81, v208, v209
	v_cvt_pk_bf16_f32 v82, v210, v211
	v_cvt_pk_bf16_f32 v83, v212, v213
	v_cvt_pk_bf16_f32 v84, v214, v215
	v_cvt_pk_bf16_f32 v85, v216, v217
	v_cvt_pk_bf16_f32 v86, v218, v219
	v_cvt_pk_bf16_f32 v87, v220, v221
	v_cvt_pk_bf16_f32 v88, v222, v223
	v_cvt_pk_bf16_f32 v89, v224, v225
	v_cvt_pk_bf16_f32 v90, v226, v227
	v_cvt_pk_bf16_f32 v91, v228, v229
	v_cvt_pk_bf16_f32 v92, v230, v231
	v_cvt_pk_bf16_f32 v3, v232, v233
	v_cvt_pk_bf16_f32 v93, v234, v235
	v_and_b32_e32 v2, 0x7f, v10
	v_lshlrev_b32_e32 v140, 2, v2
	v_lshl_add_u64 v[4:5], s[6:7], 0, v[140:141]
	v_lshlrev_b32_e32 v140, 1, v0
	v_lshl_add_u64 v[6:7], s[30:31], 0, v[140:141]
	s_mov_b64 s[6:7], 0x1b350000
	v_lshlrev_b32_e32 v140, 2, v94
	v_add_u32_e32 v10, 0x600, v10
	v_lshl_add_u64 v[6:7], v[6:7], 0, s[6:7]
	v_lshl_add_u64 v[8:9], s[30:31], 0, v[140:141]
	s_mov_b64 s[6:7], 0x1c360000
	v_ashrrev_i32_e32 v104, 7, v10
	v_lshlrev_b32_e32 v10, 1, v11
	v_mov_b32_e32 v11, v141
	v_lshl_add_u64 v[8:9], v[8:9], 0, s[6:7]
	v_lshl_add_u64 v[12:13], s[30:31], 0, v[10:11]
	s_mov_b64 s[6:7], 0x142e0000
	v_cmp_lt_u32_e64 s[10:11], 31, v2
	v_cmp_gt_u32_e64 s[12:13], 64, v2
	v_and_b32_e32 v105, 15, v104
	v_lshl_add_u64 v[12:13], v[12:13], 0, s[6:7]
	global_load_dword v203, v[4:5], off offset:3072
	s_waitcnt vmcnt(0)
	s_branch .LBB0_490

; __device__ __forceinline__ float ldbf(const bf16* p) { return bf2f((unsigned)*p); }
; __device__ __forceinline__ void rwkv_prep_part(const Args& a, int l, unsigned char* lds) {
;     ...
;             const int idx = tid + NTHR * k, tok = idx >> 7, col = idx & 127, row = row0 + tok;
;             int t, Tn; const float* shift; float* sout;
;             if (row < MP) { t = row & 4095; Tn = T; shift = nullptr; sout = out_l + O_PSHIFT + (size_t)(l * NB + (row >> 12)) * RW; }
;             else { const int rr = row - MP; t = rr & 15; Tn = TS; shift = in_I_SSHIFT + (size_t)(l * NB + (rr >> 4)) * RW; sout = out_l + O_SSHIFT + (size_t)(l * NB + (rr >> 4)) * RW; }
;             const float cur = ldbf(U + (size_t)row * NU + URW + 768 + col);
;             const float prev = (t > 0) ? ldbf(U + (size_t)(row - 1) * NU + URW + 768 + col) : (shift ? shift[768 + col] : 0.f);
.LBB0_495:
	s_lshl_b32 s18, s16, 4
	v_add_u32_e32 v20, s18, v97
	v_cmp_lt_i32_e32 vcc, s66, v20
	s_and_saveexec_b64 s[6:7], vcc
	s_xor_b64 s[6:7], exec, s[6:7]
	v_add_u32_e32 v14, 0xffff8000, v20
	v_lshrrev_b32_e32 v14, 4, v14
	v_add_u32_e32 v18, s47, v14
	v_mov_b64_e32 v[14:15], s[8:9]
	s_movk_i32 s0, 0xe00
	v_mov_b64_e32 v[16:17], s[20:21]
	v_mad_u64_u32 v[14:15], s[16:17], v18, s0, v[14:15]
	v_mad_u64_u32 v[16:17], s[16:17], v18, s0, v[16:17]
	s_or_saveexec_b64 s[6:7], s[6:7]
	v_mov_b32_e32 v18, 15
	v_mov_b32_e32 v19, v98
	s_xor_b64 exec, exec, s[6:7]
	v_ashrrev_i32_e32 v14, 12, v20
	v_add_u32_e32 v14, s47, v14
	v_mul_i32_i24_e32 v14, 0x380, v14
	v_ashrrev_i32_e32 v15, 31, v14
	v_mov_b32_e32 v18, 0xfff
	v_and_b32_e32 v19, 0xfff, v20
	v_lshl_add_u64 v[16:17], v[14:15], 2, s[22:23]
	v_mov_b64_e32 v[14:15], 0
	s_or_b64 exec, exec, s[6:7]
	v_mov_b64_e32 v[22:23], s[4:5]
	v_mad_i64_i32 v[22:23], s[6:7], v20, s91, v[22:23]
	v_lshlrev_b32_e32 v140, 1, v2
	v_lshl_add_u64 v[22:23], v[22:23], 0, v[140:141]
	v_add_co_u32_e32 v22, vcc, 0x1000, v22
	s_nop 1
	v_addc_co_u32_e32 v23, vcc, 0, v23, vcc
	global_load_ushort v21, v[22:23], off offset:1024
	v_cmp_ne_u32_e32 vcc, 0, v19
	s_and_saveexec_b64 s[6:7], vcc
	s_xor_b64 s[6:7], exec, s[6:7]
	s_cbranch_execz .LBB0_501
	v_add_u32_e32 v20, -1, v20
	v_mov_b64_e32 v[14:15], s[4:5]
	v_mad_i64_i32 v[14:15], s[16:17], v20, s91, v[14:15]
	v_lshl_add_u64 v[14:15], v[14:15], 0, v[140:141]
	v_add_co_u32_e32 v14, vcc, 0x1000, v14
	s_nop 1
	v_addc_co_u32_e32 v15, vcc, 0, v15, vcc
	global_load_ushort v22, v[14:15], off offset:1024

; __device__ __forceinline__ unsigned f2bf(float f) { return (unsigned)__builtin_bit_cast(unsigned short, (__bf16)f); }
; __device__ __forceinline__ float ldbf(const bf16* p) { return bf2f((unsigned)*p); }
; __device__ __forceinline__ float sigmoid_f(float x) { return __builtin_amdgcn_rcpf(1.0f + __expf(-x)); }
; __device__ __forceinline__ float tanh_f(float x) { return 2.0f * sigmoid_f(2.0f * x) - 1.0f; }
; __device__ __forceinline__ void rwkv_prep_part(const Args& a, int l, unsigned char* lds) {
;     ...
;             const float cur = ldbf(U + (size_t)row * NU + URW + 768 + col);
;             const float prev = (t > 0) ? ldbf(U + (size_t)(row - 1) * NU + URW + 768 + col) : (shift ? shift[768 + col] : 0.f);
;             const float xs = cur + (prev - cur) * mu[768 + col];
;             lrb[tok * 128 + col] = (bf16)f2bf(col < 32 ? tanh_f(xs) : (col < 64 ? xs : sigmoid_f(xs)));
.LBB0_505:
	s_or_b64 exec, exec, s[6:7]
	s_waitcnt vmcnt(0)
	v_cmp_ne_u32_e32 vcc, 0, v19
	v_lshlrev_b32_e32 v14, 16, v22
	s_nop 0
	v_cndmask_b32_e32 v22, v22, v14, vcc
	v_mov_b32_e32 v14, v203
	v_lshlrev_b32_e32 v20, 16, v21
	v_sub_f32_e32 v15, v22, v20
	s_waitcnt vmcnt(0)
	v_fma_f32 v15, v15, v14, v20
	s_and_saveexec_b64 s[6:7], s[10:11]
	s_xor_b64 s[6:7], exec, s[6:7]
	s_cbranch_execz .LBB0_507
	v_mul_f32_e32 v14, 0xbfb8aa3b, v15
	v_exp_f32_e32 v14, v14
	s_nop 0
	v_add_f32_e32 v14, 1.0, v14
	v_rcp_f32_e32 v14, v14
	s_nop 0
	v_cndmask_b32_e64 v14, v14, v15, s[12:13]

; __device__ __forceinline__ float ldbf(const bf16* p) { return bf2f((unsigned)*p); }
; __device__ __forceinline__ void rwkv_prep_part(const Args& a, int l, unsigned char* lds) {
;     ...
;             const int idx = tid + NTHR * k, tok = idx >> 7, col = idx & 127, row = row0 + tok;
;             int t, Tn; const float* shift; float* sout;
;             if (row < MP) { t = row & 4095; Tn = T; shift = nullptr; sout = out_l + O_PSHIFT + (size_t)(l * NB + (row >> 12)) * RW; }
;             else { const int rr = row - MP; t = rr & 15; Tn = TS; shift = in_I_SSHIFT + (size_t)(l * NB + (rr >> 4)) * RW; sout = out_l + O_SSHIFT + (size_t)(l * NB + (rr >> 4)) * RW; }
;             const float cur = ldbf(U + (size_t)row * NU + URW + 768 + col);
;             const float prev = (t > 0) ? ldbf(U + (size_t)(row - 1) * NU + URW + 768 + col) : (shift ? shift[768 + col] : 0.f);
.LBB0_511:
	s_or_b64 exec, exec, s[6:7]
	v_add_u32_e32 v15, s18, v100
	v_cmp_lt_i32_e32 vcc, s66, v15
	s_and_saveexec_b64 s[6:7], vcc
	s_xor_b64 s[6:7], exec, s[6:7]
	v_add_u32_e32 v16, 0xffff8000, v15
	v_lshrrev_b32_e32 v16, 4, v16
	v_add_u32_e32 v20, s47, v16
	v_mov_b64_e32 v[16:17], s[8:9]
	s_movk_i32 s0, 0xe00
	v_mad_u64_u32 v[18:19], s[16:17], v20, s0, v[16:17]
	v_mov_b64_e32 v[16:17], s[20:21]
	v_mad_u64_u32 v[16:17], s[16:17], v20, s0, v[16:17]
	s_or_saveexec_b64 s[6:7], s[6:7]
	v_mov_b32_e32 v20, 15
	v_mov_b32_e32 v21, v101
	s_xor_b64 exec, exec, s[6:7]
	v_ashrrev_i32_e32 v16, 12, v15
	v_add_u32_e32 v16, s47, v16
	v_mul_i32_i24_e32 v16, 0x380, v16
	v_ashrrev_i32_e32 v17, 31, v16
	v_mov_b32_e32 v20, 0xfff
	v_and_b32_e32 v21, 0xfff, v15
	v_lshl_add_u64 v[16:17], v[16:17], 2, s[22:23]
	v_mov_b64_e32 v[18:19], 0
	s_or_b64 exec, exec, s[6:7]
	v_mov_b64_e32 v[22:23], s[4:5]
	v_mad_i64_i32 v[22:23], s[6:7], v15, s91, v[22:23]
	v_lshl_add_u64 v[22:23], v[22:23], 0, v[140:141]
	v_add_co_u32_e32 v22, vcc, 0x1000, v22
	s_nop 1
	v_addc_co_u32_e32 v23, vcc, 0, v23, vcc
	global_load_ushort v22, v[22:23], off offset:1024
	v_cmp_ne_u32_e32 vcc, 0, v21
	s_and_saveexec_b64 s[6:7], vcc
	s_xor_b64 s[6:7], exec, s[6:7]
	s_cbranch_execz .LBB0_517
	v_add_u32_e32 v15, -1, v15
	v_mov_b64_e32 v[18:19], s[4:5]
	v_mad_i64_i32 v[18:19], s[16:17], v15, s91, v[18:19]
	v_lshl_add_u64 v[18:19], v[18:19], 0, v[140:141]
	v_add_co_u32_e32 v18, vcc, 0x1000, v18
	s_nop 1
	v_addc_co_u32_e32 v19, vcc, 0, v19, vcc
	global_load_ushort v23, v[18:19], off offset:1024

; __device__ __forceinline__ unsigned f2bf(float f) { return (unsigned)__builtin_bit_cast(unsigned short, (__bf16)f); }
; __device__ __forceinline__ float ldbf(const bf16* p) { return bf2f((unsigned)*p); }
; __device__ __forceinline__ float sigmoid_f(float x) { return __builtin_amdgcn_rcpf(1.0f + __expf(-x)); }
; __device__ __forceinline__ float tanh_f(float x) { return 2.0f * sigmoid_f(2.0f * x) - 1.0f; }
; __device__ __forceinline__ void rwkv_prep_part(const Args& a, int l, unsigned char* lds) {
;     ...
;             const float cur = ldbf(U + (size_t)row * NU + URW + 768 + col);
;             const float prev = (t > 0) ? ldbf(U + (size_t)(row - 1) * NU + URW + 768 + col) : (shift ? shift[768 + col] : 0.f);
;             const float xs = cur + (prev - cur) * mu[768 + col];
;             lrb[tok * 128 + col] = (bf16)f2bf(col < 32 ? tanh_f(xs) : (col < 64 ? xs : sigmoid_f(xs)));
.LBB0_521:
	s_or_b64 exec, exec, s[6:7]
	s_waitcnt vmcnt(0)
	v_cmp_ne_u32_e32 vcc, 0, v21
	v_lshlrev_b32_e32 v15, 16, v23
	s_nop 0
	v_cndmask_b32_e32 v23, v23, v15, vcc
	v_mov_b32_e32 v15, v203
	v_lshlrev_b32_e32 v18, 16, v22
	v_sub_f32_e32 v19, v23, v18
	s_waitcnt vmcnt(0)
	v_fma_f32 v15, v19, v15, v18
	s_and_saveexec_b64 s[6:7], s[10:11]
	s_xor_b64 s[6:7], exec, s[6:7]
	s_cbranch_execz .LBB0_523
	v_mul_f32_e32 v19, 0xbfb8aa3b, v15
	v_exp_f32_e32 v19, v19
	s_nop 0
	v_add_f32_e32 v19, 1.0, v19
	v_rcp_f32_e32 v19, v19
	s_nop 0
	v_cndmask_b32_e64 v19, v19, v15, s[12:13]

; __device__ __forceinline__ float ldbf(const bf16* p) { return bf2f((unsigned)*p); }
; __device__ __forceinline__ void rwkv_prep_part(const Args& a, int l, unsigned char* lds) {
;     ...
;             const int idx = tid + NTHR * k, tok = idx >> 7, col = idx & 127, row = row0 + tok;
;             int t, Tn; const float* shift; float* sout;
;             if (row < MP) { t = row & 4095; Tn = T; shift = nullptr; sout = out_l + O_PSHIFT + (size_t)(l * NB + (row >> 12)) * RW; }
;             else { const int rr = row - MP; t = rr & 15; Tn = TS; shift = in_I_SSHIFT + (size_t)(l * NB + (rr >> 4)) * RW; sout = out_l + O_SSHIFT + (size_t)(l * NB + (rr >> 4)) * RW; }
;             const float cur = ldbf(U + (size_t)row * NU + URW + 768 + col);
;             const float prev = (t > 0) ? ldbf(U + (size_t)(row - 1) * NU + URW + 768 + col) : (shift ? shift[768 + col] : 0.f);
.LBB0_527:
	s_or_b64 exec, exec, s[6:7]
	v_add_u32_e32 v15, s18, v102
	v_cmp_lt_i32_e32 vcc, s66, v15
	s_and_saveexec_b64 s[6:7], vcc
	s_xor_b64 s[6:7], exec, s[6:7]
	v_add_u32_e32 v16, 0xffff8000, v15
	v_lshrrev_b32_e32 v16, 4, v16
	v_add_u32_e32 v20, s47, v16
	v_mov_b64_e32 v[16:17], s[8:9]
	s_movk_i32 s0, 0xe00
	v_mad_u64_u32 v[18:19], s[16:17], v20, s0, v[16:17]
	v_mov_b64_e32 v[16:17], s[20:21]
	v_mad_u64_u32 v[16:17], s[16:17], v20, s0, v[16:17]
	s_or_saveexec_b64 s[6:7], s[6:7]
	v_mov_b32_e32 v20, 15
	v_mov_b32_e32 v21, v103
	s_xor_b64 exec, exec, s[6:7]
	v_ashrrev_i32_e32 v16, 12, v15
	v_add_u32_e32 v16, s47, v16
	v_mul_i32_i24_e32 v16, 0x380, v16
	v_ashrrev_i32_e32 v17, 31, v16
	v_mov_b32_e32 v20, 0xfff
	v_and_b32_e32 v21, 0xfff, v15
	v_lshl_add_u64 v[16:17], v[16:17], 2, s[22:23]
	v_mov_b64_e32 v[18:19], 0
	s_or_b64 exec, exec, s[6:7]
	v_mov_b64_e32 v[22:23], s[4:5]
	v_mad_i64_i32 v[22:23], s[6:7], v15, s91, v[22:23]
	v_lshl_add_u64 v[22:23], v[22:23], 0, v[140:141]
	v_add_co_u32_e32 v22, vcc, 0x1000, v22
	s_nop 1
	v_addc_co_u32_e32 v23, vcc, 0, v23, vcc
	global_load_ushort v22, v[22:23], off offset:1024
	v_cmp_ne_u32_e32 vcc, 0, v21
	s_and_saveexec_b64 s[6:7], vcc
	s_xor_b64 s[6:7], exec, s[6:7]
	s_cbranch_execz .LBB0_533
	v_add_u32_e32 v15, -1, v15
	v_mov_b64_e32 v[18:19], s[4:5]
	v_mad_i64_i32 v[18:19], s[16:17], v15, s91, v[18:19]
	v_lshl_add_u64 v[18:19], v[18:19], 0, v[140:141]
	v_add_co_u32_e32 v18, vcc, 0x1000, v18
	s_nop 1
	v_addc_co_u32_e32 v19, vcc, 0, v19, vcc
	global_load_ushort v23, v[18:19], off offset:1024

; __device__ __forceinline__ float ldbf(const bf16* p) { return bf2f((unsigned)*p); }
; __device__ __forceinline__ void rwkv_prep_part(const Args& a, int l, unsigned char* lds) {
;     ...
;             const int idx = tid + NTHR * k, tok = idx >> 7, col = idx & 127, row = row0 + tok;
;             int t, Tn; const float* shift; float* sout;
;             if (row < MP) { t = row & 4095; Tn = T; shift = nullptr; sout = out_l + O_PSHIFT + (size_t)(l * NB + (row >> 12)) * RW; }
;             else { const int rr = row - MP; t = rr & 15; Tn = TS; shift = in_I_SSHIFT + (size_t)(l * NB + (rr >> 4)) * RW; sout = out_l + O_SSHIFT + (size_t)(l * NB + (rr >> 4)) * RW; }
;             const float cur = ldbf(U + (size_t)row * NU + URW + 768 + col);
;             const float prev = (t > 0) ? ldbf(U + (size_t)(row - 1) * NU + URW + 768 + col) : (shift ? shift[768 + col] : 0.f);
.LBB0_543:
	s_or_b64 exec, exec, s[6:7]
	v_add_u32_e32 v15, s18, v104
	v_cmp_lt_i32_e32 vcc, s66, v15
	s_and_saveexec_b64 s[6:7], vcc
	s_xor_b64 s[6:7], exec, s[6:7]
	v_add_u32_e32 v16, 0xffff8000, v15
	v_lshrrev_b32_e32 v16, 4, v16
	v_add_u32_e32 v20, s47, v16
	v_mov_b64_e32 v[16:17], s[8:9]
	s_movk_i32 s0, 0xe00
	v_mad_u64_u32 v[18:19], s[16:17], v20, s0, v[16:17]
	v_mov_b64_e32 v[16:17], s[20:21]
	v_mad_u64_u32 v[16:17], s[16:17], v20, s0, v[16:17]
	s_or_saveexec_b64 s[6:7], s[6:7]
	v_mov_b32_e32 v20, 15
	v_mov_b32_e32 v21, v105
	s_xor_b64 exec, exec, s[6:7]
	v_ashrrev_i32_e32 v16, 12, v15
	v_add_u32_e32 v16, s47, v16
	v_mul_i32_i24_e32 v16, 0x380, v16
	v_ashrrev_i32_e32 v17, 31, v16
	v_mov_b32_e32 v20, 0xfff
	v_and_b32_e32 v21, 0xfff, v15
	v_lshl_add_u64 v[16:17], v[16:17], 2, s[22:23]
	v_mov_b64_e32 v[18:19], 0
	s_or_b64 exec, exec, s[6:7]
	v_mov_b64_e32 v[22:23], s[4:5]
	v_mad_i64_i32 v[22:23], s[6:7], v15, s91, v[22:23]
	v_lshl_add_u64 v[22:23], v[22:23], 0, v[140:141]
	v_add_co_u32_e32 v22, vcc, 0x1000, v22
	s_nop 1
	v_addc_co_u32_e32 v23, vcc, 0, v23, vcc
	global_load_ushort v22, v[22:23], off offset:1024
	v_cmp_ne_u32_e32 vcc, 0, v21
	s_and_saveexec_b64 s[6:7], vcc
	s_xor_b64 s[6:7], exec, s[6:7]
	s_cbranch_execz .LBB0_549
	v_add_u32_e32 v15, -1, v15
	v_mov_b64_e32 v[18:19], s[4:5]
	v_mad_i64_i32 v[18:19], s[16:17], v15, s91, v[18:19]
	v_lshl_add_u64 v[18:19], v[18:19], 0, v[140:141]
	v_add_co_u32_e32 v18, vcc, 0x1000, v18
	s_nop 1
	v_addc_co_u32_e32 v19, vcc, 0, v19, vcc
	global_load_ushort v23, v[18:19], off offset:1024

; template <int CH>
; __device__ __forceinline__ void scan_unit(const Args& a, int l, int unit, unsigned char* lds) {
;     ...
;     const int rowl = lane >> 4, jq = lane & 15, vrow = rg * 16 + wave * 4 + rowl;
;     f32x2v S01 = {0.f, 0.f}, S23 = {0.f, 0.f};
;     if (!loader && sample) { const f32x4 s = *(const f32x4*)(in_I_SWKV + ((size_t)((l * NB + b) * 4 + h) * 64 + vrow) * 64 + 4 * jq); S01 = s.lo; S23 = s.hi; }
.LBB0_673:
	s_and_b64 vcc, exec, s[4:5]
	s_cbranch_vccz .LBB0_662
	v_readlane_b32 s4, v253, 2
	v_mov_b32_e32 v4, v172
	v_readlane_b32 s5, v253, 3
	s_waitcnt lgkmcnt(0)
	s_load_dwordx4 s[56:59], s[4:5], 0xe0
	s_waitcnt vmcnt(0)
	v_ashrrev_i32_e32 v0, 6, v4
	v_and_b32_e32 v16, 15, v4
	s_lshr_b32 s61, s84, 3
	s_bfe_u32 s46, s49, 0x30004
	s_lshr_b32 s48, s84, 5
	v_cmp_gt_i32_e64 s[10:11], 4, v0
	v_bfe_u32 v97, v4, 4, 2
	v_lshlrev_b32_e32 v99, 2, v0
	v_lshlrev_b32_e32 v88, 4, v16
	s_and_saveexec_b64 s[4:5], s[10:11]
	s_xor_b64 s[8:9], exec, s[4:5]
	s_cbranch_execz .LBB0_678
	s_and_b32 s0, s48, 3
	s_and_b32 s4, s61, 3
	v_or_b32_e32 v0, v99, v97
	s_lshl_b32 s0, s0, 8
	s_lshl_b32 s4, s4, 4
	v_lshlrev_b32_e32 v2, 2, v0
	v_lshlrev_b32_e32 v0, 10, v16
	v_lshl_or_b32 v140, s46, 22, v0
	v_add3_u32 v0, s4, v99, v97
	s_waitcnt lgkmcnt(0)
	s_add_u32 s4, s58, s0
	v_ashrrev_i32_e32 v1, 31, v0
	s_addc_u32 s5, s59, 0
	v_lshl_add_u64 v[90:91], v[0:1], 2, s[4:5]
	v_mov_b32_e32 v0, 0
	s_mov_b32 s78, s22
	v_cmp_eq_u32_e64 s[12:13], 15, v16
	v_cmp_eq_u32_e64 s[14:15], 14, v16
	v_cmp_eq_u32_e64 s[16:17], 0, v16
	v_cmp_eq_u32_e64 s[18:19], 1, v16
	v_cmp_eq_u32_e64 s[20:21], 2, v16
	v_cmp_eq_u32_e64 s[22:23], 3, v16
	v_cmp_eq_u32_e64 s[24:25], 4, v16
	v_cmp_eq_u32_e64 s[26:27], 5, v16
	v_cmp_eq_u32_e64 s[28:29], 6, v16
	v_cmp_eq_u32_e64 s[30:31], 7, v16
	v_cmp_eq_u32_e64 s[34:35], 8, v16
	v_cmp_eq_u32_e64 s[36:37], 9, v16
	v_cmp_eq_u32_e64 s[38:39], 10, v16
	v_cmp_eq_u32_e64 s[40:41], 11, v16
	v_cmp_eq_u32_e64 s[42:43], 12, v16
	v_cmp_eq_u32_e64 s[44:45], 13, v16
	v_or_b32_e32 v92, 0x8000, v140
	v_mov_b32_e32 v93, v141
	s_mov_b32 s4, -2
	v_add_u32_e32 v89, 0, v88
	v_add_u32_e32 v101, 0, v2
	v_mov_b32_e32 v1, v0
	v_mov_b32_e32 v2, v0
	v_mov_b32_e32 v3, v0
	s_barrier
	v_lshl_add_u64 v[90:91], v[90:91], 0, v[140:141]
	v_add_u32_e32 v98, 0xa800, v89
	v_add_co_u32_e32 v90, vcc, 0x1c3e0800, v90
	v_add_u32_e32 v100, 0xa800, v101
	s_mov_b32 s4, 0
	v_addc_co_u32_e32 v91, vcc, 0, v91, vcc
	s_mov_b64 s[6:7], 0x4000
	ds_read_b128 v[54:57], v89
	ds_read_b128 v[6:9], v89 offset:768
	ds_read_b128 v[22:25], v89 offset:1024
	ds_read_b128 v[38:41], v89 offset:256
	ds_read_b128 v[70:73], v89 offset:512
	ds_read_b32 v78, v101 offset:1280
	ds_read_b128 v[58:61], v89 offset:1344
	ds_read_b128 v[10:13], v89 offset:2112
	ds_read_b128 v[26:29], v89 offset:2368
	ds_read_b128 v[42:45], v89 offset:1600
	ds_read_b128 v[74:77], v89 offset:1856
	ds_read_b32 v80, v101 offset:2624
	v_mov_b32_e32 v66, 0
	v_mov_b32_e32 v67, 0
	v_mov_b32_e32 v68, 0
	v_mov_b32_e32 v69, 0
	v_mov_b32_e32 v96, 0
	v_mov_b32_e32 v102, 0
	v_mov_b32_e32 v103, 0
	v_mov_b32_e32 v104, 0
	v_mov_b32_e32 v105, 0
	s_setprio 3
.Lscan_top:
	s_waitcnt lgkmcnt(6)
	v_pk_mul_f32 v[86:87], v[2:3], v[8:9]
	v_pk_mul_f32 v[4:5], v[2:3], v[68:69]
	v_pk_fma_f32 v[86:87], v[0:1], v[6:7], v[86:87]
	v_pk_fma_f32 v[4:5], v[0:1], v[66:67], v[4:5]
	v_pk_mul_f32 v[84:85], v[72:73], v[78:79] op_sel_hi:[1,0]
	v_add_f32_e32 v94, v86, v87
	v_add_f32_e32 v95, v4, v5
	v_pk_mul_f32 v[82:83], v[70:71], v[78:79] op_sel_hi:[1,0]
	ds_read_b128 v[62:65], v89 offset:2688
	v_add_f32_dpp v94, v94, v94 quad_perm:[1,0,3,2] row_mask:0xf bank_mask:0xf bound_ctrl:1
	v_add_f32_dpp v95, v95, v95 quad_perm:[1,0,3,2] row_mask:0xf bank_mask:0xf bound_ctrl:1
	ds_read_b128 v[14:17], v89 offset:3456
	v_add_f32_dpp v94, v94, v94 quad_perm:[2,3,0,1] row_mask:0xf bank_mask:0xf bound_ctrl:1
	v_add_f32_dpp v95, v95, v95 quad_perm:[2,3,0,1] row_mask:0xf bank_mask:0xf bound_ctrl:1
	ds_read_b128 v[30:33], v89 offset:3712
	v_add_f32_dpp v94, v94, v94 row_half_mirror row_mask:0xf bank_mask:0xf bound_ctrl:1
	v_add_f32_dpp v95, v95, v95 row_half_mirror row_mask:0xf bank_mask:0xf bound_ctrl:1
	ds_read_b128 v[46:49], v89 offset:2944
	v_add_f32_dpp v94, v94, v94 row_mirror row_mask:0xf bank_mask:0xf bound_ctrl:1
	v_add_f32_dpp v95, v95, v95 row_mirror row_mask:0xf bank_mask:0xf bound_ctrl:1
	v_pk_fma_f32 v[84:85], v[24:25], v[94:95], v[84:85] op_sel_hi:[1,0,1] neg_lo:[0,1,0] neg_hi:[0,1,0]
	v_pk_fma_f32 v[82:83], v[22:23], v[94:95], v[82:83] op_sel_hi:[1,0,1] neg_lo:[0,1,0] neg_hi:[0,1,0]
	v_cndmask_b32_e64 v96, v96, v95, s[12:13]
	v_pk_fma_f32 v[2:3], v[2:3], v[40:41], v[84:85]
	v_pk_fma_f32 v[0:1], v[0:1], v[38:39], v[82:83]
	ds_read_b128 v[70:73], v89 offset:3200
	ds_read_b32 v78, v101 offset:3968
	s_cmp_eq_u32 s4, 0
	s_cbranch_scc1 .Lscan_skip_st0
	global_store_dword v[90:91], v96, off
	v_lshl_add_u64 v[90:91], v[90:91], 0, s[6:7]
.Lscan_skip_st0:
	s_waitcnt lgkmcnt(6)
	v_pk_mul_f32 v[86:87], v[2:3], v[12:13]
	v_pk_mul_f32 v[4:5], v[2:3], v[56:57]
	v_pk_fma_f32 v[86:87], v[0:1], v[10:11], v[86:87]
	v_pk_fma_f32 v[4:5], v[0:1], v[54:55], v[4:5]
	v_pk_mul_f32 v[84:85], v[76:77], v[80:81] op_sel_hi:[1,0]
	v_add_f32_e32 v94, v86, v87
	v_add_f32_e32 v95, v4, v5
	v_pk_mul_f32 v[82:83], v[74:75], v[80:81] op_sel_hi:[1,0]
	ds_read_b128 v[66:69], v89 offset:4032
	v_add_f32_dpp v94, v94, v94 quad_perm:[1,0,3,2] row_mask:0xf bank_mask:0xf bound_ctrl:1
	v_add_f32_dpp v95, v95, v95 quad_perm:[1,0,3,2] row_mask:0xf bank_mask:0xf bound_ctrl:1
	ds_read_b128 v[18:21], v89 offset:4800
	v_add_f32_dpp v94, v94, v94 quad_perm:[2,3,0,1] row_mask:0xf bank_mask:0xf bound_ctrl:1
	v_add_f32_dpp v95, v95, v95 quad_perm:[2,3,0,1] row_mask:0xf bank_mask:0xf bound_ctrl:1
	ds_read_b128 v[34:37], v89 offset:5056
	v_add_f32_dpp v94, v94, v94 row_half_mirror row_mask:0xf bank_mask:0xf bound_ctrl:1
	v_add_f32_dpp v95, v95, v95 row_half_mirror row_mask:0xf bank_mask:0xf bound_ctrl:1
	ds_read_b128 v[50:53], v89 offset:4288
	v_add_f32_dpp v94, v94, v94 row_mirror row_mask:0xf bank_mask:0xf bound_ctrl:1
	v_add_f32_dpp v95, v95, v95 row_mirror row_mask:0xf bank_mask:0xf bound_ctrl:1
	v_pk_fma_f32 v[84:85], v[28:29], v[94:95], v[84:85] op_sel_hi:[1,0,1] neg_lo:[0,1,0] neg_hi:[0,1,0]
	v_pk_fma_f32 v[82:83], v[26:27], v[94:95], v[82:83] op_sel_hi:[1,0,1] neg_lo:[0,1,0] neg_hi:[0,1,0]
	v_cndmask_b32_e64 v96, 0, v95, s[16:17]
	v_pk_fma_f32 v[2:3], v[2:3], v[44:45], v[84:85]
	v_pk_fma_f32 v[0:1], v[0:1], v[42:43], v[82:83]
	ds_read_b128 v[74:77], v89 offset:4544
	ds_read_b32 v80, v101 offset:5312
	s_waitcnt lgkmcnt(6)
	v_pk_mul_f32 v[86:87], v[2:3], v[16:17]
	v_pk_mul_f32 v[4:5], v[2:3], v[60:61]
	v_pk_fma_f32 v[86:87], v[0:1], v[14:15], v[86:87]
	v_pk_fma_f32 v[4:5], v[0:1], v[58:59], v[4:5]
	v_pk_mul_f32 v[84:85], v[72:73], v[78:79] op_sel_hi:[1,0]
	v_add_f32_e32 v94, v86, v87
	v_add_f32_e32 v95, v4, v5
	v_pk_mul_f32 v[82:83], v[70:71], v[78:79] op_sel_hi:[1,0]
	ds_read_b128 v[54:57], v89 offset:5376
	v_add_f32_dpp v94, v94, v94 quad_perm:[1,0,3,2] row_mask:0xf bank_mask:0xf bound_ctrl:1
	v_add_f32_dpp v95, v95, v95 quad_perm:[1,0,3,2] row_mask:0xf bank_mask:0xf bound_ctrl:1
	ds_read_b128 v[6:9], v89 offset:6144
	v_add_f32_dpp v94, v94, v94 quad_perm:[2,3,0,1] row_mask:0xf bank_mask:0xf bound_ctrl:1
	v_add_f32_dpp v95, v95, v95 quad_perm:[2,3,0,1] row_mask:0xf bank_mask:0xf bound_ctrl:1
	ds_read_b128 v[22:25], v89 offset:6400
	v_add_f32_dpp v94, v94, v94 row_half_mirror row_mask:0xf bank_mask:0xf bound_ctrl:1
	v_add_f32_dpp v95, v95, v95 row_half_mirror row_mask:0xf bank_mask:0xf bound_ctrl:1
	ds_read_b128 v[38:41], v89 offset:5632
	v_add_f32_dpp v94, v94, v94 row_mirror row_mask:0xf bank_mask:0xf bound_ctrl:1
	v_add_f32_dpp v95, v95, v95 row_mirror row_mask:0xf bank_mask:0xf bound_ctrl:1
	v_pk_fma_f32 v[84:85], v[32:33], v[94:95], v[84:85] op_sel_hi:[1,0,1] neg_lo:[0,1,0] neg_hi:[0,1,0]
	v_pk_fma_f32 v[82:83], v[30:31], v[94:95], v[82:83] op_sel_hi:[1,0,1] neg_lo:[0,1,0] neg_hi:[0,1,0]
	v_cndmask_b32_e64 v96, v96, v95, s[18:19]
	v_pk_fma_f32 v[2:3], v[2:3], v[48:49], v[84:85]
	v_pk_fma_f32 v[0:1], v[0:1], v[46:47], v[82:83]
	ds_read_b128 v[70:73], v89 offset:5888
	ds_read_b32 v78, v101 offset:6656
	s_waitcnt lgkmcnt(6)
	v_pk_mul_f32 v[86:87], v[2:3], v[20:21]
	v_pk_mul_f32 v[4:5], v[2:3], v[64:65]
	v_pk_fma_f32 v[86:87], v[0:1], v[18:19], v[86:87]
	v_pk_fma_f32 v[4:5], v[0:1], v[62:63], v[4:5]
	v_pk_mul_f32 v[84:85], v[76:77], v[80:81] op_sel_hi:[1,0]
	v_add_f32_e32 v94, v86, v87
	v_add_f32_e32 v95, v4, v5
	v_pk_mul_f32 v[82:83], v[74:75], v[80:81] op_sel_hi:[1,0]
	ds_read_b128 v[58:61], v89 offset:6720
	v_add_f32_dpp v94, v94, v94 quad_perm:[1,0,3,2] row_mask:0xf bank_mask:0xf bound_ctrl:1
	v_add_f32_dpp v95, v95, v95 quad_perm:[1,0,3,2] row_mask:0xf bank_mask:0xf bound_ctrl:1
	ds_read_b128 v[10:13], v89 offset:7488
	v_add_f32_dpp v94, v94, v94 quad_perm:[2,3,0,1] row_mask:0xf bank_mask:0xf bound_ctrl:1
	v_add_f32_dpp v95, v95, v95 quad_perm:[2,3,0,1] row_mask:0xf bank_mask:0xf bound_ctrl:1
	ds_read_b128 v[26:29], v89 offset:7744
	v_add_f32_dpp v94, v94, v94 row_half_mirror row_mask:0xf bank_mask:0xf bound_ctrl:1
	v_add_f32_dpp v95, v95, v95 row_half_mirror row_mask:0xf bank_mask:0xf bound_ctrl:1
	ds_read_b128 v[42:45], v89 offset:6976
	v_add_f32_dpp v94, v94, v94 row_mirror row_mask:0xf bank_mask:0xf bound_ctrl:1
	v_add_f32_dpp v95, v95, v95 row_mirror row_mask:0xf bank_mask:0xf bound_ctrl:1
	v_pk_fma_f32 v[84:85], v[36:37], v[94:95], v[84:85] op_sel_hi:[1,0,1] neg_lo:[0,1,0] neg_hi:[0,1,0]
	v_pk_fma_f32 v[82:83], v[34:35], v[94:95], v[82:83] op_sel_hi:[1,0,1] neg_lo:[0,1,0] neg_hi:[0,1,0]
	v_cndmask_b32_e64 v96, v96, v95, s[20:21]
	v_pk_fma_f32 v[2:3], v[2:3], v[52:53], v[84:85]
	v_pk_fma_f32 v[0:1], v[0:1], v[50:51], v[82:83]
	ds_read_b128 v[74:77], v89 offset:7232
	ds_read_b32 v80, v101 offset:8000
	s_waitcnt lgkmcnt(6)
	v_pk_mul_f32 v[86:87], v[2:3], v[8:9]
	v_pk_mul_f32 v[4:5], v[2:3], v[68:69]
	v_pk_fma_f32 v[86:87], v[0:1], v[6:7], v[86:87]
	v_pk_fma_f32 v[4:5], v[0:1], v[66:67], v[4:5]
	v_pk_mul_f32 v[84:85], v[72:73], v[78:79] op_sel_hi:[1,0]
	v_add_f32_e32 v94, v86, v87
	v_add_f32_e32 v95, v4, v5
	v_pk_mul_f32 v[82:83], v[70:71], v[78:79] op_sel_hi:[1,0]
	ds_read_b128 v[62:65], v89 offset:8064
	v_add_f32_dpp v94, v94, v94 quad_perm:[1,0,3,2] row_mask:0xf bank_mask:0xf bound_ctrl:1
	v_add_f32_dpp v95, v95, v95 quad_perm:[1,0,3,2] row_mask:0xf bank_mask:0xf bound_ctrl:1
	ds_read_b128 v[14:17], v89 offset:8832
	v_add_f32_dpp v94, v94, v94 quad_perm:[2,3,0,1] row_mask:0xf bank_mask:0xf bound_ctrl:1
	v_add_f32_dpp v95, v95, v95 quad_perm:[2,3,0,1] row_mask:0xf bank_mask:0xf bound_ctrl:1
	ds_read_b128 v[30:33], v89 offset:9088
	v_add_f32_dpp v94, v94, v94 row_half_mirror row_mask:0xf bank_mask:0xf bound_ctrl:1
	v_add_f32_dpp v95, v95, v95 row_half_mirror row_mask:0xf bank_mask:0xf bound_ctrl:1
	ds_read_b128 v[46:49], v89 offset:8320
	v_add_f32_dpp v94, v94, v94 row_mirror row_mask:0xf bank_mask:0xf bound_ctrl:1
	v_add_f32_dpp v95, v95, v95 row_mirror row_mask:0xf bank_mask:0xf bound_ctrl:1
	v_pk_fma_f32 v[84:85], v[24:25], v[94:95], v[84:85] op_sel_hi:[1,0,1] neg_lo:[0,1,0] neg_hi:[0,1,0]
	v_pk_fma_f32 v[82:83], v[22:23], v[94:95], v[82:83] op_sel_hi:[1,0,1] neg_lo:[0,1,0] neg_hi:[0,1,0]
	v_cndmask_b32_e64 v96, v96, v95, s[22:23]
	v_pk_fma_f32 v[2:3], v[2:3], v[40:41], v[84:85]
	v_pk_fma_f32 v[0:1], v[0:1], v[38:39], v[82:83]
	ds_read_b128 v[70:73], v89 offset:8576
	ds_read_b32 v78, v101 offset:9344
	s_waitcnt lgkmcnt(6)
	v_pk_mul_f32 v[86:87], v[2:3], v[12:13]
	v_pk_mul_f32 v[4:5], v[2:3], v[56:57]
	v_pk_fma_f32 v[86:87], v[0:1], v[10:11], v[86:87]
	v_pk_fma_f32 v[4:5], v[0:1], v[54:55], v[4:5]
	v_pk_mul_f32 v[84:85], v[76:77], v[80:81] op_sel_hi:[1,0]
	v_add_f32_e32 v94, v86, v87
	v_add_f32_e32 v95, v4, v5
	v_pk_mul_f32 v[82:83], v[74:75], v[80:81] op_sel_hi:[1,0]
	ds_read_b128 v[66:69], v89 offset:9408
	v_add_f32_dpp v94, v94, v94 quad_perm:[1,0,3,2] row_mask:0xf bank_mask:0xf bound_ctrl:1
	v_add_f32_dpp v95, v95, v95 quad_perm:[1,0,3,2] row_mask:0xf bank_mask:0xf bound_ctrl:1
	ds_read_b128 v[18:21], v89 offset:10176
	v_add_f32_dpp v94, v94, v94 quad_perm:[2,3,0,1] row_mask:0xf bank_mask:0xf bound_ctrl:1
	v_add_f32_dpp v95, v95, v95 quad_perm:[2,3,0,1] row_mask:0xf bank_mask:0xf bound_ctrl:1
	ds_read_b128 v[34:37], v89 offset:10432
	v_add_f32_dpp v94, v94, v94 row_half_mirror row_mask:0xf bank_mask:0xf bound_ctrl:1
	v_add_f32_dpp v95, v95, v95 row_half_mirror row_mask:0xf bank_mask:0xf bound_ctrl:1
	ds_read_b128 v[50:53], v89 offset:9664
	v_add_f32_dpp v94, v94, v94 row_mirror row_mask:0xf bank_mask:0xf bound_ctrl:1
	v_add_f32_dpp v95, v95, v95 row_mirror row_mask:0xf bank_mask:0xf bound_ctrl:1
	v_pk_fma_f32 v[84:85], v[28:29], v[94:95], v[84:85] op_sel_hi:[1,0,1] neg_lo:[0,1,0] neg_hi:[0,1,0]
	v_pk_fma_f32 v[82:83], v[26:27], v[94:95], v[82:83] op_sel_hi:[1,0,1] neg_lo:[0,1,0] neg_hi:[0,1,0]
	v_cndmask_b32_e64 v96, v96, v95, s[24:25]
	v_pk_fma_f32 v[2:3], v[2:3], v[44:45], v[84:85]
	v_pk_fma_f32 v[0:1], v[0:1], v[42:43], v[82:83]
	ds_read_b128 v[74:77], v89 offset:9920
	ds_read_b32 v80, v101 offset:10688
	s_waitcnt lgkmcnt(6)
	v_pk_mul_f32 v[86:87], v[2:3], v[16:17]
	v_pk_mul_f32 v[4:5], v[2:3], v[60:61]
	v_pk_fma_f32 v[86:87], v[0:1], v[14:15], v[86:87]
	v_pk_fma_f32 v[4:5], v[0:1], v[58:59], v[4:5]
	v_pk_mul_f32 v[84:85], v[72:73], v[78:79] op_sel_hi:[1,0]
	v_add_f32_e32 v94, v86, v87
	v_add_f32_e32 v95, v4, v5
	v_pk_mul_f32 v[82:83], v[70:71], v[78:79] op_sel_hi:[1,0]
	ds_read_b128 v[54:57], v89 offset:10752
	v_add_f32_dpp v94, v94, v94 quad_perm:[1,0,3,2] row_mask:0xf bank_mask:0xf bound_ctrl:1
	v_add_f32_dpp v95, v95, v95 quad_perm:[1,0,3,2] row_mask:0xf bank_mask:0xf bound_ctrl:1
	ds_read_b128 v[6:9], v89 offset:11520
	v_add_f32_dpp v94, v94, v94 quad_perm:[2,3,0,1] row_mask:0xf bank_mask:0xf bound_ctrl:1
	v_add_f32_dpp v95, v95, v95 quad_perm:[2,3,0,1] row_mask:0xf bank_mask:0xf bound_ctrl:1
	ds_read_b128 v[22:25], v89 offset:11776
	v_add_f32_dpp v94, v94, v94 row_half_mirror row_mask:0xf bank_mask:0xf bound_ctrl:1
	v_add_f32_dpp v95, v95, v95 row_half_mirror row_mask:0xf bank_mask:0xf bound_ctrl:1
	ds_read_b128 v[38:41], v89 offset:11008
	v_add_f32_dpp v94, v94, v94 row_mirror row_mask:0xf bank_mask:0xf bound_ctrl:1
	v_add_f32_dpp v95, v95, v95 row_mirror row_mask:0xf bank_mask:0xf bound_ctrl:1
	v_pk_fma_f32 v[84:85], v[32:33], v[94:95], v[84:85] op_sel_hi:[1,0,1] neg_lo:[0,1,0] neg_hi:[0,1,0]
	v_pk_fma_f32 v[82:83], v[30:31], v[94:95], v[82:83] op_sel_hi:[1,0,1] neg_lo:[0,1,0] neg_hi:[0,1,0]
	v_cndmask_b32_e64 v96, v96, v95, s[26:27]
	v_pk_fma_f32 v[2:3], v[2:3], v[48:49], v[84:85]
	v_pk_fma_f32 v[0:1], v[0:1], v[46:47], v[82:83]
	ds_read_b128 v[70:73], v89 offset:11264
	ds_read_b32 v78, v101 offset:12032
	s_waitcnt lgkmcnt(6)
	v_pk_mul_f32 v[86:87], v[2:3], v[20:21]
	v_pk_mul_f32 v[4:5], v[2:3], v[64:65]
	v_pk_fma_f32 v[86:87], v[0:1], v[18:19], v[86:87]
	v_pk_fma_f32 v[4:5], v[0:1], v[62:63], v[4:5]
	v_pk_mul_f32 v[84:85], v[76:77], v[80:81] op_sel_hi:[1,0]
	v_add_f32_e32 v94, v86, v87
	v_add_f32_e32 v95, v4, v5
	v_pk_mul_f32 v[82:83], v[74:75], v[80:81] op_sel_hi:[1,0]
	ds_read_b128 v[58:61], v89 offset:12096
	v_add_f32_dpp v94, v94, v94 quad_perm:[1,0,3,2] row_mask:0xf bank_mask:0xf bound_ctrl:1
	v_add_f32_dpp v95, v95, v95 quad_perm:[1,0,3,2] row_mask:0xf bank_mask:0xf bound_ctrl:1
	ds_read_b128 v[10:13], v89 offset:12864
	v_add_f32_dpp v94, v94, v94 quad_perm:[2,3,0,1] row_mask:0xf bank_mask:0xf bound_ctrl:1
	v_add_f32_dpp v95, v95, v95 quad_perm:[2,3,0,1] row_mask:0xf bank_mask:0xf bound_ctrl:1
	ds_read_b128 v[26:29], v89 offset:13120
	v_add_f32_dpp v94, v94, v94 row_half_mirror row_mask:0xf bank_mask:0xf bound_ctrl:1
	v_add_f32_dpp v95, v95, v95 row_half_mirror row_mask:0xf bank_mask:0xf bound_ctrl:1
	ds_read_b128 v[42:45], v89 offset:12352
	v_add_f32_dpp v94, v94, v94 row_mirror row_mask:0xf bank_mask:0xf bound_ctrl:1
	v_add_f32_dpp v95, v95, v95 row_mirror row_mask:0xf bank_mask:0xf bound_ctrl:1
	v_pk_fma_f32 v[84:85], v[36:37], v[94:95], v[84:85] op_sel_hi:[1,0,1] neg_lo:[0,1,0] neg_hi:[0,1,0]
	v_pk_fma_f32 v[82:83], v[34:35], v[94:95], v[82:83] op_sel_hi:[1,0,1] neg_lo:[0,1,0] neg_hi:[0,1,0]
	v_cndmask_b32_e64 v96, v96, v95, s[28:29]
	v_pk_fma_f32 v[2:3], v[2:3], v[52:53], v[84:85]
	v_pk_fma_f32 v[0:1], v[0:1], v[50:51], v[82:83]
	ds_read_b128 v[74:77], v89 offset:12608
	ds_read_b32 v80, v101 offset:13376
	s_waitcnt lgkmcnt(6)
	v_pk_mul_f32 v[86:87], v[2:3], v[8:9]
	v_pk_mul_f32 v[4:5], v[2:3], v[68:69]
	v_pk_fma_f32 v[86:87], v[0:1], v[6:7], v[86:87]
	v_pk_fma_f32 v[4:5], v[0:1], v[66:67], v[4:5]
	v_pk_mul_f32 v[84:85], v[72:73], v[78:79] op_sel_hi:[1,0]
	v_add_f32_e32 v94, v86, v87
	v_add_f32_e32 v95, v4, v5
	v_pk_mul_f32 v[82:83], v[70:71], v[78:79] op_sel_hi:[1,0]
	ds_read_b128 v[62:65], v89 offset:13440
	v_add_f32_dpp v94, v94, v94 quad_perm:[1,0,3,2] row_mask:0xf bank_mask:0xf bound_ctrl:1
	v_add_f32_dpp v95, v95, v95 quad_perm:[1,0,3,2] row_mask:0xf bank_mask:0xf bound_ctrl:1
	ds_read_b128 v[14:17], v89 offset:14208
	v_add_f32_dpp v94, v94, v94 quad_perm:[2,3,0,1] row_mask:0xf bank_mask:0xf bound_ctrl:1
	v_add_f32_dpp v95, v95, v95 quad_perm:[2,3,0,1] row_mask:0xf bank_mask:0xf bound_ctrl:1
	ds_read_b128 v[30:33], v89 offset:14464
	v_add_f32_dpp v94, v94, v94 row_half_mirror row_mask:0xf bank_mask:0xf bound_ctrl:1
	v_add_f32_dpp v95, v95, v95 row_half_mirror row_mask:0xf bank_mask:0xf bound_ctrl:1
	ds_read_b128 v[46:49], v89 offset:13696
	v_add_f32_dpp v94, v94, v94 row_mirror row_mask:0xf bank_mask:0xf bound_ctrl:1
	v_add_f32_dpp v95, v95, v95 row_mirror row_mask:0xf bank_mask:0xf bound_ctrl:1
	v_pk_fma_f32 v[84:85], v[24:25], v[94:95], v[84:85] op_sel_hi:[1,0,1] neg_lo:[0,1,0] neg_hi:[0,1,0]
	v_pk_fma_f32 v[82:83], v[22:23], v[94:95], v[82:83] op_sel_hi:[1,0,1] neg_lo:[0,1,0] neg_hi:[0,1,0]
	v_cndmask_b32_e64 v96, v96, v95, s[30:31]
	v_pk_fma_f32 v[2:3], v[2:3], v[40:41], v[84:85]
	v_pk_fma_f32 v[0:1], v[0:1], v[38:39], v[82:83]
	ds_read_b128 v[70:73], v89 offset:13952
	ds_read_b32 v78, v101 offset:14720
	s_waitcnt lgkmcnt(6)
	v_pk_mul_f32 v[86:87], v[2:3], v[12:13]
	v_pk_mul_f32 v[4:5], v[2:3], v[56:57]
	v_pk_fma_f32 v[86:87], v[0:1], v[10:11], v[86:87]
	v_pk_fma_f32 v[4:5], v[0:1], v[54:55], v[4:5]
	v_pk_mul_f32 v[84:85], v[76:77], v[80:81] op_sel_hi:[1,0]
	v_add_f32_e32 v94, v86, v87
	v_add_f32_e32 v95, v4, v5
	v_pk_mul_f32 v[82:83], v[74:75], v[80:81] op_sel_hi:[1,0]
	ds_read_b128 v[66:69], v89 offset:14784
	v_add_f32_dpp v94, v94, v94 quad_perm:[1,0,3,2] row_mask:0xf bank_mask:0xf bound_ctrl:1
	v_add_f32_dpp v95, v95, v95 quad_perm:[1,0,3,2] row_mask:0xf bank_mask:0xf bound_ctrl:1
	ds_read_b128 v[18:21], v89 offset:15552
	v_add_f32_dpp v94, v94, v94 quad_perm:[2,3,0,1] row_mask:0xf bank_mask:0xf bound_ctrl:1
	v_add_f32_dpp v95, v95, v95 quad_perm:[2,3,0,1] row_mask:0xf bank_mask:0xf bound_ctrl:1
	ds_read_b128 v[34:37], v89 offset:15808
	v_add_f32_dpp v94, v94, v94 row_half_mirror row_mask:0xf bank_mask:0xf bound_ctrl:1
	v_add_f32_dpp v95, v95, v95 row_half_mirror row_mask:0xf bank_mask:0xf bound_ctrl:1
	ds_read_b128 v[50:53], v89 offset:15040
	v_add_f32_dpp v94, v94, v94 row_mirror row_mask:0xf bank_mask:0xf bound_ctrl:1
	v_add_f32_dpp v95, v95, v95 row_mirror row_mask:0xf bank_mask:0xf bound_ctrl:1
	v_pk_fma_f32 v[84:85], v[28:29], v[94:95], v[84:85] op_sel_hi:[1,0,1] neg_lo:[0,1,0] neg_hi:[0,1,0]
	v_pk_fma_f32 v[82:83], v[26:27], v[94:95], v[82:83] op_sel_hi:[1,0,1] neg_lo:[0,1,0] neg_hi:[0,1,0]
	v_cndmask_b32_e64 v96, v96, v95, s[34:35]
	v_pk_fma_f32 v[2:3], v[2:3], v[44:45], v[84:85]
	v_pk_fma_f32 v[0:1], v[0:1], v[42:43], v[82:83]
	ds_read_b128 v[74:77], v89 offset:15296
	ds_read_b32 v80, v101 offset:16064
	s_waitcnt lgkmcnt(6)
	v_pk_mul_f32 v[86:87], v[2:3], v[16:17]
	v_pk_mul_f32 v[4:5], v[2:3], v[60:61]
	v_pk_fma_f32 v[86:87], v[0:1], v[14:15], v[86:87]
	v_pk_fma_f32 v[4:5], v[0:1], v[58:59], v[4:5]
	v_pk_mul_f32 v[84:85], v[72:73], v[78:79] op_sel_hi:[1,0]
	v_add_f32_e32 v94, v86, v87
	v_add_f32_e32 v95, v4, v5
	v_pk_mul_f32 v[82:83], v[70:71], v[78:79] op_sel_hi:[1,0]
	ds_read_b128 v[54:57], v89 offset:16128
	v_add_f32_dpp v94, v94, v94 quad_perm:[1,0,3,2] row_mask:0xf bank_mask:0xf bound_ctrl:1
	v_add_f32_dpp v95, v95, v95 quad_perm:[1,0,3,2] row_mask:0xf bank_mask:0xf bound_ctrl:1
	ds_read_b128 v[6:9], v89 offset:16896
	v_add_f32_dpp v94, v94, v94 quad_perm:[2,3,0,1] row_mask:0xf bank_mask:0xf bound_ctrl:1
	v_add_f32_dpp v95, v95, v95 quad_perm:[2,3,0,1] row_mask:0xf bank_mask:0xf bound_ctrl:1
	ds_read_b128 v[22:25], v89 offset:17152
	v_add_f32_dpp v94, v94, v94 row_half_mirror row_mask:0xf bank_mask:0xf bound_ctrl:1
	v_add_f32_dpp v95, v95, v95 row_half_mirror row_mask:0xf bank_mask:0xf bound_ctrl:1
	ds_read_b128 v[38:41], v89 offset:16384
	v_add_f32_dpp v94, v94, v94 row_mirror row_mask:0xf bank_mask:0xf bound_ctrl:1
	v_add_f32_dpp v95, v95, v95 row_mirror row_mask:0xf bank_mask:0xf bound_ctrl:1
	v_pk_fma_f32 v[84:85], v[32:33], v[94:95], v[84:85] op_sel_hi:[1,0,1] neg_lo:[0,1,0] neg_hi:[0,1,0]
	v_pk_fma_f32 v[82:83], v[30:31], v[94:95], v[82:83] op_sel_hi:[1,0,1] neg_lo:[0,1,0] neg_hi:[0,1,0]
	v_cndmask_b32_e64 v96, v96, v95, s[36:37]
	v_pk_fma_f32 v[2:3], v[2:3], v[48:49], v[84:85]
	v_pk_fma_f32 v[0:1], v[0:1], v[46:47], v[82:83]
	ds_read_b128 v[70:73], v89 offset:16640
	ds_read_b32 v78, v101 offset:17408
	s_waitcnt lgkmcnt(6)
	v_pk_mul_f32 v[86:87], v[2:3], v[20:21]
	v_pk_mul_f32 v[4:5], v[2:3], v[64:65]
	v_pk_fma_f32 v[86:87], v[0:1], v[18:19], v[86:87]
	v_pk_fma_f32 v[4:5], v[0:1], v[62:63], v[4:5]
	v_pk_mul_f32 v[84:85], v[76:77], v[80:81] op_sel_hi:[1,0]
	v_add_f32_e32 v94, v86, v87
	v_add_f32_e32 v95, v4, v5
	v_pk_mul_f32 v[82:83], v[74:75], v[80:81] op_sel_hi:[1,0]
	ds_read_b128 v[58:61], v89 offset:17472
	v_add_f32_dpp v94, v94, v94 quad_perm:[1,0,3,2] row_mask:0xf bank_mask:0xf bound_ctrl:1
	v_add_f32_dpp v95, v95, v95 quad_perm:[1,0,3,2] row_mask:0xf bank_mask:0xf bound_ctrl:1
	ds_read_b128 v[10:13], v89 offset:18240
	v_add_f32_dpp v94, v94, v94 quad_perm:[2,3,0,1] row_mask:0xf bank_mask:0xf bound_ctrl:1
	v_add_f32_dpp v95, v95, v95 quad_perm:[2,3,0,1] row_mask:0xf bank_mask:0xf bound_ctrl:1
	ds_read_b128 v[26:29], v89 offset:18496
	v_add_f32_dpp v94, v94, v94 row_half_mirror row_mask:0xf bank_mask:0xf bound_ctrl:1
	v_add_f32_dpp v95, v95, v95 row_half_mirror row_mask:0xf bank_mask:0xf bound_ctrl:1
	ds_read_b128 v[42:45], v89 offset:17728
	v_add_f32_dpp v94, v94, v94 row_mirror row_mask:0xf bank_mask:0xf bound_ctrl:1
	v_add_f32_dpp v95, v95, v95 row_mirror row_mask:0xf bank_mask:0xf bound_ctrl:1
	v_pk_fma_f32 v[84:85], v[36:37], v[94:95], v[84:85] op_sel_hi:[1,0,1] neg_lo:[0,1,0] neg_hi:[0,1,0]
	v_pk_fma_f32 v[82:83], v[34:35], v[94:95], v[82:83] op_sel_hi:[1,0,1] neg_lo:[0,1,0] neg_hi:[0,1,0]
	v_cndmask_b32_e64 v96, v96, v95, s[38:39]
	v_pk_fma_f32 v[2:3], v[2:3], v[52:53], v[84:85]
	v_pk_fma_f32 v[0:1], v[0:1], v[50:51], v[82:83]
	ds_read_b128 v[74:77], v89 offset:17984
	ds_read_b32 v80, v101 offset:18752
	s_waitcnt lgkmcnt(6)
	v_pk_mul_f32 v[86:87], v[2:3], v[8:9]
	v_pk_mul_f32 v[4:5], v[2:3], v[68:69]
	v_pk_fma_f32 v[86:87], v[0:1], v[6:7], v[86:87]
	v_pk_fma_f32 v[4:5], v[0:1], v[66:67], v[4:5]
	v_pk_mul_f32 v[84:85], v[72:73], v[78:79] op_sel_hi:[1,0]
	v_add_f32_e32 v94, v86, v87
	v_add_f32_e32 v95, v4, v5
	v_pk_mul_f32 v[82:83], v[70:71], v[78:79] op_sel_hi:[1,0]
	ds_read_b128 v[62:65], v89 offset:18816
	v_add_f32_dpp v94, v94, v94 quad_perm:[1,0,3,2] row_mask:0xf bank_mask:0xf bound_ctrl:1
	v_add_f32_dpp v95, v95, v95 quad_perm:[1,0,3,2] row_mask:0xf bank_mask:0xf bound_ctrl:1
	ds_read_b128 v[14:17], v89 offset:19584
	v_add_f32_dpp v94, v94, v94 quad_perm:[2,3,0,1] row_mask:0xf bank_mask:0xf bound_ctrl:1
	v_add_f32_dpp v95, v95, v95 quad_perm:[2,3,0,1] row_mask:0xf bank_mask:0xf bound_ctrl:1
	ds_read_b128 v[30:33], v89 offset:19840
	v_add_f32_dpp v94, v94, v94 row_half_mirror row_mask:0xf bank_mask:0xf bound_ctrl:1
	v_add_f32_dpp v95, v95, v95 row_half_mirror row_mask:0xf bank_mask:0xf bound_ctrl:1
	ds_read_b128 v[46:49], v89 offset:19072
	v_add_f32_dpp v94, v94, v94 row_mirror row_mask:0xf bank_mask:0xf bound_ctrl:1
	v_add_f32_dpp v95, v95, v95 row_mirror row_mask:0xf bank_mask:0xf bound_ctrl:1
	v_pk_fma_f32 v[84:85], v[24:25], v[94:95], v[84:85] op_sel_hi:[1,0,1] neg_lo:[0,1,0] neg_hi:[0,1,0]
	v_pk_fma_f32 v[82:83], v[22:23], v[94:95], v[82:83] op_sel_hi:[1,0,1] neg_lo:[0,1,0] neg_hi:[0,1,0]
	v_cndmask_b32_e64 v96, v96, v95, s[40:41]
	v_pk_fma_f32 v[2:3], v[2:3], v[40:41], v[84:85]
	v_pk_fma_f32 v[0:1], v[0:1], v[38:39], v[82:83]
	ds_read_b128 v[70:73], v89 offset:19328
	ds_read_b32 v78, v101 offset:20096
	s_waitcnt lgkmcnt(6)
	v_pk_mul_f32 v[86:87], v[2:3], v[12:13]
	v_pk_mul_f32 v[4:5], v[2:3], v[56:57]
	v_pk_fma_f32 v[86:87], v[0:1], v[10:11], v[86:87]
	v_pk_fma_f32 v[4:5], v[0:1], v[54:55], v[4:5]
	v_pk_mul_f32 v[84:85], v[76:77], v[80:81] op_sel_hi:[1,0]
	v_add_f32_e32 v94, v86, v87
	v_add_f32_e32 v95, v4, v5
	v_pk_mul_f32 v[82:83], v[74:75], v[80:81] op_sel_hi:[1,0]
	ds_read_b128 v[66:69], v89 offset:20160
	v_add_f32_dpp v94, v94, v94 quad_perm:[1,0,3,2] row_mask:0xf bank_mask:0xf bound_ctrl:1
	v_add_f32_dpp v95, v95, v95 quad_perm:[1,0,3,2] row_mask:0xf bank_mask:0xf bound_ctrl:1
	ds_read_b128 v[18:21], v89 offset:20928
	v_add_f32_dpp v94, v94, v94 quad_perm:[2,3,0,1] row_mask:0xf bank_mask:0xf bound_ctrl:1
	v_add_f32_dpp v95, v95, v95 quad_perm:[2,3,0,1] row_mask:0xf bank_mask:0xf bound_ctrl:1
	ds_read_b128 v[34:37], v89 offset:21184
	v_add_f32_dpp v94, v94, v94 row_half_mirror row_mask:0xf bank_mask:0xf bound_ctrl:1
	v_add_f32_dpp v95, v95, v95 row_half_mirror row_mask:0xf bank_mask:0xf bound_ctrl:1
	ds_read_b128 v[50:53], v89 offset:20416
	v_add_f32_dpp v94, v94, v94 row_mirror row_mask:0xf bank_mask:0xf bound_ctrl:1
	v_add_f32_dpp v95, v95, v95 row_mirror row_mask:0xf bank_mask:0xf bound_ctrl:1
	v_pk_fma_f32 v[84:85], v[28:29], v[94:95], v[84:85] op_sel_hi:[1,0,1] neg_lo:[0,1,0] neg_hi:[0,1,0]
	v_pk_fma_f32 v[82:83], v[26:27], v[94:95], v[82:83] op_sel_hi:[1,0,1] neg_lo:[0,1,0] neg_hi:[0,1,0]
	v_cndmask_b32_e64 v96, v96, v95, s[42:43]
	v_pk_fma_f32 v[2:3], v[2:3], v[44:45], v[84:85]
	v_pk_fma_f32 v[0:1], v[0:1], v[42:43], v[82:83]
	ds_read_b128 v[74:77], v89 offset:20672
	ds_read_b32 v80, v101 offset:21440
	s_waitcnt lgkmcnt(6)
	v_pk_mul_f32 v[86:87], v[2:3], v[16:17]
	v_pk_mul_f32 v[4:5], v[2:3], v[60:61]
	v_pk_fma_f32 v[86:87], v[0:1], v[14:15], v[86:87]
	v_pk_fma_f32 v[4:5], v[0:1], v[58:59], v[4:5]
	v_pk_mul_f32 v[84:85], v[72:73], v[78:79] op_sel_hi:[1,0]
	v_add_f32_e32 v94, v86, v87
	v_add_f32_e32 v95, v4, v5
	v_pk_mul_f32 v[82:83], v[70:71], v[78:79] op_sel_hi:[1,0]
	ds_read_b128 v[54:57], v89 offset:21504
	v_add_f32_dpp v94, v94, v94 quad_perm:[1,0,3,2] row_mask:0xf bank_mask:0xf bound_ctrl:1
	v_add_f32_dpp v95, v95, v95 quad_perm:[1,0,3,2] row_mask:0xf bank_mask:0xf bound_ctrl:1
	ds_read_b128 v[6:9], v89 offset:22272
	v_add_f32_dpp v94, v94, v94 quad_perm:[2,3,0,1] row_mask:0xf bank_mask:0xf bound_ctrl:1
	v_add_f32_dpp v95, v95, v95 quad_perm:[2,3,0,1] row_mask:0xf bank_mask:0xf bound_ctrl:1
	ds_read_b128 v[22:25], v89 offset:22528
	v_add_f32_dpp v94, v94, v94 row_half_mirror row_mask:0xf bank_mask:0xf bound_ctrl:1
	v_add_f32_dpp v95, v95, v95 row_half_mirror row_mask:0xf bank_mask:0xf bound_ctrl:1
	ds_read_b128 v[38:41], v89 offset:21760
	v_add_f32_dpp v94, v94, v94 row_mirror row_mask:0xf bank_mask:0xf bound_ctrl:1
	v_add_f32_dpp v95, v95, v95 row_mirror row_mask:0xf bank_mask:0xf bound_ctrl:1
	v_pk_fma_f32 v[84:85], v[32:33], v[94:95], v[84:85] op_sel_hi:[1,0,1] neg_lo:[0,1,0] neg_hi:[0,1,0]
	v_pk_fma_f32 v[82:83], v[30:31], v[94:95], v[82:83] op_sel_hi:[1,0,1] neg_lo:[0,1,0] neg_hi:[0,1,0]
	v_cndmask_b32_e64 v96, v96, v95, s[44:45]
	v_pk_fma_f32 v[2:3], v[2:3], v[48:49], v[84:85]
	v_pk_fma_f32 v[0:1], v[0:1], v[46:47], v[82:83]
	ds_read_b128 v[70:73], v89 offset:22016
	ds_read_b32 v78, v101 offset:22784
	s_waitcnt lgkmcnt(6)
	v_pk_mul_f32 v[86:87], v[2:3], v[20:21]
	v_pk_mul_f32 v[4:5], v[2:3], v[64:65]
	v_pk_fma_f32 v[86:87], v[0:1], v[18:19], v[86:87]
	v_pk_fma_f32 v[4:5], v[0:1], v[62:63], v[4:5]
	v_pk_mul_f32 v[84:85], v[76:77], v[80:81] op_sel_hi:[1,0]
	v_add_f32_e32 v94, v86, v87
	v_add_f32_e32 v95, v4, v5
	v_pk_mul_f32 v[82:83], v[74:75], v[80:81] op_sel_hi:[1,0]
	ds_read_b128 v[58:61], v89 offset:22848
	v_add_f32_dpp v94, v94, v94 quad_perm:[1,0,3,2] row_mask:0xf bank_mask:0xf bound_ctrl:1
	v_add_f32_dpp v95, v95, v95 quad_perm:[1,0,3,2] row_mask:0xf bank_mask:0xf bound_ctrl:1
	ds_read_b128 v[10:13], v89 offset:23616
	v_add_f32_dpp v94, v94, v94 quad_perm:[2,3,0,1] row_mask:0xf bank_mask:0xf bound_ctrl:1
	v_add_f32_dpp v95, v95, v95 quad_perm:[2,3,0,1] row_mask:0xf bank_mask:0xf bound_ctrl:1
	ds_read_b128 v[26:29], v89 offset:23872
	v_add_f32_dpp v94, v94, v94 row_half_mirror row_mask:0xf bank_mask:0xf bound_ctrl:1
	v_add_f32_dpp v95, v95, v95 row_half_mirror row_mask:0xf bank_mask:0xf bound_ctrl:1
	ds_read_b128 v[42:45], v89 offset:23104
	v_add_f32_dpp v94, v94, v94 row_mirror row_mask:0xf bank_mask:0xf bound_ctrl:1
	v_add_f32_dpp v95, v95, v95 row_mirror row_mask:0xf bank_mask:0xf bound_ctrl:1
	v_pk_fma_f32 v[84:85], v[36:37], v[94:95], v[84:85] op_sel_hi:[1,0,1] neg_lo:[0,1,0] neg_hi:[0,1,0]
	v_pk_fma_f32 v[82:83], v[34:35], v[94:95], v[82:83] op_sel_hi:[1,0,1] neg_lo:[0,1,0] neg_hi:[0,1,0]
	v_cndmask_b32_e64 v96, v96, v95, s[14:15]
	v_pk_fma_f32 v[2:3], v[2:3], v[52:53], v[84:85]
	v_pk_fma_f32 v[0:1], v[0:1], v[50:51], v[82:83]
	ds_read_b128 v[74:77], v89 offset:23360
	ds_read_b32 v80, v101 offset:24128
	s_waitcnt lgkmcnt(6)
	v_pk_mul_f32 v[86:87], v[2:3], v[8:9]
	v_pk_mul_f32 v[4:5], v[2:3], v[68:69]
	v_pk_fma_f32 v[86:87], v[0:1], v[6:7], v[86:87]
	v_pk_fma_f32 v[4:5], v[0:1], v[66:67], v[4:5]
	v_pk_mul_f32 v[84:85], v[72:73], v[78:79] op_sel_hi:[1,0]
	v_add_f32_e32 v94, v86, v87
	v_add_f32_e32 v95, v4, v5
	v_pk_mul_f32 v[82:83], v[70:71], v[78:79] op_sel_hi:[1,0]
	ds_read_b128 v[62:65], v89 offset:24192
	v_add_f32_dpp v94, v94, v94 quad_perm:[1,0,3,2] row_mask:0xf bank_mask:0xf bound_ctrl:1
	v_add_f32_dpp v95, v95, v95 quad_perm:[1,0,3,2] row_mask:0xf bank_mask:0xf bound_ctrl:1
	ds_read_b128 v[14:17], v89 offset:24960
	v_add_f32_dpp v94, v94, v94 quad_perm:[2,3,0,1] row_mask:0xf bank_mask:0xf bound_ctrl:1
	v_add_f32_dpp v95, v95, v95 quad_perm:[2,3,0,1] row_mask:0xf bank_mask:0xf bound_ctrl:1
	ds_read_b128 v[30:33], v89 offset:25216
	v_add_f32_dpp v94, v94, v94 row_half_mirror row_mask:0xf bank_mask:0xf bound_ctrl:1
	v_add_f32_dpp v95, v95, v95 row_half_mirror row_mask:0xf bank_mask:0xf bound_ctrl:1
	ds_read_b128 v[46:49], v89 offset:24448
	v_add_f32_dpp v94, v94, v94 row_mirror row_mask:0xf bank_mask:0xf bound_ctrl:1
	v_add_f32_dpp v95, v95, v95 row_mirror row_mask:0xf bank_mask:0xf bound_ctrl:1
	v_pk_fma_f32 v[84:85], v[24:25], v[94:95], v[84:85] op_sel_hi:[1,0,1] neg_lo:[0,1,0] neg_hi:[0,1,0]
	v_pk_fma_f32 v[82:83], v[22:23], v[94:95], v[82:83] op_sel_hi:[1,0,1] neg_lo:[0,1,0] neg_hi:[0,1,0]
	v_cndmask_b32_e64 v96, v96, v95, s[12:13]
	v_pk_fma_f32 v[2:3], v[2:3], v[40:41], v[84:85]
	v_pk_fma_f32 v[0:1], v[0:1], v[38:39], v[82:83]
	ds_read_b128 v[70:73], v89 offset:24704
	ds_read_b32 v78, v101 offset:25472
	global_store_dword v[90:91], v96, off
	v_lshl_add_u64 v[90:91], v[90:91], 0, s[6:7]
	s_waitcnt lgkmcnt(6)
	v_pk_mul_f32 v[86:87], v[2:3], v[12:13]
	v_pk_mul_f32 v[4:5], v[2:3], v[56:57]
	v_pk_fma_f32 v[86:87], v[0:1], v[10:11], v[86:87]
	v_pk_fma_f32 v[4:5], v[0:1], v[54:55], v[4:5]
	v_pk_mul_f32 v[84:85], v[76:77], v[80:81] op_sel_hi:[1,0]
	v_add_f32_e32 v94, v86, v87
	v_add_f32_e32 v95, v4, v5
	v_pk_mul_f32 v[82:83], v[74:75], v[80:81] op_sel_hi:[1,0]
	ds_read_b128 v[66:69], v89 offset:25536
	v_add_f32_dpp v94, v94, v94 quad_perm:[1,0,3,2] row_mask:0xf bank_mask:0xf bound_ctrl:1
	v_add_f32_dpp v95, v95, v95 quad_perm:[1,0,3,2] row_mask:0xf bank_mask:0xf bound_ctrl:1
	ds_read_b128 v[18:21], v89 offset:26304
	v_add_f32_dpp v94, v94, v94 quad_perm:[2,3,0,1] row_mask:0xf bank_mask:0xf bound_ctrl:1
	v_add_f32_dpp v95, v95, v95 quad_perm:[2,3,0,1] row_mask:0xf bank_mask:0xf bound_ctrl:1
	ds_read_b128 v[34:37], v89 offset:26560
	v_add_f32_dpp v94, v94, v94 row_half_mirror row_mask:0xf bank_mask:0xf bound_ctrl:1
	v_add_f32_dpp v95, v95, v95 row_half_mirror row_mask:0xf bank_mask:0xf bound_ctrl:1
	ds_read_b128 v[50:53], v89 offset:25792
	v_add_f32_dpp v94, v94, v94 row_mirror row_mask:0xf bank_mask:0xf bound_ctrl:1
	v_add_f32_dpp v95, v95, v95 row_mirror row_mask:0xf bank_mask:0xf bound_ctrl:1
	v_pk_fma_f32 v[84:85], v[28:29], v[94:95], v[84:85] op_sel_hi:[1,0,1] neg_lo:[0,1,0] neg_hi:[0,1,0]
	v_pk_fma_f32 v[82:83], v[26:27], v[94:95], v[82:83] op_sel_hi:[1,0,1] neg_lo:[0,1,0] neg_hi:[0,1,0]
	v_cndmask_b32_e64 v96, 0, v95, s[16:17]
	v_pk_fma_f32 v[2:3], v[2:3], v[44:45], v[84:85]
	v_pk_fma_f32 v[0:1], v[0:1], v[42:43], v[82:83]
	ds_read_b128 v[74:77], v89 offset:26048
	ds_read_b32 v80, v101 offset:26816
	s_waitcnt lgkmcnt(6)
	v_pk_mul_f32 v[86:87], v[2:3], v[16:17]
	v_pk_mul_f32 v[4:5], v[2:3], v[60:61]
	v_pk_fma_f32 v[86:87], v[0:1], v[14:15], v[86:87]
	v_pk_fma_f32 v[4:5], v[0:1], v[58:59], v[4:5]
	v_pk_mul_f32 v[84:85], v[72:73], v[78:79] op_sel_hi:[1,0]
	v_add_f32_e32 v94, v86, v87
	v_add_f32_e32 v95, v4, v5
	v_pk_mul_f32 v[82:83], v[70:71], v[78:79] op_sel_hi:[1,0]
	ds_read_b128 v[54:57], v89 offset:26880
	v_add_f32_dpp v94, v94, v94 quad_perm:[1,0,3,2] row_mask:0xf bank_mask:0xf bound_ctrl:1
	v_add_f32_dpp v95, v95, v95 quad_perm:[1,0,3,2] row_mask:0xf bank_mask:0xf bound_ctrl:1
	ds_read_b128 v[6:9], v89 offset:27648
	v_add_f32_dpp v94, v94, v94 quad_perm:[2,3,0,1] row_mask:0xf bank_mask:0xf bound_ctrl:1
	v_add_f32_dpp v95, v95, v95 quad_perm:[2,3,0,1] row_mask:0xf bank_mask:0xf bound_ctrl:1
	ds_read_b128 v[22:25], v89 offset:27904
	v_add_f32_dpp v94, v94, v94 row_half_mirror row_mask:0xf bank_mask:0xf bound_ctrl:1
	v_add_f32_dpp v95, v95, v95 row_half_mirror row_mask:0xf bank_mask:0xf bound_ctrl:1
	ds_read_b128 v[38:41], v89 offset:27136
	v_add_f32_dpp v94, v94, v94 row_mirror row_mask:0xf bank_mask:0xf bound_ctrl:1
	v_add_f32_dpp v95, v95, v95 row_mirror row_mask:0xf bank_mask:0xf bound_ctrl:1
	v_pk_fma_f32 v[84:85], v[32:33], v[94:95], v[84:85] op_sel_hi:[1,0,1] neg_lo:[0,1,0] neg_hi:[0,1,0]
	v_pk_fma_f32 v[82:83], v[30:31], v[94:95], v[82:83] op_sel_hi:[1,0,1] neg_lo:[0,1,0] neg_hi:[0,1,0]
	v_cndmask_b32_e64 v96, v96, v95, s[18:19]
	v_pk_fma_f32 v[2:3], v[2:3], v[48:49], v[84:85]
	v_pk_fma_f32 v[0:1], v[0:1], v[46:47], v[82:83]
	ds_read_b128 v[70:73], v89 offset:27392
	ds_read_b32 v78, v101 offset:28160
	s_waitcnt lgkmcnt(6)
	v_pk_mul_f32 v[86:87], v[2:3], v[20:21]
	v_pk_mul_f32 v[4:5], v[2:3], v[64:65]
	v_pk_fma_f32 v[86:87], v[0:1], v[18:19], v[86:87]
	v_pk_fma_f32 v[4:5], v[0:1], v[62:63], v[4:5]
	v_pk_mul_f32 v[84:85], v[76:77], v[80:81] op_sel_hi:[1,0]
	v_add_f32_e32 v94, v86, v87
	v_add_f32_e32 v95, v4, v5
	v_pk_mul_f32 v[82:83], v[74:75], v[80:81] op_sel_hi:[1,0]
	ds_read_b128 v[58:61], v89 offset:28224
	v_add_f32_dpp v94, v94, v94 quad_perm:[1,0,3,2] row_mask:0xf bank_mask:0xf bound_ctrl:1
	v_add_f32_dpp v95, v95, v95 quad_perm:[1,0,3,2] row_mask:0xf bank_mask:0xf bound_ctrl:1
	ds_read_b128 v[10:13], v89 offset:28992
	v_add_f32_dpp v94, v94, v94 quad_perm:[2,3,0,1] row_mask:0xf bank_mask:0xf bound_ctrl:1
	v_add_f32_dpp v95, v95, v95 quad_perm:[2,3,0,1] row_mask:0xf bank_mask:0xf bound_ctrl:1
	ds_read_b128 v[26:29], v89 offset:29248
	v_add_f32_dpp v94, v94, v94 row_half_mirror row_mask:0xf bank_mask:0xf bound_ctrl:1
	v_add_f32_dpp v95, v95, v95 row_half_mirror row_mask:0xf bank_mask:0xf bound_ctrl:1
	ds_read_b128 v[42:45], v89 offset:28480
	v_add_f32_dpp v94, v94, v94 row_mirror row_mask:0xf bank_mask:0xf bound_ctrl:1
	v_add_f32_dpp v95, v95, v95 row_mirror row_mask:0xf bank_mask:0xf bound_ctrl:1
	v_pk_fma_f32 v[84:85], v[36:37], v[94:95], v[84:85] op_sel_hi:[1,0,1] neg_lo:[0,1,0] neg_hi:[0,1,0]
	v_pk_fma_f32 v[82:83], v[34:35], v[94:95], v[82:83] op_sel_hi:[1,0,1] neg_lo:[0,1,0] neg_hi:[0,1,0]
	v_cndmask_b32_e64 v96, v96, v95, s[20:21]
	v_pk_fma_f32 v[2:3], v[2:3], v[52:53], v[84:85]
	v_pk_fma_f32 v[0:1], v[0:1], v[50:51], v[82:83]
	ds_read_b128 v[74:77], v89 offset:28736
	ds_read_b32 v80, v101 offset:29504
	s_waitcnt lgkmcnt(6)
	v_pk_mul_f32 v[86:87], v[2:3], v[8:9]
	v_pk_mul_f32 v[4:5], v[2:3], v[68:69]
	v_pk_fma_f32 v[86:87], v[0:1], v[6:7], v[86:87]
	v_pk_fma_f32 v[4:5], v[0:1], v[66:67], v[4:5]
	v_pk_mul_f32 v[84:85], v[72:73], v[78:79] op_sel_hi:[1,0]
	v_add_f32_e32 v94, v86, v87
	v_add_f32_e32 v95, v4, v5
	v_pk_mul_f32 v[82:83], v[70:71], v[78:79] op_sel_hi:[1,0]
	ds_read_b128 v[62:65], v89 offset:29568
	v_add_f32_dpp v94, v94, v94 quad_perm:[1,0,3,2] row_mask:0xf bank_mask:0xf bound_ctrl:1
	v_add_f32_dpp v95, v95, v95 quad_perm:[1,0,3,2] row_mask:0xf bank_mask:0xf bound_ctrl:1
	ds_read_b128 v[14:17], v89 offset:30336
	v_add_f32_dpp v94, v94, v94 quad_perm:[2,3,0,1] row_mask:0xf bank_mask:0xf bound_ctrl:1
	v_add_f32_dpp v95, v95, v95 quad_perm:[2,3,0,1] row_mask:0xf bank_mask:0xf bound_ctrl:1
	ds_read_b128 v[30:33], v89 offset:30592
	v_add_f32_dpp v94, v94, v94 row_half_mirror row_mask:0xf bank_mask:0xf bound_ctrl:1
	v_add_f32_dpp v95, v95, v95 row_half_mirror row_mask:0xf bank_mask:0xf bound_ctrl:1
	ds_read_b128 v[46:49], v89 offset:29824
	v_add_f32_dpp v94, v94, v94 row_mirror row_mask:0xf bank_mask:0xf bound_ctrl:1
	v_add_f32_dpp v95, v95, v95 row_mirror row_mask:0xf bank_mask:0xf bound_ctrl:1
	v_pk_fma_f32 v[84:85], v[24:25], v[94:95], v[84:85] op_sel_hi:[1,0,1] neg_lo:[0,1,0] neg_hi:[0,1,0]
	v_pk_fma_f32 v[82:83], v[22:23], v[94:95], v[82:83] op_sel_hi:[1,0,1] neg_lo:[0,1,0] neg_hi:[0,1,0]
	v_cndmask_b32_e64 v96, v96, v95, s[22:23]
	v_pk_fma_f32 v[2:3], v[2:3], v[40:41], v[84:85]
	v_pk_fma_f32 v[0:1], v[0:1], v[38:39], v[82:83]
	ds_read_b128 v[70:73], v89 offset:30080
	ds_read_b32 v78, v101 offset:30848
	s_waitcnt lgkmcnt(6)
	v_pk_mul_f32 v[86:87], v[2:3], v[12:13]
	v_pk_mul_f32 v[4:5], v[2:3], v[56:57]
	v_pk_fma_f32 v[86:87], v[0:1], v[10:11], v[86:87]
	v_pk_fma_f32 v[4:5], v[0:1], v[54:55], v[4:5]
	v_pk_mul_f32 v[84:85], v[76:77], v[80:81] op_sel_hi:[1,0]
	v_add_f32_e32 v94, v86, v87
	v_add_f32_e32 v95, v4, v5
	v_pk_mul_f32 v[82:83], v[74:75], v[80:81] op_sel_hi:[1,0]
	ds_read_b128 v[66:69], v89 offset:30912
	v_add_f32_dpp v94, v94, v94 quad_perm:[1,0,3,2] row_mask:0xf bank_mask:0xf bound_ctrl:1
	v_add_f32_dpp v95, v95, v95 quad_perm:[1,0,3,2] row_mask:0xf bank_mask:0xf bound_ctrl:1
	ds_read_b128 v[18:21], v89 offset:31680
	v_add_f32_dpp v94, v94, v94 quad_perm:[2,3,0,1] row_mask:0xf bank_mask:0xf bound_ctrl:1
	v_add_f32_dpp v95, v95, v95 quad_perm:[2,3,0,1] row_mask:0xf bank_mask:0xf bound_ctrl:1
	ds_read_b128 v[34:37], v89 offset:31936
	v_add_f32_dpp v94, v94, v94 row_half_mirror row_mask:0xf bank_mask:0xf bound_ctrl:1
	v_add_f32_dpp v95, v95, v95 row_half_mirror row_mask:0xf bank_mask:0xf bound_ctrl:1
	ds_read_b128 v[50:53], v89 offset:31168
	v_add_f32_dpp v94, v94, v94 row_mirror row_mask:0xf bank_mask:0xf bound_ctrl:1
	v_add_f32_dpp v95, v95, v95 row_mirror row_mask:0xf bank_mask:0xf bound_ctrl:1
	v_pk_fma_f32 v[84:85], v[28:29], v[94:95], v[84:85] op_sel_hi:[1,0,1] neg_lo:[0,1,0] neg_hi:[0,1,0]
	v_pk_fma_f32 v[82:83], v[26:27], v[94:95], v[82:83] op_sel_hi:[1,0,1] neg_lo:[0,1,0] neg_hi:[0,1,0]
	v_cndmask_b32_e64 v96, v96, v95, s[24:25]
	v_pk_fma_f32 v[2:3], v[2:3], v[44:45], v[84:85]
	v_pk_fma_f32 v[0:1], v[0:1], v[42:43], v[82:83]
	ds_read_b128 v[74:77], v89 offset:31424
	ds_read_b32 v80, v101 offset:32192
	s_waitcnt lgkmcnt(6)
	v_pk_mul_f32 v[86:87], v[2:3], v[16:17]
	v_pk_mul_f32 v[4:5], v[2:3], v[60:61]
	v_pk_fma_f32 v[86:87], v[0:1], v[14:15], v[86:87]
	v_pk_fma_f32 v[4:5], v[0:1], v[58:59], v[4:5]
	v_pk_mul_f32 v[84:85], v[72:73], v[78:79] op_sel_hi:[1,0]
	v_add_f32_e32 v94, v86, v87
	v_add_f32_e32 v95, v4, v5
	v_pk_mul_f32 v[82:83], v[70:71], v[78:79] op_sel_hi:[1,0]
	ds_read_b128 v[54:57], v89 offset:32256
	v_add_f32_dpp v94, v94, v94 quad_perm:[1,0,3,2] row_mask:0xf bank_mask:0xf bound_ctrl:1
	v_add_f32_dpp v95, v95, v95 quad_perm:[1,0,3,2] row_mask:0xf bank_mask:0xf bound_ctrl:1
	ds_read_b128 v[6:9], v89 offset:33024
	v_add_f32_dpp v94, v94, v94 quad_perm:[2,3,0,1] row_mask:0xf bank_mask:0xf bound_ctrl:1
	v_add_f32_dpp v95, v95, v95 quad_perm:[2,3,0,1] row_mask:0xf bank_mask:0xf bound_ctrl:1
	ds_read_b128 v[22:25], v89 offset:33280
	v_add_f32_dpp v94, v94, v94 row_half_mirror row_mask:0xf bank_mask:0xf bound_ctrl:1
	v_add_f32_dpp v95, v95, v95 row_half_mirror row_mask:0xf bank_mask:0xf bound_ctrl:1
	ds_read_b128 v[38:41], v89 offset:32512
	v_add_f32_dpp v94, v94, v94 row_mirror row_mask:0xf bank_mask:0xf bound_ctrl:1
	v_add_f32_dpp v95, v95, v95 row_mirror row_mask:0xf bank_mask:0xf bound_ctrl:1
	v_pk_fma_f32 v[84:85], v[32:33], v[94:95], v[84:85] op_sel_hi:[1,0,1] neg_lo:[0,1,0] neg_hi:[0,1,0]
	v_pk_fma_f32 v[82:83], v[30:31], v[94:95], v[82:83] op_sel_hi:[1,0,1] neg_lo:[0,1,0] neg_hi:[0,1,0]
	v_cndmask_b32_e64 v96, v96, v95, s[26:27]
	v_pk_fma_f32 v[2:3], v[2:3], v[48:49], v[84:85]
	v_pk_fma_f32 v[0:1], v[0:1], v[46:47], v[82:83]
	ds_read_b128 v[70:73], v89 offset:32768
	ds_read_b32 v78, v101 offset:33536
	s_waitcnt lgkmcnt(6)
	v_pk_mul_f32 v[86:87], v[2:3], v[20:21]
	v_pk_mul_f32 v[4:5], v[2:3], v[64:65]
	v_pk_fma_f32 v[86:87], v[0:1], v[18:19], v[86:87]
	v_pk_fma_f32 v[4:5], v[0:1], v[62:63], v[4:5]
	v_pk_mul_f32 v[84:85], v[76:77], v[80:81] op_sel_hi:[1,0]
	v_add_f32_e32 v94, v86, v87
	v_add_f32_e32 v95, v4, v5
	v_pk_mul_f32 v[82:83], v[74:75], v[80:81] op_sel_hi:[1,0]
	ds_read_b128 v[58:61], v89 offset:33600
	v_add_f32_dpp v94, v94, v94 quad_perm:[1,0,3,2] row_mask:0xf bank_mask:0xf bound_ctrl:1
	v_add_f32_dpp v95, v95, v95 quad_perm:[1,0,3,2] row_mask:0xf bank_mask:0xf bound_ctrl:1
	ds_read_b128 v[10:13], v89 offset:34368
	v_add_f32_dpp v94, v94, v94 quad_perm:[2,3,0,1] row_mask:0xf bank_mask:0xf bound_ctrl:1
	v_add_f32_dpp v95, v95, v95 quad_perm:[2,3,0,1] row_mask:0xf bank_mask:0xf bound_ctrl:1
	ds_read_b128 v[26:29], v89 offset:34624
	v_add_f32_dpp v94, v94, v94 row_half_mirror row_mask:0xf bank_mask:0xf bound_ctrl:1
	v_add_f32_dpp v95, v95, v95 row_half_mirror row_mask:0xf bank_mask:0xf bound_ctrl:1
	ds_read_b128 v[42:45], v89 offset:33856
	v_add_f32_dpp v94, v94, v94 row_mirror row_mask:0xf bank_mask:0xf bound_ctrl:1
	v_add_f32_dpp v95, v95, v95 row_mirror row_mask:0xf bank_mask:0xf bound_ctrl:1
	v_pk_fma_f32 v[84:85], v[36:37], v[94:95], v[84:85] op_sel_hi:[1,0,1] neg_lo:[0,1,0] neg_hi:[0,1,0]
	v_pk_fma_f32 v[82:83], v[34:35], v[94:95], v[82:83] op_sel_hi:[1,0,1] neg_lo:[0,1,0] neg_hi:[0,1,0]
	v_cndmask_b32_e64 v96, v96, v95, s[28:29]
	v_pk_fma_f32 v[2:3], v[2:3], v[52:53], v[84:85]
	v_pk_fma_f32 v[0:1], v[0:1], v[50:51], v[82:83]
	ds_read_b128 v[74:77], v89 offset:34112
	ds_read_b32 v80, v101 offset:34880
	s_waitcnt lgkmcnt(6)
	v_pk_mul_f32 v[86:87], v[2:3], v[8:9]
	v_pk_mul_f32 v[4:5], v[2:3], v[68:69]
	v_pk_fma_f32 v[86:87], v[0:1], v[6:7], v[86:87]
	v_pk_fma_f32 v[4:5], v[0:1], v[66:67], v[4:5]
	v_pk_mul_f32 v[84:85], v[72:73], v[78:79] op_sel_hi:[1,0]
	v_add_f32_e32 v94, v86, v87
	v_add_f32_e32 v95, v4, v5
	v_pk_mul_f32 v[82:83], v[70:71], v[78:79] op_sel_hi:[1,0]
	ds_read_b128 v[62:65], v89 offset:34944
	v_add_f32_dpp v94, v94, v94 quad_perm:[1,0,3,2] row_mask:0xf bank_mask:0xf bound_ctrl:1
	v_add_f32_dpp v95, v95, v95 quad_perm:[1,0,3,2] row_mask:0xf bank_mask:0xf bound_ctrl:1
	ds_read_b128 v[14:17], v89 offset:35712
	v_add_f32_dpp v94, v94, v94 quad_perm:[2,3,0,1] row_mask:0xf bank_mask:0xf bound_ctrl:1
	v_add_f32_dpp v95, v95, v95 quad_perm:[2,3,0,1] row_mask:0xf bank_mask:0xf bound_ctrl:1
	ds_read_b128 v[30:33], v89 offset:35968
	v_add_f32_dpp v94, v94, v94 row_half_mirror row_mask:0xf bank_mask:0xf bound_ctrl:1
	v_add_f32_dpp v95, v95, v95 row_half_mirror row_mask:0xf bank_mask:0xf bound_ctrl:1
	ds_read_b128 v[46:49], v89 offset:35200
	v_add_f32_dpp v94, v94, v94 row_mirror row_mask:0xf bank_mask:0xf bound_ctrl:1
	v_add_f32_dpp v95, v95, v95 row_mirror row_mask:0xf bank_mask:0xf bound_ctrl:1
	v_pk_fma_f32 v[84:85], v[24:25], v[94:95], v[84:85] op_sel_hi:[1,0,1] neg_lo:[0,1,0] neg_hi:[0,1,0]
	v_pk_fma_f32 v[82:83], v[22:23], v[94:95], v[82:83] op_sel_hi:[1,0,1] neg_lo:[0,1,0] neg_hi:[0,1,0]
	v_cndmask_b32_e64 v96, v96, v95, s[30:31]
	v_pk_fma_f32 v[2:3], v[2:3], v[40:41], v[84:85]
	v_pk_fma_f32 v[0:1], v[0:1], v[38:39], v[82:83]
	ds_read_b128 v[70:73], v89 offset:35456
	ds_read_b32 v78, v101 offset:36224
	s_waitcnt lgkmcnt(6)
	v_pk_mul_f32 v[86:87], v[2:3], v[12:13]
	v_pk_mul_f32 v[4:5], v[2:3], v[56:57]
	v_pk_fma_f32 v[86:87], v[0:1], v[10:11], v[86:87]
	v_pk_fma_f32 v[4:5], v[0:1], v[54:55], v[4:5]
	v_pk_mul_f32 v[84:85], v[76:77], v[80:81] op_sel_hi:[1,0]
	v_add_f32_e32 v94, v86, v87
	v_add_f32_e32 v95, v4, v5
	v_pk_mul_f32 v[82:83], v[74:75], v[80:81] op_sel_hi:[1,0]
	ds_read_b128 v[66:69], v89 offset:36288
	v_add_f32_dpp v94, v94, v94 quad_perm:[1,0,3,2] row_mask:0xf bank_mask:0xf bound_ctrl:1
	v_add_f32_dpp v95, v95, v95 quad_perm:[1,0,3,2] row_mask:0xf bank_mask:0xf bound_ctrl:1
	ds_read_b128 v[18:21], v89 offset:37056
	v_add_f32_dpp v94, v94, v94 quad_perm:[2,3,0,1] row_mask:0xf bank_mask:0xf bound_ctrl:1
	v_add_f32_dpp v95, v95, v95 quad_perm:[2,3,0,1] row_mask:0xf bank_mask:0xf bound_ctrl:1
	ds_read_b128 v[34:37], v89 offset:37312
	v_add_f32_dpp v94, v94, v94 row_half_mirror row_mask:0xf bank_mask:0xf bound_ctrl:1
	v_add_f32_dpp v95, v95, v95 row_half_mirror row_mask:0xf bank_mask:0xf bound_ctrl:1
	ds_read_b128 v[50:53], v89 offset:36544
	v_add_f32_dpp v94, v94, v94 row_mirror row_mask:0xf bank_mask:0xf bound_ctrl:1
	v_add_f32_dpp v95, v95, v95 row_mirror row_mask:0xf bank_mask:0xf bound_ctrl:1
	v_pk_fma_f32 v[84:85], v[28:29], v[94:95], v[84:85] op_sel_hi:[1,0,1] neg_lo:[0,1,0] neg_hi:[0,1,0]
	v_pk_fma_f32 v[82:83], v[26:27], v[94:95], v[82:83] op_sel_hi:[1,0,1] neg_lo:[0,1,0] neg_hi:[0,1,0]
	v_cndmask_b32_e64 v96, v96, v95, s[34:35]
	v_pk_fma_f32 v[2:3], v[2:3], v[44:45], v[84:85]
	v_pk_fma_f32 v[0:1], v[0:1], v[42:43], v[82:83]
	ds_read_b128 v[74:77], v89 offset:36800
	ds_read_b32 v80, v101 offset:37568
	s_waitcnt lgkmcnt(6)
	v_pk_mul_f32 v[86:87], v[2:3], v[16:17]
	v_pk_mul_f32 v[4:5], v[2:3], v[60:61]
	v_pk_fma_f32 v[86:87], v[0:1], v[14:15], v[86:87]
	v_pk_fma_f32 v[4:5], v[0:1], v[58:59], v[4:5]
	v_pk_mul_f32 v[84:85], v[72:73], v[78:79] op_sel_hi:[1,0]
	v_add_f32_e32 v94, v86, v87
	v_add_f32_e32 v95, v4, v5
	v_pk_mul_f32 v[82:83], v[70:71], v[78:79] op_sel_hi:[1,0]
	ds_read_b128 v[54:57], v89 offset:37632
	v_add_f32_dpp v94, v94, v94 quad_perm:[1,0,3,2] row_mask:0xf bank_mask:0xf bound_ctrl:1
	v_add_f32_dpp v95, v95, v95 quad_perm:[1,0,3,2] row_mask:0xf bank_mask:0xf bound_ctrl:1
	ds_read_b128 v[6:9], v89 offset:38400
	v_add_f32_dpp v94, v94, v94 quad_perm:[2,3,0,1] row_mask:0xf bank_mask:0xf bound_ctrl:1
	v_add_f32_dpp v95, v95, v95 quad_perm:[2,3,0,1] row_mask:0xf bank_mask:0xf bound_ctrl:1
	ds_read_b128 v[22:25], v89 offset:38656
	v_add_f32_dpp v94, v94, v94 row_half_mirror row_mask:0xf bank_mask:0xf bound_ctrl:1
	v_add_f32_dpp v95, v95, v95 row_half_mirror row_mask:0xf bank_mask:0xf bound_ctrl:1
	ds_read_b128 v[38:41], v89 offset:37888
	v_add_f32_dpp v94, v94, v94 row_mirror row_mask:0xf bank_mask:0xf bound_ctrl:1
	v_add_f32_dpp v95, v95, v95 row_mirror row_mask:0xf bank_mask:0xf bound_ctrl:1
	v_pk_fma_f32 v[84:85], v[32:33], v[94:95], v[84:85] op_sel_hi:[1,0,1] neg_lo:[0,1,0] neg_hi:[0,1,0]
	v_pk_fma_f32 v[82:83], v[30:31], v[94:95], v[82:83] op_sel_hi:[1,0,1] neg_lo:[0,1,0] neg_hi:[0,1,0]
	v_cndmask_b32_e64 v96, v96, v95, s[36:37]
	v_pk_fma_f32 v[2:3], v[2:3], v[48:49], v[84:85]
	v_pk_fma_f32 v[0:1], v[0:1], v[46:47], v[82:83]
	ds_read_b128 v[70:73], v89 offset:38144
	ds_read_b32 v78, v101 offset:38912
	s_waitcnt lgkmcnt(6)
	v_pk_mul_f32 v[86:87], v[2:3], v[20:21]
	v_pk_mul_f32 v[4:5], v[2:3], v[64:65]
	v_pk_fma_f32 v[86:87], v[0:1], v[18:19], v[86:87]
	v_pk_fma_f32 v[4:5], v[0:1], v[62:63], v[4:5]
	v_pk_mul_f32 v[84:85], v[76:77], v[80:81] op_sel_hi:[1,0]
	v_add_f32_e32 v94, v86, v87
	v_add_f32_e32 v95, v4, v5
	v_pk_mul_f32 v[82:83], v[74:75], v[80:81] op_sel_hi:[1,0]
	ds_read_b128 v[58:61], v89 offset:38976
	v_add_f32_dpp v94, v94, v94 quad_perm:[1,0,3,2] row_mask:0xf bank_mask:0xf bound_ctrl:1
	v_add_f32_dpp v95, v95, v95 quad_perm:[1,0,3,2] row_mask:0xf bank_mask:0xf bound_ctrl:1
	ds_read_b128 v[10:13], v89 offset:39744
	v_add_f32_dpp v94, v94, v94 quad_perm:[2,3,0,1] row_mask:0xf bank_mask:0xf bound_ctrl:1
	v_add_f32_dpp v95, v95, v95 quad_perm:[2,3,0,1] row_mask:0xf bank_mask:0xf bound_ctrl:1
	ds_read_b128 v[26:29], v89 offset:40000
	v_add_f32_dpp v94, v94, v94 row_half_mirror row_mask:0xf bank_mask:0xf bound_ctrl:1
	v_add_f32_dpp v95, v95, v95 row_half_mirror row_mask:0xf bank_mask:0xf bound_ctrl:1
	ds_read_b128 v[42:45], v89 offset:39232
	v_add_f32_dpp v94, v94, v94 row_mirror row_mask:0xf bank_mask:0xf bound_ctrl:1
	v_add_f32_dpp v95, v95, v95 row_mirror row_mask:0xf bank_mask:0xf bound_ctrl:1
	v_pk_fma_f32 v[84:85], v[36:37], v[94:95], v[84:85] op_sel_hi:[1,0,1] neg_lo:[0,1,0] neg_hi:[0,1,0]
	v_pk_fma_f32 v[82:83], v[34:35], v[94:95], v[82:83] op_sel_hi:[1,0,1] neg_lo:[0,1,0] neg_hi:[0,1,0]
	v_cndmask_b32_e64 v96, v96, v95, s[38:39]
	v_pk_fma_f32 v[2:3], v[2:3], v[52:53], v[84:85]
	v_pk_fma_f32 v[0:1], v[0:1], v[50:51], v[82:83]
	ds_read_b128 v[74:77], v89 offset:39488
	ds_read_b32 v80, v101 offset:40256
	s_waitcnt lgkmcnt(6)
; template <int CH>
; __device__ __forceinline__ void scan_unit(const Args& a, int l, int unit, unsigned char* lds) {
;     ...
;             __syncthreads();
	v_pk_mul_f32 v[86:87], v[2:3], v[8:9]
	v_pk_mul_f32 v[4:5], v[2:3], v[68:69]
	v_pk_fma_f32 v[86:87], v[0:1], v[6:7], v[86:87]
	v_pk_fma_f32 v[4:5], v[0:1], v[66:67], v[4:5]
	v_pk_mul_f32 v[84:85], v[72:73], v[78:79] op_sel_hi:[1,0]
	v_add_f32_e32 v94, v86, v87
	v_add_f32_e32 v95, v4, v5
	v_pk_mul_f32 v[82:83], v[70:71], v[78:79] op_sel_hi:[1,0]
	ds_read_b128 v[62:65], v89 offset:40320
	v_add_f32_dpp v94, v94, v94 quad_perm:[1,0,3,2] row_mask:0xf bank_mask:0xf bound_ctrl:1
	v_add_f32_dpp v95, v95, v95 quad_perm:[1,0,3,2] row_mask:0xf bank_mask:0xf bound_ctrl:1
	ds_read_b128 v[14:17], v89 offset:41088
	v_add_f32_dpp v94, v94, v94 quad_perm:[2,3,0,1] row_mask:0xf bank_mask:0xf bound_ctrl:1
	v_add_f32_dpp v95, v95, v95 quad_perm:[2,3,0,1] row_mask:0xf bank_mask:0xf bound_ctrl:1
	ds_read_b128 v[30:33], v89 offset:41344
	v_add_f32_dpp v94, v94, v94 row_half_mirror row_mask:0xf bank_mask:0xf bound_ctrl:1
	v_add_f32_dpp v95, v95, v95 row_half_mirror row_mask:0xf bank_mask:0xf bound_ctrl:1
	ds_read_b128 v[46:49], v89 offset:40576
	v_add_f32_dpp v94, v94, v94 row_mirror row_mask:0xf bank_mask:0xf bound_ctrl:1
	v_add_f32_dpp v95, v95, v95 row_mirror row_mask:0xf bank_mask:0xf bound_ctrl:1
	v_pk_fma_f32 v[84:85], v[24:25], v[94:95], v[84:85] op_sel_hi:[1,0,1] neg_lo:[0,1,0] neg_hi:[0,1,0]
	v_pk_fma_f32 v[82:83], v[22:23], v[94:95], v[82:83] op_sel_hi:[1,0,1] neg_lo:[0,1,0] neg_hi:[0,1,0]
	v_cndmask_b32_e64 v96, v96, v95, s[40:41]
	v_pk_fma_f32 v[2:3], v[2:3], v[40:41], v[84:85]
	v_pk_fma_f32 v[0:1], v[0:1], v[38:39], v[82:83]
	ds_read_b128 v[70:73], v89 offset:40832
	ds_read_b32 v78, v101 offset:41600
	s_waitcnt lgkmcnt(6)
	v_pk_mul_f32 v[86:87], v[2:3], v[12:13]
	v_pk_mul_f32 v[4:5], v[2:3], v[56:57]
	v_pk_fma_f32 v[86:87], v[0:1], v[10:11], v[86:87]
	v_pk_fma_f32 v[4:5], v[0:1], v[54:55], v[4:5]
	v_pk_mul_f32 v[84:85], v[76:77], v[80:81] op_sel_hi:[1,0]
	v_add_f32_e32 v94, v86, v87
	v_add_f32_e32 v95, v4, v5
	v_pk_mul_f32 v[82:83], v[74:75], v[80:81] op_sel_hi:[1,0]
	ds_read_b128 v[66:69], v89 offset:41664
	v_add_f32_dpp v94, v94, v94 quad_perm:[1,0,3,2] row_mask:0xf bank_mask:0xf bound_ctrl:1
	v_add_f32_dpp v95, v95, v95 quad_perm:[1,0,3,2] row_mask:0xf bank_mask:0xf bound_ctrl:1
	ds_read_b128 v[18:21], v89 offset:42432
	v_add_f32_dpp v94, v94, v94 quad_perm:[2,3,0,1] row_mask:0xf bank_mask:0xf bound_ctrl:1
	v_add_f32_dpp v95, v95, v95 quad_perm:[2,3,0,1] row_mask:0xf bank_mask:0xf bound_ctrl:1
	ds_read_b128 v[34:37], v89 offset:42688
	v_add_f32_dpp v94, v94, v94 row_half_mirror row_mask:0xf bank_mask:0xf bound_ctrl:1
	v_add_f32_dpp v95, v95, v95 row_half_mirror row_mask:0xf bank_mask:0xf bound_ctrl:1
	ds_read_b128 v[50:53], v89 offset:41920
	v_add_f32_dpp v94, v94, v94 row_mirror row_mask:0xf bank_mask:0xf bound_ctrl:1
	v_add_f32_dpp v95, v95, v95 row_mirror row_mask:0xf bank_mask:0xf bound_ctrl:1
	v_pk_fma_f32 v[84:85], v[28:29], v[94:95], v[84:85] op_sel_hi:[1,0,1] neg_lo:[0,1,0] neg_hi:[0,1,0]
	v_pk_fma_f32 v[82:83], v[26:27], v[94:95], v[82:83] op_sel_hi:[1,0,1] neg_lo:[0,1,0] neg_hi:[0,1,0]
	v_cndmask_b32_e64 v96, v96, v95, s[42:43]
	v_pk_fma_f32 v[2:3], v[2:3], v[44:45], v[84:85]
	v_pk_fma_f32 v[0:1], v[0:1], v[42:43], v[82:83]
	ds_read_b128 v[74:77], v89 offset:42176
	ds_read_b32 v80, v101 offset:42944
	s_waitcnt lgkmcnt(6)
	v_pk_mul_f32 v[86:87], v[2:3], v[16:17]
	v_pk_mul_f32 v[4:5], v[2:3], v[60:61]
	v_pk_fma_f32 v[86:87], v[0:1], v[14:15], v[86:87]
	v_pk_fma_f32 v[4:5], v[0:1], v[58:59], v[4:5]
	v_pk_mul_f32 v[84:85], v[72:73], v[78:79] op_sel_hi:[1,0]
	v_add_f32_e32 v94, v86, v87
	v_add_f32_e32 v95, v4, v5
	v_pk_mul_f32 v[82:83], v[70:71], v[78:79] op_sel_hi:[1,0]
	s_nop 0
	v_add_f32_dpp v94, v94, v94 quad_perm:[1,0,3,2] row_mask:0xf bank_mask:0xf bound_ctrl:1
	v_add_f32_dpp v95, v95, v95 quad_perm:[1,0,3,2] row_mask:0xf bank_mask:0xf bound_ctrl:1
	s_nop 0
	v_add_f32_dpp v94, v94, v94 quad_perm:[2,3,0,1] row_mask:0xf bank_mask:0xf bound_ctrl:1
	v_add_f32_dpp v95, v95, v95 quad_perm:[2,3,0,1] row_mask:0xf bank_mask:0xf bound_ctrl:1
	s_nop 0
	v_add_f32_dpp v94, v94, v94 row_half_mirror row_mask:0xf bank_mask:0xf bound_ctrl:1
	v_add_f32_dpp v95, v95, v95 row_half_mirror row_mask:0xf bank_mask:0xf bound_ctrl:1
	s_nop 0
	v_add_f32_dpp v94, v94, v94 row_mirror row_mask:0xf bank_mask:0xf bound_ctrl:1
	v_add_f32_dpp v95, v95, v95 row_mirror row_mask:0xf bank_mask:0xf bound_ctrl:1
	v_pk_fma_f32 v[84:85], v[32:33], v[94:95], v[84:85] op_sel_hi:[1,0,1] neg_lo:[0,1,0] neg_hi:[0,1,0]
	v_pk_fma_f32 v[82:83], v[30:31], v[94:95], v[82:83] op_sel_hi:[1,0,1] neg_lo:[0,1,0] neg_hi:[0,1,0]
	v_cndmask_b32_e64 v96, v96, v95, s[44:45]
	v_pk_fma_f32 v[2:3], v[2:3], v[48:49], v[84:85]
	v_pk_fma_f32 v[0:1], v[0:1], v[46:47], v[82:83]
	s_waitcnt lgkmcnt(0)
	s_barrier
; template <int CH>
; __device__ __forceinline__ void scan_unit(const Args& a, int l, int unit, unsigned char* lds) {
;     ...
;             if (ch + 1 < nch) { SC_SCAN(1, ch + 1); __syncthreads(); }
	ds_read_b128 v[54:57], v98
	ds_read_b128 v[6:9], v98 offset:768
	ds_read_b128 v[22:25], v98 offset:1024
	ds_read_b128 v[38:41], v98 offset:256
	ds_read_b128 v[70:73], v98 offset:512
	ds_read_b32 v78, v100 offset:1280
	s_waitcnt lgkmcnt(6)
	v_pk_mul_f32 v[86:87], v[2:3], v[20:21]
	v_pk_mul_f32 v[4:5], v[2:3], v[64:65]
	v_pk_fma_f32 v[86:87], v[0:1], v[18:19], v[86:87]
	v_pk_fma_f32 v[4:5], v[0:1], v[62:63], v[4:5]
	v_pk_mul_f32 v[84:85], v[76:77], v[80:81] op_sel_hi:[1,0]
	v_add_f32_e32 v94, v86, v87
	v_add_f32_e32 v95, v4, v5
	v_pk_mul_f32 v[82:83], v[74:75], v[80:81] op_sel_hi:[1,0]
	ds_read_b128 v[58:61], v98 offset:1344
	v_add_f32_dpp v94, v94, v94 quad_perm:[1,0,3,2] row_mask:0xf bank_mask:0xf bound_ctrl:1
	v_add_f32_dpp v95, v95, v95 quad_perm:[1,0,3,2] row_mask:0xf bank_mask:0xf bound_ctrl:1
	ds_read_b128 v[10:13], v98 offset:2112
	v_add_f32_dpp v94, v94, v94 quad_perm:[2,3,0,1] row_mask:0xf bank_mask:0xf bound_ctrl:1
	v_add_f32_dpp v95, v95, v95 quad_perm:[2,3,0,1] row_mask:0xf bank_mask:0xf bound_ctrl:1
	ds_read_b128 v[26:29], v98 offset:2368
	v_add_f32_dpp v94, v94, v94 row_half_mirror row_mask:0xf bank_mask:0xf bound_ctrl:1
	v_add_f32_dpp v95, v95, v95 row_half_mirror row_mask:0xf bank_mask:0xf bound_ctrl:1
	ds_read_b128 v[42:45], v98 offset:1600
	v_add_f32_dpp v94, v94, v94 row_mirror row_mask:0xf bank_mask:0xf bound_ctrl:1
	v_add_f32_dpp v95, v95, v95 row_mirror row_mask:0xf bank_mask:0xf bound_ctrl:1
	v_pk_fma_f32 v[84:85], v[36:37], v[94:95], v[84:85] op_sel_hi:[1,0,1] neg_lo:[0,1,0] neg_hi:[0,1,0]
	v_pk_fma_f32 v[82:83], v[34:35], v[94:95], v[82:83] op_sel_hi:[1,0,1] neg_lo:[0,1,0] neg_hi:[0,1,0]
	v_cndmask_b32_e64 v96, v96, v95, s[14:15]
	v_pk_fma_f32 v[2:3], v[2:3], v[52:53], v[84:85]
	v_pk_fma_f32 v[0:1], v[0:1], v[50:51], v[82:83]
	ds_read_b128 v[74:77], v98 offset:1856
	ds_read_b32 v80, v100 offset:2624
	s_waitcnt lgkmcnt(6)
	v_pk_mul_f32 v[86:87], v[2:3], v[8:9]
	v_pk_mul_f32 v[4:5], v[2:3], v[68:69]
	v_pk_fma_f32 v[86:87], v[0:1], v[6:7], v[86:87]
	v_pk_fma_f32 v[4:5], v[0:1], v[66:67], v[4:5]
	v_pk_mul_f32 v[84:85], v[72:73], v[78:79] op_sel_hi:[1,0]
	v_add_f32_e32 v94, v86, v87
	v_add_f32_e32 v95, v4, v5
	v_pk_mul_f32 v[82:83], v[70:71], v[78:79] op_sel_hi:[1,0]
	ds_read_b128 v[62:65], v98 offset:2688
	v_add_f32_dpp v94, v94, v94 quad_perm:[1,0,3,2] row_mask:0xf bank_mask:0xf bound_ctrl:1
	v_add_f32_dpp v95, v95, v95 quad_perm:[1,0,3,2] row_mask:0xf bank_mask:0xf bound_ctrl:1
	ds_read_b128 v[14:17], v98 offset:3456
	v_add_f32_dpp v94, v94, v94 quad_perm:[2,3,0,1] row_mask:0xf bank_mask:0xf bound_ctrl:1
	v_add_f32_dpp v95, v95, v95 quad_perm:[2,3,0,1] row_mask:0xf bank_mask:0xf bound_ctrl:1
	ds_read_b128 v[30:33], v98 offset:3712
	v_add_f32_dpp v94, v94, v94 row_half_mirror row_mask:0xf bank_mask:0xf bound_ctrl:1
	v_add_f32_dpp v95, v95, v95 row_half_mirror row_mask:0xf bank_mask:0xf bound_ctrl:1
	ds_read_b128 v[46:49], v98 offset:2944
	v_add_f32_dpp v94, v94, v94 row_mirror row_mask:0xf bank_mask:0xf bound_ctrl:1
	v_add_f32_dpp v95, v95, v95 row_mirror row_mask:0xf bank_mask:0xf bound_ctrl:1
	v_pk_fma_f32 v[84:85], v[24:25], v[94:95], v[84:85] op_sel_hi:[1,0,1] neg_lo:[0,1,0] neg_hi:[0,1,0]
	v_pk_fma_f32 v[82:83], v[22:23], v[94:95], v[82:83] op_sel_hi:[1,0,1] neg_lo:[0,1,0] neg_hi:[0,1,0]
	v_cndmask_b32_e64 v96, v96, v95, s[12:13]
	v_pk_fma_f32 v[2:3], v[2:3], v[40:41], v[84:85]
	v_pk_fma_f32 v[0:1], v[0:1], v[38:39], v[82:83]
	ds_read_b128 v[70:73], v98 offset:3200
	ds_read_b32 v78, v100 offset:3968
	global_store_dword v[90:91], v96, off
	v_lshl_add_u64 v[90:91], v[90:91], 0, s[6:7]
	s_waitcnt lgkmcnt(6)
	v_pk_mul_f32 v[86:87], v[2:3], v[12:13]
	v_pk_mul_f32 v[4:5], v[2:3], v[56:57]
	v_pk_fma_f32 v[86:87], v[0:1], v[10:11], v[86:87]
	v_pk_fma_f32 v[4:5], v[0:1], v[54:55], v[4:5]
	v_pk_mul_f32 v[84:85], v[76:77], v[80:81] op_sel_hi:[1,0]
	v_add_f32_e32 v94, v86, v87
	v_add_f32_e32 v95, v4, v5
	v_pk_mul_f32 v[82:83], v[74:75], v[80:81] op_sel_hi:[1,0]
	ds_read_b128 v[66:69], v98 offset:4032
	v_add_f32_dpp v94, v94, v94 quad_perm:[1,0,3,2] row_mask:0xf bank_mask:0xf bound_ctrl:1
	v_add_f32_dpp v95, v95, v95 quad_perm:[1,0,3,2] row_mask:0xf bank_mask:0xf bound_ctrl:1
	ds_read_b128 v[18:21], v98 offset:4800
	v_add_f32_dpp v94, v94, v94 quad_perm:[2,3,0,1] row_mask:0xf bank_mask:0xf bound_ctrl:1
	v_add_f32_dpp v95, v95, v95 quad_perm:[2,3,0,1] row_mask:0xf bank_mask:0xf bound_ctrl:1
	ds_read_b128 v[34:37], v98 offset:5056
	v_add_f32_dpp v94, v94, v94 row_half_mirror row_mask:0xf bank_mask:0xf bound_ctrl:1
	v_add_f32_dpp v95, v95, v95 row_half_mirror row_mask:0xf bank_mask:0xf bound_ctrl:1
	ds_read_b128 v[50:53], v98 offset:4288
	v_add_f32_dpp v94, v94, v94 row_mirror row_mask:0xf bank_mask:0xf bound_ctrl:1
	v_add_f32_dpp v95, v95, v95 row_mirror row_mask:0xf bank_mask:0xf bound_ctrl:1
	v_pk_fma_f32 v[84:85], v[28:29], v[94:95], v[84:85] op_sel_hi:[1,0,1] neg_lo:[0,1,0] neg_hi:[0,1,0]
	v_pk_fma_f32 v[82:83], v[26:27], v[94:95], v[82:83] op_sel_hi:[1,0,1] neg_lo:[0,1,0] neg_hi:[0,1,0]
	v_cndmask_b32_e64 v96, 0, v95, s[16:17]
	v_pk_fma_f32 v[2:3], v[2:3], v[44:45], v[84:85]
	v_pk_fma_f32 v[0:1], v[0:1], v[42:43], v[82:83]
	ds_read_b128 v[74:77], v98 offset:4544
	ds_read_b32 v80, v100 offset:5312
	s_waitcnt lgkmcnt(6)
	v_pk_mul_f32 v[86:87], v[2:3], v[16:17]
	v_pk_mul_f32 v[4:5], v[2:3], v[60:61]
	v_pk_fma_f32 v[86:87], v[0:1], v[14:15], v[86:87]
	v_pk_fma_f32 v[4:5], v[0:1], v[58:59], v[4:5]
	v_pk_mul_f32 v[84:85], v[72:73], v[78:79] op_sel_hi:[1,0]
	v_add_f32_e32 v94, v86, v87
	v_add_f32_e32 v95, v4, v5
	v_pk_mul_f32 v[82:83], v[70:71], v[78:79] op_sel_hi:[1,0]
	ds_read_b128 v[54:57], v98 offset:5376
	v_add_f32_dpp v94, v94, v94 quad_perm:[1,0,3,2] row_mask:0xf bank_mask:0xf bound_ctrl:1
	v_add_f32_dpp v95, v95, v95 quad_perm:[1,0,3,2] row_mask:0xf bank_mask:0xf bound_ctrl:1
	ds_read_b128 v[6:9], v98 offset:6144
	v_add_f32_dpp v94, v94, v94 quad_perm:[2,3,0,1] row_mask:0xf bank_mask:0xf bound_ctrl:1
	v_add_f32_dpp v95, v95, v95 quad_perm:[2,3,0,1] row_mask:0xf bank_mask:0xf bound_ctrl:1
	ds_read_b128 v[22:25], v98 offset:6400
	v_add_f32_dpp v94, v94, v94 row_half_mirror row_mask:0xf bank_mask:0xf bound_ctrl:1
	v_add_f32_dpp v95, v95, v95 row_half_mirror row_mask:0xf bank_mask:0xf bound_ctrl:1
	ds_read_b128 v[38:41], v98 offset:5632
	v_add_f32_dpp v94, v94, v94 row_mirror row_mask:0xf bank_mask:0xf bound_ctrl:1
	v_add_f32_dpp v95, v95, v95 row_mirror row_mask:0xf bank_mask:0xf bound_ctrl:1
	v_pk_fma_f32 v[84:85], v[32:33], v[94:95], v[84:85] op_sel_hi:[1,0,1] neg_lo:[0,1,0] neg_hi:[0,1,0]
	v_pk_fma_f32 v[82:83], v[30:31], v[94:95], v[82:83] op_sel_hi:[1,0,1] neg_lo:[0,1,0] neg_hi:[0,1,0]
	v_cndmask_b32_e64 v96, v96, v95, s[18:19]
	v_pk_fma_f32 v[2:3], v[2:3], v[48:49], v[84:85]
	v_pk_fma_f32 v[0:1], v[0:1], v[46:47], v[82:83]
	ds_read_b128 v[70:73], v98 offset:5888
	ds_read_b32 v78, v100 offset:6656
	s_waitcnt lgkmcnt(6)
	v_pk_mul_f32 v[86:87], v[2:3], v[20:21]
	v_pk_mul_f32 v[4:5], v[2:3], v[64:65]
	v_pk_fma_f32 v[86:87], v[0:1], v[18:19], v[86:87]
	v_pk_fma_f32 v[4:5], v[0:1], v[62:63], v[4:5]
	v_pk_mul_f32 v[84:85], v[76:77], v[80:81] op_sel_hi:[1,0]
	v_add_f32_e32 v94, v86, v87
	v_add_f32_e32 v95, v4, v5
	v_pk_mul_f32 v[82:83], v[74:75], v[80:81] op_sel_hi:[1,0]
	ds_read_b128 v[58:61], v98 offset:6720
	v_add_f32_dpp v94, v94, v94 quad_perm:[1,0,3,2] row_mask:0xf bank_mask:0xf bound_ctrl:1
	v_add_f32_dpp v95, v95, v95 quad_perm:[1,0,3,2] row_mask:0xf bank_mask:0xf bound_ctrl:1
	ds_read_b128 v[10:13], v98 offset:7488
	v_add_f32_dpp v94, v94, v94 quad_perm:[2,3,0,1] row_mask:0xf bank_mask:0xf bound_ctrl:1
	v_add_f32_dpp v95, v95, v95 quad_perm:[2,3,0,1] row_mask:0xf bank_mask:0xf bound_ctrl:1
	ds_read_b128 v[26:29], v98 offset:7744
	v_add_f32_dpp v94, v94, v94 row_half_mirror row_mask:0xf bank_mask:0xf bound_ctrl:1
	v_add_f32_dpp v95, v95, v95 row_half_mirror row_mask:0xf bank_mask:0xf bound_ctrl:1
	ds_read_b128 v[42:45], v98 offset:6976
	v_add_f32_dpp v94, v94, v94 row_mirror row_mask:0xf bank_mask:0xf bound_ctrl:1
	v_add_f32_dpp v95, v95, v95 row_mirror row_mask:0xf bank_mask:0xf bound_ctrl:1
	v_pk_fma_f32 v[84:85], v[36:37], v[94:95], v[84:85] op_sel_hi:[1,0,1] neg_lo:[0,1,0] neg_hi:[0,1,0]
	v_pk_fma_f32 v[82:83], v[34:35], v[94:95], v[82:83] op_sel_hi:[1,0,1] neg_lo:[0,1,0] neg_hi:[0,1,0]
	v_cndmask_b32_e64 v96, v96, v95, s[20:21]
	v_pk_fma_f32 v[2:3], v[2:3], v[52:53], v[84:85]
	v_pk_fma_f32 v[0:1], v[0:1], v[50:51], v[82:83]
	ds_read_b128 v[74:77], v98 offset:7232
	ds_read_b32 v80, v100 offset:8000
	s_waitcnt lgkmcnt(6)
	v_pk_mul_f32 v[86:87], v[2:3], v[8:9]
	v_pk_mul_f32 v[4:5], v[2:3], v[68:69]
	v_pk_fma_f32 v[86:87], v[0:1], v[6:7], v[86:87]
	v_pk_fma_f32 v[4:5], v[0:1], v[66:67], v[4:5]
	v_pk_mul_f32 v[84:85], v[72:73], v[78:79] op_sel_hi:[1,0]
	v_add_f32_e32 v94, v86, v87
	v_add_f32_e32 v95, v4, v5
	v_pk_mul_f32 v[82:83], v[70:71], v[78:79] op_sel_hi:[1,0]
	ds_read_b128 v[62:65], v98 offset:8064
	v_add_f32_dpp v94, v94, v94 quad_perm:[1,0,3,2] row_mask:0xf bank_mask:0xf bound_ctrl:1
	v_add_f32_dpp v95, v95, v95 quad_perm:[1,0,3,2] row_mask:0xf bank_mask:0xf bound_ctrl:1
	ds_read_b128 v[14:17], v98 offset:8832
	v_add_f32_dpp v94, v94, v94 quad_perm:[2,3,0,1] row_mask:0xf bank_mask:0xf bound_ctrl:1
	v_add_f32_dpp v95, v95, v95 quad_perm:[2,3,0,1] row_mask:0xf bank_mask:0xf bound_ctrl:1
	ds_read_b128 v[30:33], v98 offset:9088
	v_add_f32_dpp v94, v94, v94 row_half_mirror row_mask:0xf bank_mask:0xf bound_ctrl:1
	v_add_f32_dpp v95, v95, v95 row_half_mirror row_mask:0xf bank_mask:0xf bound_ctrl:1
	ds_read_b128 v[46:49], v98 offset:8320
	v_add_f32_dpp v94, v94, v94 row_mirror row_mask:0xf bank_mask:0xf bound_ctrl:1
	v_add_f32_dpp v95, v95, v95 row_mirror row_mask:0xf bank_mask:0xf bound_ctrl:1
	v_pk_fma_f32 v[84:85], v[24:25], v[94:95], v[84:85] op_sel_hi:[1,0,1] neg_lo:[0,1,0] neg_hi:[0,1,0]
	v_pk_fma_f32 v[82:83], v[22:23], v[94:95], v[82:83] op_sel_hi:[1,0,1] neg_lo:[0,1,0] neg_hi:[0,1,0]
	v_cndmask_b32_e64 v96, v96, v95, s[22:23]
	v_pk_fma_f32 v[2:3], v[2:3], v[40:41], v[84:85]
	v_pk_fma_f32 v[0:1], v[0:1], v[38:39], v[82:83]
	ds_read_b128 v[70:73], v98 offset:8576
	ds_read_b32 v78, v100 offset:9344
	s_waitcnt lgkmcnt(6)
	v_pk_mul_f32 v[86:87], v[2:3], v[12:13]
	v_pk_mul_f32 v[4:5], v[2:3], v[56:57]
	v_pk_fma_f32 v[86:87], v[0:1], v[10:11], v[86:87]
	v_pk_fma_f32 v[4:5], v[0:1], v[54:55], v[4:5]
	v_pk_mul_f32 v[84:85], v[76:77], v[80:81] op_sel_hi:[1,0]
	v_add_f32_e32 v94, v86, v87
	v_add_f32_e32 v95, v4, v5
	v_pk_mul_f32 v[82:83], v[74:75], v[80:81] op_sel_hi:[1,0]
	ds_read_b128 v[66:69], v98 offset:9408
	v_add_f32_dpp v94, v94, v94 quad_perm:[1,0,3,2] row_mask:0xf bank_mask:0xf bound_ctrl:1
	v_add_f32_dpp v95, v95, v95 quad_perm:[1,0,3,2] row_mask:0xf bank_mask:0xf bound_ctrl:1
	ds_read_b128 v[18:21], v98 offset:10176
	v_add_f32_dpp v94, v94, v94 quad_perm:[2,3,0,1] row_mask:0xf bank_mask:0xf bound_ctrl:1
	v_add_f32_dpp v95, v95, v95 quad_perm:[2,3,0,1] row_mask:0xf bank_mask:0xf bound_ctrl:1
	ds_read_b128 v[34:37], v98 offset:10432
	v_add_f32_dpp v94, v94, v94 row_half_mirror row_mask:0xf bank_mask:0xf bound_ctrl:1
	v_add_f32_dpp v95, v95, v95 row_half_mirror row_mask:0xf bank_mask:0xf bound_ctrl:1
	ds_read_b128 v[50:53], v98 offset:9664
	v_add_f32_dpp v94, v94, v94 row_mirror row_mask:0xf bank_mask:0xf bound_ctrl:1
	v_add_f32_dpp v95, v95, v95 row_mirror row_mask:0xf bank_mask:0xf bound_ctrl:1
	v_pk_fma_f32 v[84:85], v[28:29], v[94:95], v[84:85] op_sel_hi:[1,0,1] neg_lo:[0,1,0] neg_hi:[0,1,0]
	v_pk_fma_f32 v[82:83], v[26:27], v[94:95], v[82:83] op_sel_hi:[1,0,1] neg_lo:[0,1,0] neg_hi:[0,1,0]
	v_cndmask_b32_e64 v96, v96, v95, s[24:25]
	v_pk_fma_f32 v[2:3], v[2:3], v[44:45], v[84:85]
	v_pk_fma_f32 v[0:1], v[0:1], v[42:43], v[82:83]
	ds_read_b128 v[74:77], v98 offset:9920
	ds_read_b32 v80, v100 offset:10688
	s_waitcnt lgkmcnt(6)
	v_pk_mul_f32 v[86:87], v[2:3], v[16:17]
	v_pk_mul_f32 v[4:5], v[2:3], v[60:61]
	v_pk_fma_f32 v[86:87], v[0:1], v[14:15], v[86:87]
	v_pk_fma_f32 v[4:5], v[0:1], v[58:59], v[4:5]
	v_pk_mul_f32 v[84:85], v[72:73], v[78:79] op_sel_hi:[1,0]
	v_add_f32_e32 v94, v86, v87
	v_add_f32_e32 v95, v4, v5
	v_pk_mul_f32 v[82:83], v[70:71], v[78:79] op_sel_hi:[1,0]
	ds_read_b128 v[54:57], v98 offset:10752
	v_add_f32_dpp v94, v94, v94 quad_perm:[1,0,3,2] row_mask:0xf bank_mask:0xf bound_ctrl:1
	v_add_f32_dpp v95, v95, v95 quad_perm:[1,0,3,2] row_mask:0xf bank_mask:0xf bound_ctrl:1
	ds_read_b128 v[6:9], v98 offset:11520
	v_add_f32_dpp v94, v94, v94 quad_perm:[2,3,0,1] row_mask:0xf bank_mask:0xf bound_ctrl:1
	v_add_f32_dpp v95, v95, v95 quad_perm:[2,3,0,1] row_mask:0xf bank_mask:0xf bound_ctrl:1
	ds_read_b128 v[22:25], v98 offset:11776
	v_add_f32_dpp v94, v94, v94 row_half_mirror row_mask:0xf bank_mask:0xf bound_ctrl:1
	v_add_f32_dpp v95, v95, v95 row_half_mirror row_mask:0xf bank_mask:0xf bound_ctrl:1
	ds_read_b128 v[38:41], v98 offset:11008
	v_add_f32_dpp v94, v94, v94 row_mirror row_mask:0xf bank_mask:0xf bound_ctrl:1
	v_add_f32_dpp v95, v95, v95 row_mirror row_mask:0xf bank_mask:0xf bound_ctrl:1
	v_pk_fma_f32 v[84:85], v[32:33], v[94:95], v[84:85] op_sel_hi:[1,0,1] neg_lo:[0,1,0] neg_hi:[0,1,0]
	v_pk_fma_f32 v[82:83], v[30:31], v[94:95], v[82:83] op_sel_hi:[1,0,1] neg_lo:[0,1,0] neg_hi:[0,1,0]
	v_cndmask_b32_e64 v96, v96, v95, s[26:27]
	v_pk_fma_f32 v[2:3], v[2:3], v[48:49], v[84:85]
	v_pk_fma_f32 v[0:1], v[0:1], v[46:47], v[82:83]
	ds_read_b128 v[70:73], v98 offset:11264
	ds_read_b32 v78, v100 offset:12032
	s_waitcnt lgkmcnt(6)
	v_pk_mul_f32 v[86:87], v[2:3], v[20:21]
	v_pk_mul_f32 v[4:5], v[2:3], v[64:65]
	v_pk_fma_f32 v[86:87], v[0:1], v[18:19], v[86:87]
	v_pk_fma_f32 v[4:5], v[0:1], v[62:63], v[4:5]
	v_pk_mul_f32 v[84:85], v[76:77], v[80:81] op_sel_hi:[1,0]
	v_add_f32_e32 v94, v86, v87
	v_add_f32_e32 v95, v4, v5
	v_pk_mul_f32 v[82:83], v[74:75], v[80:81] op_sel_hi:[1,0]
	ds_read_b128 v[58:61], v98 offset:12096
	v_add_f32_dpp v94, v94, v94 quad_perm:[1,0,3,2] row_mask:0xf bank_mask:0xf bound_ctrl:1
	v_add_f32_dpp v95, v95, v95 quad_perm:[1,0,3,2] row_mask:0xf bank_mask:0xf bound_ctrl:1
	ds_read_b128 v[10:13], v98 offset:12864
	v_add_f32_dpp v94, v94, v94 quad_perm:[2,3,0,1] row_mask:0xf bank_mask:0xf bound_ctrl:1
	v_add_f32_dpp v95, v95, v95 quad_perm:[2,3,0,1] row_mask:0xf bank_mask:0xf bound_ctrl:1
	ds_read_b128 v[26:29], v98 offset:13120
	v_add_f32_dpp v94, v94, v94 row_half_mirror row_mask:0xf bank_mask:0xf bound_ctrl:1
	v_add_f32_dpp v95, v95, v95 row_half_mirror row_mask:0xf bank_mask:0xf bound_ctrl:1
	ds_read_b128 v[42:45], v98 offset:12352
	v_add_f32_dpp v94, v94, v94 row_mirror row_mask:0xf bank_mask:0xf bound_ctrl:1
	v_add_f32_dpp v95, v95, v95 row_mirror row_mask:0xf bank_mask:0xf bound_ctrl:1
	v_pk_fma_f32 v[84:85], v[36:37], v[94:95], v[84:85] op_sel_hi:[1,0,1] neg_lo:[0,1,0] neg_hi:[0,1,0]
	v_pk_fma_f32 v[82:83], v[34:35], v[94:95], v[82:83] op_sel_hi:[1,0,1] neg_lo:[0,1,0] neg_hi:[0,1,0]
	v_cndmask_b32_e64 v96, v96, v95, s[28:29]
	v_pk_fma_f32 v[2:3], v[2:3], v[52:53], v[84:85]
	v_pk_fma_f32 v[0:1], v[0:1], v[50:51], v[82:83]
	ds_read_b128 v[74:77], v98 offset:12608
	ds_read_b32 v80, v100 offset:13376
	s_waitcnt lgkmcnt(6)
	v_pk_mul_f32 v[86:87], v[2:3], v[8:9]
	v_pk_mul_f32 v[4:5], v[2:3], v[68:69]
	v_pk_fma_f32 v[86:87], v[0:1], v[6:7], v[86:87]
	v_pk_fma_f32 v[4:5], v[0:1], v[66:67], v[4:5]
	v_pk_mul_f32 v[84:85], v[72:73], v[78:79] op_sel_hi:[1,0]
	v_add_f32_e32 v94, v86, v87
	v_add_f32_e32 v95, v4, v5
	v_pk_mul_f32 v[82:83], v[70:71], v[78:79] op_sel_hi:[1,0]
	ds_read_b128 v[62:65], v98 offset:13440
	v_add_f32_dpp v94, v94, v94 quad_perm:[1,0,3,2] row_mask:0xf bank_mask:0xf bound_ctrl:1
	v_add_f32_dpp v95, v95, v95 quad_perm:[1,0,3,2] row_mask:0xf bank_mask:0xf bound_ctrl:1
	ds_read_b128 v[14:17], v98 offset:14208
	v_add_f32_dpp v94, v94, v94 quad_perm:[2,3,0,1] row_mask:0xf bank_mask:0xf bound_ctrl:1
	v_add_f32_dpp v95, v95, v95 quad_perm:[2,3,0,1] row_mask:0xf bank_mask:0xf bound_ctrl:1
	ds_read_b128 v[30:33], v98 offset:14464
	v_add_f32_dpp v94, v94, v94 row_half_mirror row_mask:0xf bank_mask:0xf bound_ctrl:1
	v_add_f32_dpp v95, v95, v95 row_half_mirror row_mask:0xf bank_mask:0xf bound_ctrl:1
	ds_read_b128 v[46:49], v98 offset:13696
	v_add_f32_dpp v94, v94, v94 row_mirror row_mask:0xf bank_mask:0xf bound_ctrl:1
	v_add_f32_dpp v95, v95, v95 row_mirror row_mask:0xf bank_mask:0xf bound_ctrl:1
	v_pk_fma_f32 v[84:85], v[24:25], v[94:95], v[84:85] op_sel_hi:[1,0,1] neg_lo:[0,1,0] neg_hi:[0,1,0]
	v_pk_fma_f32 v[82:83], v[22:23], v[94:95], v[82:83] op_sel_hi:[1,0,1] neg_lo:[0,1,0] neg_hi:[0,1,0]
	v_cndmask_b32_e64 v96, v96, v95, s[30:31]
	v_pk_fma_f32 v[2:3], v[2:3], v[40:41], v[84:85]
	v_pk_fma_f32 v[0:1], v[0:1], v[38:39], v[82:83]
	ds_read_b128 v[70:73], v98 offset:13952
	ds_read_b32 v78, v100 offset:14720
	s_waitcnt lgkmcnt(6)
	v_pk_mul_f32 v[86:87], v[2:3], v[12:13]
	v_pk_mul_f32 v[4:5], v[2:3], v[56:57]
	v_pk_fma_f32 v[86:87], v[0:1], v[10:11], v[86:87]
	v_pk_fma_f32 v[4:5], v[0:1], v[54:55], v[4:5]
	v_pk_mul_f32 v[84:85], v[76:77], v[80:81] op_sel_hi:[1,0]
	v_add_f32_e32 v94, v86, v87
	v_add_f32_e32 v95, v4, v5
	v_pk_mul_f32 v[82:83], v[74:75], v[80:81] op_sel_hi:[1,0]
	ds_read_b128 v[66:69], v98 offset:14784
	v_add_f32_dpp v94, v94, v94 quad_perm:[1,0,3,2] row_mask:0xf bank_mask:0xf bound_ctrl:1
	v_add_f32_dpp v95, v95, v95 quad_perm:[1,0,3,2] row_mask:0xf bank_mask:0xf bound_ctrl:1
	ds_read_b128 v[18:21], v98 offset:15552
	v_add_f32_dpp v94, v94, v94 quad_perm:[2,3,0,1] row_mask:0xf bank_mask:0xf bound_ctrl:1
	v_add_f32_dpp v95, v95, v95 quad_perm:[2,3,0,1] row_mask:0xf bank_mask:0xf bound_ctrl:1
	ds_read_b128 v[34:37], v98 offset:15808
	v_add_f32_dpp v94, v94, v94 row_half_mirror row_mask:0xf bank_mask:0xf bound_ctrl:1
	v_add_f32_dpp v95, v95, v95 row_half_mirror row_mask:0xf bank_mask:0xf bound_ctrl:1
	ds_read_b128 v[50:53], v98 offset:15040
	v_add_f32_dpp v94, v94, v94 row_mirror row_mask:0xf bank_mask:0xf bound_ctrl:1
	v_add_f32_dpp v95, v95, v95 row_mirror row_mask:0xf bank_mask:0xf bound_ctrl:1
	v_pk_fma_f32 v[84:85], v[28:29], v[94:95], v[84:85] op_sel_hi:[1,0,1] neg_lo:[0,1,0] neg_hi:[0,1,0]
	v_pk_fma_f32 v[82:83], v[26:27], v[94:95], v[82:83] op_sel_hi:[1,0,1] neg_lo:[0,1,0] neg_hi:[0,1,0]
	v_cndmask_b32_e64 v96, v96, v95, s[34:35]
	v_pk_fma_f32 v[2:3], v[2:3], v[44:45], v[84:85]
	v_pk_fma_f32 v[0:1], v[0:1], v[42:43], v[82:83]
	ds_read_b128 v[74:77], v98 offset:15296
	ds_read_b32 v80, v100 offset:16064
	s_waitcnt lgkmcnt(6)
	v_pk_mul_f32 v[86:87], v[2:3], v[16:17]
	v_pk_mul_f32 v[4:5], v[2:3], v[60:61]
	v_pk_fma_f32 v[86:87], v[0:1], v[14:15], v[86:87]
	v_pk_fma_f32 v[4:5], v[0:1], v[58:59], v[4:5]
	v_pk_mul_f32 v[84:85], v[72:73], v[78:79] op_sel_hi:[1,0]
	v_add_f32_e32 v94, v86, v87
	v_add_f32_e32 v95, v4, v5
	v_pk_mul_f32 v[82:83], v[70:71], v[78:79] op_sel_hi:[1,0]
	ds_read_b128 v[54:57], v98 offset:16128
	v_add_f32_dpp v94, v94, v94 quad_perm:[1,0,3,2] row_mask:0xf bank_mask:0xf bound_ctrl:1
	v_add_f32_dpp v95, v95, v95 quad_perm:[1,0,3,2] row_mask:0xf bank_mask:0xf bound_ctrl:1
	ds_read_b128 v[6:9], v98 offset:16896
	v_add_f32_dpp v94, v94, v94 quad_perm:[2,3,0,1] row_mask:0xf bank_mask:0xf bound_ctrl:1
	v_add_f32_dpp v95, v95, v95 quad_perm:[2,3,0,1] row_mask:0xf bank_mask:0xf bound_ctrl:1
	ds_read_b128 v[22:25], v98 offset:17152
	v_add_f32_dpp v94, v94, v94 row_half_mirror row_mask:0xf bank_mask:0xf bound_ctrl:1
	v_add_f32_dpp v95, v95, v95 row_half_mirror row_mask:0xf bank_mask:0xf bound_ctrl:1
	ds_read_b128 v[38:41], v98 offset:16384
	v_add_f32_dpp v94, v94, v94 row_mirror row_mask:0xf bank_mask:0xf bound_ctrl:1
	v_add_f32_dpp v95, v95, v95 row_mirror row_mask:0xf bank_mask:0xf bound_ctrl:1
	v_pk_fma_f32 v[84:85], v[32:33], v[94:95], v[84:85] op_sel_hi:[1,0,1] neg_lo:[0,1,0] neg_hi:[0,1,0]
	v_pk_fma_f32 v[82:83], v[30:31], v[94:95], v[82:83] op_sel_hi:[1,0,1] neg_lo:[0,1,0] neg_hi:[0,1,0]
	v_cndmask_b32_e64 v96, v96, v95, s[36:37]
	v_pk_fma_f32 v[2:3], v[2:3], v[48:49], v[84:85]
	v_pk_fma_f32 v[0:1], v[0:1], v[46:47], v[82:83]
	ds_read_b128 v[70:73], v98 offset:16640
	ds_read_b32 v78, v100 offset:17408
	s_waitcnt lgkmcnt(6)
	v_pk_mul_f32 v[86:87], v[2:3], v[20:21]
	v_pk_mul_f32 v[4:5], v[2:3], v[64:65]
	v_pk_fma_f32 v[86:87], v[0:1], v[18:19], v[86:87]
	v_pk_fma_f32 v[4:5], v[0:1], v[62:63], v[4:5]
	v_pk_mul_f32 v[84:85], v[76:77], v[80:81] op_sel_hi:[1,0]
	v_add_f32_e32 v94, v86, v87
	v_add_f32_e32 v95, v4, v5
	v_pk_mul_f32 v[82:83], v[74:75], v[80:81] op_sel_hi:[1,0]
	ds_read_b128 v[58:61], v98 offset:17472
	v_add_f32_dpp v94, v94, v94 quad_perm:[1,0,3,2] row_mask:0xf bank_mask:0xf bound_ctrl:1
	v_add_f32_dpp v95, v95, v95 quad_perm:[1,0,3,2] row_mask:0xf bank_mask:0xf bound_ctrl:1
	ds_read_b128 v[10:13], v98 offset:18240
	v_add_f32_dpp v94, v94, v94 quad_perm:[2,3,0,1] row_mask:0xf bank_mask:0xf bound_ctrl:1
	v_add_f32_dpp v95, v95, v95 quad_perm:[2,3,0,1] row_mask:0xf bank_mask:0xf bound_ctrl:1
	ds_read_b128 v[26:29], v98 offset:18496
	v_add_f32_dpp v94, v94, v94 row_half_mirror row_mask:0xf bank_mask:0xf bound_ctrl:1
	v_add_f32_dpp v95, v95, v95 row_half_mirror row_mask:0xf bank_mask:0xf bound_ctrl:1
	ds_read_b128 v[42:45], v98 offset:17728
	v_add_f32_dpp v94, v94, v94 row_mirror row_mask:0xf bank_mask:0xf bound_ctrl:1
	v_add_f32_dpp v95, v95, v95 row_mirror row_mask:0xf bank_mask:0xf bound_ctrl:1
	v_pk_fma_f32 v[84:85], v[36:37], v[94:95], v[84:85] op_sel_hi:[1,0,1] neg_lo:[0,1,0] neg_hi:[0,1,0]
	v_pk_fma_f32 v[82:83], v[34:35], v[94:95], v[82:83] op_sel_hi:[1,0,1] neg_lo:[0,1,0] neg_hi:[0,1,0]
	v_cndmask_b32_e64 v96, v96, v95, s[38:39]
	v_pk_fma_f32 v[2:3], v[2:3], v[52:53], v[84:85]
	v_pk_fma_f32 v[0:1], v[0:1], v[50:51], v[82:83]
	ds_read_b128 v[74:77], v98 offset:17984
	ds_read_b32 v80, v100 offset:18752
	s_waitcnt lgkmcnt(6)
	v_pk_mul_f32 v[86:87], v[2:3], v[8:9]
	v_pk_mul_f32 v[4:5], v[2:3], v[68:69]
	v_pk_fma_f32 v[86:87], v[0:1], v[6:7], v[86:87]
	v_pk_fma_f32 v[4:5], v[0:1], v[66:67], v[4:5]
	v_pk_mul_f32 v[84:85], v[72:73], v[78:79] op_sel_hi:[1,0]
	v_add_f32_e32 v94, v86, v87
	v_add_f32_e32 v95, v4, v5
	v_pk_mul_f32 v[82:83], v[70:71], v[78:79] op_sel_hi:[1,0]
	ds_read_b128 v[62:65], v98 offset:18816
	v_add_f32_dpp v94, v94, v94 quad_perm:[1,0,3,2] row_mask:0xf bank_mask:0xf bound_ctrl:1
	v_add_f32_dpp v95, v95, v95 quad_perm:[1,0,3,2] row_mask:0xf bank_mask:0xf bound_ctrl:1
	ds_read_b128 v[14:17], v98 offset:19584
	v_add_f32_dpp v94, v94, v94 quad_perm:[2,3,0,1] row_mask:0xf bank_mask:0xf bound_ctrl:1
	v_add_f32_dpp v95, v95, v95 quad_perm:[2,3,0,1] row_mask:0xf bank_mask:0xf bound_ctrl:1
	ds_read_b128 v[30:33], v98 offset:19840
	v_add_f32_dpp v94, v94, v94 row_half_mirror row_mask:0xf bank_mask:0xf bound_ctrl:1
	v_add_f32_dpp v95, v95, v95 row_half_mirror row_mask:0xf bank_mask:0xf bound_ctrl:1
	ds_read_b128 v[46:49], v98 offset:19072
	v_add_f32_dpp v94, v94, v94 row_mirror row_mask:0xf bank_mask:0xf bound_ctrl:1
	v_add_f32_dpp v95, v95, v95 row_mirror row_mask:0xf bank_mask:0xf bound_ctrl:1
	v_pk_fma_f32 v[84:85], v[24:25], v[94:95], v[84:85] op_sel_hi:[1,0,1] neg_lo:[0,1,0] neg_hi:[0,1,0]
	v_pk_fma_f32 v[82:83], v[22:23], v[94:95], v[82:83] op_sel_hi:[1,0,1] neg_lo:[0,1,0] neg_hi:[0,1,0]
	v_cndmask_b32_e64 v96, v96, v95, s[40:41]
	v_pk_fma_f32 v[2:3], v[2:3], v[40:41], v[84:85]
	v_pk_fma_f32 v[0:1], v[0:1], v[38:39], v[82:83]
	ds_read_b128 v[70:73], v98 offset:19328
	ds_read_b32 v78, v100 offset:20096
	s_waitcnt lgkmcnt(6)
	v_pk_mul_f32 v[86:87], v[2:3], v[12:13]
	v_pk_mul_f32 v[4:5], v[2:3], v[56:57]
	v_pk_fma_f32 v[86:87], v[0:1], v[10:11], v[86:87]
	v_pk_fma_f32 v[4:5], v[0:1], v[54:55], v[4:5]
	v_pk_mul_f32 v[84:85], v[76:77], v[80:81] op_sel_hi:[1,0]
	v_add_f32_e32 v94, v86, v87
	v_add_f32_e32 v95, v4, v5
	v_pk_mul_f32 v[82:83], v[74:75], v[80:81] op_sel_hi:[1,0]
	ds_read_b128 v[66:69], v98 offset:20160
	v_add_f32_dpp v94, v94, v94 quad_perm:[1,0,3,2] row_mask:0xf bank_mask:0xf bound_ctrl:1
	v_add_f32_dpp v95, v95, v95 quad_perm:[1,0,3,2] row_mask:0xf bank_mask:0xf bound_ctrl:1
	ds_read_b128 v[18:21], v98 offset:20928
	v_add_f32_dpp v94, v94, v94 quad_perm:[2,3,0,1] row_mask:0xf bank_mask:0xf bound_ctrl:1
	v_add_f32_dpp v95, v95, v95 quad_perm:[2,3,0,1] row_mask:0xf bank_mask:0xf bound_ctrl:1
	ds_read_b128 v[34:37], v98 offset:21184
	v_add_f32_dpp v94, v94, v94 row_half_mirror row_mask:0xf bank_mask:0xf bound_ctrl:1
	v_add_f32_dpp v95, v95, v95 row_half_mirror row_mask:0xf bank_mask:0xf bound_ctrl:1
	ds_read_b128 v[50:53], v98 offset:20416
	v_add_f32_dpp v94, v94, v94 row_mirror row_mask:0xf bank_mask:0xf bound_ctrl:1
	v_add_f32_dpp v95, v95, v95 row_mirror row_mask:0xf bank_mask:0xf bound_ctrl:1
	v_pk_fma_f32 v[84:85], v[28:29], v[94:95], v[84:85] op_sel_hi:[1,0,1] neg_lo:[0,1,0] neg_hi:[0,1,0]
	v_pk_fma_f32 v[82:83], v[26:27], v[94:95], v[82:83] op_sel_hi:[1,0,1] neg_lo:[0,1,0] neg_hi:[0,1,0]
	v_cndmask_b32_e64 v96, v96, v95, s[42:43]
	v_pk_fma_f32 v[2:3], v[2:3], v[44:45], v[84:85]
	v_pk_fma_f32 v[0:1], v[0:1], v[42:43], v[82:83]
	ds_read_b128 v[74:77], v98 offset:20672
	ds_read_b32 v80, v100 offset:21440
	s_waitcnt lgkmcnt(6)
	v_pk_mul_f32 v[86:87], v[2:3], v[16:17]
	v_pk_mul_f32 v[4:5], v[2:3], v[60:61]
	v_pk_fma_f32 v[86:87], v[0:1], v[14:15], v[86:87]
	v_pk_fma_f32 v[4:5], v[0:1], v[58:59], v[4:5]
	v_pk_mul_f32 v[84:85], v[72:73], v[78:79] op_sel_hi:[1,0]
	v_add_f32_e32 v94, v86, v87
	v_add_f32_e32 v95, v4, v5
	v_pk_mul_f32 v[82:83], v[70:71], v[78:79] op_sel_hi:[1,0]
	ds_read_b128 v[54:57], v98 offset:21504
	v_add_f32_dpp v94, v94, v94 quad_perm:[1,0,3,2] row_mask:0xf bank_mask:0xf bound_ctrl:1
	v_add_f32_dpp v95, v95, v95 quad_perm:[1,0,3,2] row_mask:0xf bank_mask:0xf bound_ctrl:1
	ds_read_b128 v[6:9], v98 offset:22272
	v_add_f32_dpp v94, v94, v94 quad_perm:[2,3,0,1] row_mask:0xf bank_mask:0xf bound_ctrl:1
	v_add_f32_dpp v95, v95, v95 quad_perm:[2,3,0,1] row_mask:0xf bank_mask:0xf bound_ctrl:1
	ds_read_b128 v[22:25], v98 offset:22528
	v_add_f32_dpp v94, v94, v94 row_half_mirror row_mask:0xf bank_mask:0xf bound_ctrl:1
	v_add_f32_dpp v95, v95, v95 row_half_mirror row_mask:0xf bank_mask:0xf bound_ctrl:1
	ds_read_b128 v[38:41], v98 offset:21760
	v_add_f32_dpp v94, v94, v94 row_mirror row_mask:0xf bank_mask:0xf bound_ctrl:1
	v_add_f32_dpp v95, v95, v95 row_mirror row_mask:0xf bank_mask:0xf bound_ctrl:1
	v_pk_fma_f32 v[84:85], v[32:33], v[94:95], v[84:85] op_sel_hi:[1,0,1] neg_lo:[0,1,0] neg_hi:[0,1,0]
	v_pk_fma_f32 v[82:83], v[30:31], v[94:95], v[82:83] op_sel_hi:[1,0,1] neg_lo:[0,1,0] neg_hi:[0,1,0]
	v_cndmask_b32_e64 v96, v96, v95, s[44:45]
	v_pk_fma_f32 v[2:3], v[2:3], v[48:49], v[84:85]
	v_pk_fma_f32 v[0:1], v[0:1], v[46:47], v[82:83]
	ds_read_b128 v[70:73], v98 offset:22016
	ds_read_b32 v78, v100 offset:22784
	s_waitcnt lgkmcnt(6)
	v_pk_mul_f32 v[86:87], v[2:3], v[20:21]
	v_pk_mul_f32 v[4:5], v[2:3], v[64:65]
	v_pk_fma_f32 v[86:87], v[0:1], v[18:19], v[86:87]
	v_pk_fma_f32 v[4:5], v[0:1], v[62:63], v[4:5]
	v_pk_mul_f32 v[84:85], v[76:77], v[80:81] op_sel_hi:[1,0]
	v_add_f32_e32 v94, v86, v87
	v_add_f32_e32 v95, v4, v5
	v_pk_mul_f32 v[82:83], v[74:75], v[80:81] op_sel_hi:[1,0]
	ds_read_b128 v[58:61], v98 offset:22848
	v_add_f32_dpp v94, v94, v94 quad_perm:[1,0,3,2] row_mask:0xf bank_mask:0xf bound_ctrl:1
	v_add_f32_dpp v95, v95, v95 quad_perm:[1,0,3,2] row_mask:0xf bank_mask:0xf bound_ctrl:1
	ds_read_b128 v[10:13], v98 offset:23616
	v_add_f32_dpp v94, v94, v94 quad_perm:[2,3,0,1] row_mask:0xf bank_mask:0xf bound_ctrl:1
	v_add_f32_dpp v95, v95, v95 quad_perm:[2,3,0,1] row_mask:0xf bank_mask:0xf bound_ctrl:1
	ds_read_b128 v[26:29], v98 offset:23872
	v_add_f32_dpp v94, v94, v94 row_half_mirror row_mask:0xf bank_mask:0xf bound_ctrl:1
	v_add_f32_dpp v95, v95, v95 row_half_mirror row_mask:0xf bank_mask:0xf bound_ctrl:1
	ds_read_b128 v[42:45], v98 offset:23104
	v_add_f32_dpp v94, v94, v94 row_mirror row_mask:0xf bank_mask:0xf bound_ctrl:1
	v_add_f32_dpp v95, v95, v95 row_mirror row_mask:0xf bank_mask:0xf bound_ctrl:1
	v_pk_fma_f32 v[84:85], v[36:37], v[94:95], v[84:85] op_sel_hi:[1,0,1] neg_lo:[0,1,0] neg_hi:[0,1,0]
	v_pk_fma_f32 v[82:83], v[34:35], v[94:95], v[82:83] op_sel_hi:[1,0,1] neg_lo:[0,1,0] neg_hi:[0,1,0]
	v_cndmask_b32_e64 v96, v96, v95, s[14:15]
	v_pk_fma_f32 v[2:3], v[2:3], v[52:53], v[84:85]
	v_pk_fma_f32 v[0:1], v[0:1], v[50:51], v[82:83]
	ds_read_b128 v[74:77], v98 offset:23360
	ds_read_b32 v80, v100 offset:24128
	s_waitcnt lgkmcnt(6)
	v_pk_mul_f32 v[86:87], v[2:3], v[8:9]
	v_pk_mul_f32 v[4:5], v[2:3], v[68:69]
	v_pk_fma_f32 v[86:87], v[0:1], v[6:7], v[86:87]
	v_pk_fma_f32 v[4:5], v[0:1], v[66:67], v[4:5]
	v_pk_mul_f32 v[84:85], v[72:73], v[78:79] op_sel_hi:[1,0]
	v_add_f32_e32 v94, v86, v87
	v_add_f32_e32 v95, v4, v5
	v_pk_mul_f32 v[82:83], v[70:71], v[78:79] op_sel_hi:[1,0]
	ds_read_b128 v[62:65], v98 offset:24192
	v_add_f32_dpp v94, v94, v94 quad_perm:[1,0,3,2] row_mask:0xf bank_mask:0xf bound_ctrl:1
	v_add_f32_dpp v95, v95, v95 quad_perm:[1,0,3,2] row_mask:0xf bank_mask:0xf bound_ctrl:1
	ds_read_b128 v[14:17], v98 offset:24960
	v_add_f32_dpp v94, v94, v94 quad_perm:[2,3,0,1] row_mask:0xf bank_mask:0xf bound_ctrl:1
	v_add_f32_dpp v95, v95, v95 quad_perm:[2,3,0,1] row_mask:0xf bank_mask:0xf bound_ctrl:1
	ds_read_b128 v[30:33], v98 offset:25216
	v_add_f32_dpp v94, v94, v94 row_half_mirror row_mask:0xf bank_mask:0xf bound_ctrl:1
	v_add_f32_dpp v95, v95, v95 row_half_mirror row_mask:0xf bank_mask:0xf bound_ctrl:1
	ds_read_b128 v[46:49], v98 offset:24448
	v_add_f32_dpp v94, v94, v94 row_mirror row_mask:0xf bank_mask:0xf bound_ctrl:1
	v_add_f32_dpp v95, v95, v95 row_mirror row_mask:0xf bank_mask:0xf bound_ctrl:1
	v_pk_fma_f32 v[84:85], v[24:25], v[94:95], v[84:85] op_sel_hi:[1,0,1] neg_lo:[0,1,0] neg_hi:[0,1,0]
	v_pk_fma_f32 v[82:83], v[22:23], v[94:95], v[82:83] op_sel_hi:[1,0,1] neg_lo:[0,1,0] neg_hi:[0,1,0]
	v_cndmask_b32_e64 v96, v96, v95, s[12:13]
	v_pk_fma_f32 v[2:3], v[2:3], v[40:41], v[84:85]
	v_pk_fma_f32 v[0:1], v[0:1], v[38:39], v[82:83]
	ds_read_b128 v[70:73], v98 offset:24704
	ds_read_b32 v78, v100 offset:25472
	global_store_dword v[90:91], v96, off
	v_lshl_add_u64 v[90:91], v[90:91], 0, s[6:7]
	s_waitcnt lgkmcnt(6)
	v_pk_mul_f32 v[86:87], v[2:3], v[12:13]
	v_pk_mul_f32 v[4:5], v[2:3], v[56:57]
	v_pk_fma_f32 v[86:87], v[0:1], v[10:11], v[86:87]
	v_pk_fma_f32 v[4:5], v[0:1], v[54:55], v[4:5]
	v_pk_mul_f32 v[84:85], v[76:77], v[80:81] op_sel_hi:[1,0]
	v_add_f32_e32 v94, v86, v87
	v_add_f32_e32 v95, v4, v5
	v_pk_mul_f32 v[82:83], v[74:75], v[80:81] op_sel_hi:[1,0]
	ds_read_b128 v[66:69], v98 offset:25536
	v_add_f32_dpp v94, v94, v94 quad_perm:[1,0,3,2] row_mask:0xf bank_mask:0xf bound_ctrl:1
	v_add_f32_dpp v95, v95, v95 quad_perm:[1,0,3,2] row_mask:0xf bank_mask:0xf bound_ctrl:1
	ds_read_b128 v[18:21], v98 offset:26304
	v_add_f32_dpp v94, v94, v94 quad_perm:[2,3,0,1] row_mask:0xf bank_mask:0xf bound_ctrl:1
	v_add_f32_dpp v95, v95, v95 quad_perm:[2,3,0,1] row_mask:0xf bank_mask:0xf bound_ctrl:1
	ds_read_b128 v[34:37], v98 offset:26560
	v_add_f32_dpp v94, v94, v94 row_half_mirror row_mask:0xf bank_mask:0xf bound_ctrl:1
	v_add_f32_dpp v95, v95, v95 row_half_mirror row_mask:0xf bank_mask:0xf bound_ctrl:1
	ds_read_b128 v[50:53], v98 offset:25792
	v_add_f32_dpp v94, v94, v94 row_mirror row_mask:0xf bank_mask:0xf bound_ctrl:1
	v_add_f32_dpp v95, v95, v95 row_mirror row_mask:0xf bank_mask:0xf bound_ctrl:1
	v_pk_fma_f32 v[84:85], v[28:29], v[94:95], v[84:85] op_sel_hi:[1,0,1] neg_lo:[0,1,0] neg_hi:[0,1,0]
	v_pk_fma_f32 v[82:83], v[26:27], v[94:95], v[82:83] op_sel_hi:[1,0,1] neg_lo:[0,1,0] neg_hi:[0,1,0]
	v_cndmask_b32_e64 v96, 0, v95, s[16:17]
	v_pk_fma_f32 v[2:3], v[2:3], v[44:45], v[84:85]
	v_pk_fma_f32 v[0:1], v[0:1], v[42:43], v[82:83]
	ds_read_b128 v[74:77], v98 offset:26048
	ds_read_b32 v80, v100 offset:26816
	s_waitcnt lgkmcnt(6)
	v_pk_mul_f32 v[86:87], v[2:3], v[16:17]
	v_pk_mul_f32 v[4:5], v[2:3], v[60:61]
	v_pk_fma_f32 v[86:87], v[0:1], v[14:15], v[86:87]
	v_pk_fma_f32 v[4:5], v[0:1], v[58:59], v[4:5]
	v_pk_mul_f32 v[84:85], v[72:73], v[78:79] op_sel_hi:[1,0]
	v_add_f32_e32 v94, v86, v87
	v_add_f32_e32 v95, v4, v5
	v_pk_mul_f32 v[82:83], v[70:71], v[78:79] op_sel_hi:[1,0]
	ds_read_b128 v[54:57], v98 offset:26880
	v_add_f32_dpp v94, v94, v94 quad_perm:[1,0,3,2] row_mask:0xf bank_mask:0xf bound_ctrl:1
	v_add_f32_dpp v95, v95, v95 quad_perm:[1,0,3,2] row_mask:0xf bank_mask:0xf bound_ctrl:1
	ds_read_b128 v[6:9], v98 offset:27648
	v_add_f32_dpp v94, v94, v94 quad_perm:[2,3,0,1] row_mask:0xf bank_mask:0xf bound_ctrl:1
	v_add_f32_dpp v95, v95, v95 quad_perm:[2,3,0,1] row_mask:0xf bank_mask:0xf bound_ctrl:1
	ds_read_b128 v[22:25], v98 offset:27904
	v_add_f32_dpp v94, v94, v94 row_half_mirror row_mask:0xf bank_mask:0xf bound_ctrl:1
	v_add_f32_dpp v95, v95, v95 row_half_mirror row_mask:0xf bank_mask:0xf bound_ctrl:1
	ds_read_b128 v[38:41], v98 offset:27136
	v_add_f32_dpp v94, v94, v94 row_mirror row_mask:0xf bank_mask:0xf bound_ctrl:1
	v_add_f32_dpp v95, v95, v95 row_mirror row_mask:0xf bank_mask:0xf bound_ctrl:1
	v_pk_fma_f32 v[84:85], v[32:33], v[94:95], v[84:85] op_sel_hi:[1,0,1] neg_lo:[0,1,0] neg_hi:[0,1,0]
	v_pk_fma_f32 v[82:83], v[30:31], v[94:95], v[82:83] op_sel_hi:[1,0,1] neg_lo:[0,1,0] neg_hi:[0,1,0]
	v_cndmask_b32_e64 v96, v96, v95, s[18:19]
	v_pk_fma_f32 v[2:3], v[2:3], v[48:49], v[84:85]
	v_pk_fma_f32 v[0:1], v[0:1], v[46:47], v[82:83]
	ds_read_b128 v[70:73], v98 offset:27392
	ds_read_b32 v78, v100 offset:28160
	s_waitcnt lgkmcnt(6)
	v_pk_mul_f32 v[86:87], v[2:3], v[20:21]
	v_pk_mul_f32 v[4:5], v[2:3], v[64:65]
	v_pk_fma_f32 v[86:87], v[0:1], v[18:19], v[86:87]
	v_pk_fma_f32 v[4:5], v[0:1], v[62:63], v[4:5]
	v_pk_mul_f32 v[84:85], v[76:77], v[80:81] op_sel_hi:[1,0]
	v_add_f32_e32 v94, v86, v87
	v_add_f32_e32 v95, v4, v5
	v_pk_mul_f32 v[82:83], v[74:75], v[80:81] op_sel_hi:[1,0]
	ds_read_b128 v[58:61], v98 offset:28224
	v_add_f32_dpp v94, v94, v94 quad_perm:[1,0,3,2] row_mask:0xf bank_mask:0xf bound_ctrl:1
	v_add_f32_dpp v95, v95, v95 quad_perm:[1,0,3,2] row_mask:0xf bank_mask:0xf bound_ctrl:1
	ds_read_b128 v[10:13], v98 offset:28992
	v_add_f32_dpp v94, v94, v94 quad_perm:[2,3,0,1] row_mask:0xf bank_mask:0xf bound_ctrl:1
	v_add_f32_dpp v95, v95, v95 quad_perm:[2,3,0,1] row_mask:0xf bank_mask:0xf bound_ctrl:1
	ds_read_b128 v[26:29], v98 offset:29248
	v_add_f32_dpp v94, v94, v94 row_half_mirror row_mask:0xf bank_mask:0xf bound_ctrl:1
	v_add_f32_dpp v95, v95, v95 row_half_mirror row_mask:0xf bank_mask:0xf bound_ctrl:1
	ds_read_b128 v[42:45], v98 offset:28480
	v_add_f32_dpp v94, v94, v94 row_mirror row_mask:0xf bank_mask:0xf bound_ctrl:1
	v_add_f32_dpp v95, v95, v95 row_mirror row_mask:0xf bank_mask:0xf bound_ctrl:1
	v_pk_fma_f32 v[84:85], v[36:37], v[94:95], v[84:85] op_sel_hi:[1,0,1] neg_lo:[0,1,0] neg_hi:[0,1,0]
	v_pk_fma_f32 v[82:83], v[34:35], v[94:95], v[82:83] op_sel_hi:[1,0,1] neg_lo:[0,1,0] neg_hi:[0,1,0]
	v_cndmask_b32_e64 v96, v96, v95, s[20:21]
	v_pk_fma_f32 v[2:3], v[2:3], v[52:53], v[84:85]
	v_pk_fma_f32 v[0:1], v[0:1], v[50:51], v[82:83]
	ds_read_b128 v[74:77], v98 offset:28736
	ds_read_b32 v80, v100 offset:29504
	s_waitcnt lgkmcnt(6)
	v_pk_mul_f32 v[86:87], v[2:3], v[8:9]
	v_pk_mul_f32 v[4:5], v[2:3], v[68:69]
	v_pk_fma_f32 v[86:87], v[0:1], v[6:7], v[86:87]
	v_pk_fma_f32 v[4:5], v[0:1], v[66:67], v[4:5]
	v_pk_mul_f32 v[84:85], v[72:73], v[78:79] op_sel_hi:[1,0]
	v_add_f32_e32 v94, v86, v87
	v_add_f32_e32 v95, v4, v5
	v_pk_mul_f32 v[82:83], v[70:71], v[78:79] op_sel_hi:[1,0]
	ds_read_b128 v[62:65], v98 offset:29568
	v_add_f32_dpp v94, v94, v94 quad_perm:[1,0,3,2] row_mask:0xf bank_mask:0xf bound_ctrl:1
	v_add_f32_dpp v95, v95, v95 quad_perm:[1,0,3,2] row_mask:0xf bank_mask:0xf bound_ctrl:1
	ds_read_b128 v[14:17], v98 offset:30336
	v_add_f32_dpp v94, v94, v94 quad_perm:[2,3,0,1] row_mask:0xf bank_mask:0xf bound_ctrl:1
	v_add_f32_dpp v95, v95, v95 quad_perm:[2,3,0,1] row_mask:0xf bank_mask:0xf bound_ctrl:1
	ds_read_b128 v[30:33], v98 offset:30592
	v_add_f32_dpp v94, v94, v94 row_half_mirror row_mask:0xf bank_mask:0xf bound_ctrl:1
	v_add_f32_dpp v95, v95, v95 row_half_mirror row_mask:0xf bank_mask:0xf bound_ctrl:1
	ds_read_b128 v[46:49], v98 offset:29824
	v_add_f32_dpp v94, v94, v94 row_mirror row_mask:0xf bank_mask:0xf bound_ctrl:1
	v_add_f32_dpp v95, v95, v95 row_mirror row_mask:0xf bank_mask:0xf bound_ctrl:1
	v_pk_fma_f32 v[84:85], v[24:25], v[94:95], v[84:85] op_sel_hi:[1,0,1] neg_lo:[0,1,0] neg_hi:[0,1,0]
	v_pk_fma_f32 v[82:83], v[22:23], v[94:95], v[82:83] op_sel_hi:[1,0,1] neg_lo:[0,1,0] neg_hi:[0,1,0]
	v_cndmask_b32_e64 v96, v96, v95, s[22:23]
	v_pk_fma_f32 v[2:3], v[2:3], v[40:41], v[84:85]
	v_pk_fma_f32 v[0:1], v[0:1], v[38:39], v[82:83]
	ds_read_b128 v[70:73], v98 offset:30080
	ds_read_b32 v78, v100 offset:30848
	s_waitcnt lgkmcnt(6)
	v_pk_mul_f32 v[86:87], v[2:3], v[12:13]
	v_pk_mul_f32 v[4:5], v[2:3], v[56:57]
	v_pk_fma_f32 v[86:87], v[0:1], v[10:11], v[86:87]
	v_pk_fma_f32 v[4:5], v[0:1], v[54:55], v[4:5]
	v_pk_mul_f32 v[84:85], v[76:77], v[80:81] op_sel_hi:[1,0]
	v_add_f32_e32 v94, v86, v87
	v_add_f32_e32 v95, v4, v5
	v_pk_mul_f32 v[82:83], v[74:75], v[80:81] op_sel_hi:[1,0]
	ds_read_b128 v[66:69], v98 offset:30912
	v_add_f32_dpp v94, v94, v94 quad_perm:[1,0,3,2] row_mask:0xf bank_mask:0xf bound_ctrl:1
	v_add_f32_dpp v95, v95, v95 quad_perm:[1,0,3,2] row_mask:0xf bank_mask:0xf bound_ctrl:1
	ds_read_b128 v[18:21], v98 offset:31680
	v_add_f32_dpp v94, v94, v94 quad_perm:[2,3,0,1] row_mask:0xf bank_mask:0xf bound_ctrl:1
	v_add_f32_dpp v95, v95, v95 quad_perm:[2,3,0,1] row_mask:0xf bank_mask:0xf bound_ctrl:1
	ds_read_b128 v[34:37], v98 offset:31936
	v_add_f32_dpp v94, v94, v94 row_half_mirror row_mask:0xf bank_mask:0xf bound_ctrl:1
	v_add_f32_dpp v95, v95, v95 row_half_mirror row_mask:0xf bank_mask:0xf bound_ctrl:1
	ds_read_b128 v[50:53], v98 offset:31168
	v_add_f32_dpp v94, v94, v94 row_mirror row_mask:0xf bank_mask:0xf bound_ctrl:1
	v_add_f32_dpp v95, v95, v95 row_mirror row_mask:0xf bank_mask:0xf bound_ctrl:1
	v_pk_fma_f32 v[84:85], v[28:29], v[94:95], v[84:85] op_sel_hi:[1,0,1] neg_lo:[0,1,0] neg_hi:[0,1,0]
	v_pk_fma_f32 v[82:83], v[26:27], v[94:95], v[82:83] op_sel_hi:[1,0,1] neg_lo:[0,1,0] neg_hi:[0,1,0]
	v_cndmask_b32_e64 v96, v96, v95, s[24:25]
	v_pk_fma_f32 v[2:3], v[2:3], v[44:45], v[84:85]
	v_pk_fma_f32 v[0:1], v[0:1], v[42:43], v[82:83]
	ds_read_b128 v[74:77], v98 offset:31424
	ds_read_b32 v80, v100 offset:32192
	s_waitcnt lgkmcnt(6)
	v_pk_mul_f32 v[86:87], v[2:3], v[16:17]
	v_pk_mul_f32 v[4:5], v[2:3], v[60:61]
	v_pk_fma_f32 v[86:87], v[0:1], v[14:15], v[86:87]
	v_pk_fma_f32 v[4:5], v[0:1], v[58:59], v[4:5]
	v_pk_mul_f32 v[84:85], v[72:73], v[78:79] op_sel_hi:[1,0]
	v_add_f32_e32 v94, v86, v87
	v_add_f32_e32 v95, v4, v5
	v_pk_mul_f32 v[82:83], v[70:71], v[78:79] op_sel_hi:[1,0]
	ds_read_b128 v[54:57], v98 offset:32256
	v_add_f32_dpp v94, v94, v94 quad_perm:[1,0,3,2] row_mask:0xf bank_mask:0xf bound_ctrl:1
	v_add_f32_dpp v95, v95, v95 quad_perm:[1,0,3,2] row_mask:0xf bank_mask:0xf bound_ctrl:1
	ds_read_b128 v[6:9], v98 offset:33024
	v_add_f32_dpp v94, v94, v94 quad_perm:[2,3,0,1] row_mask:0xf bank_mask:0xf bound_ctrl:1
	v_add_f32_dpp v95, v95, v95 quad_perm:[2,3,0,1] row_mask:0xf bank_mask:0xf bound_ctrl:1
	ds_read_b128 v[22:25], v98 offset:33280
	v_add_f32_dpp v94, v94, v94 row_half_mirror row_mask:0xf bank_mask:0xf bound_ctrl:1
	v_add_f32_dpp v95, v95, v95 row_half_mirror row_mask:0xf bank_mask:0xf bound_ctrl:1
	ds_read_b128 v[38:41], v98 offset:32512
	v_add_f32_dpp v94, v94, v94 row_mirror row_mask:0xf bank_mask:0xf bound_ctrl:1
	v_add_f32_dpp v95, v95, v95 row_mirror row_mask:0xf bank_mask:0xf bound_ctrl:1
	v_pk_fma_f32 v[84:85], v[32:33], v[94:95], v[84:85] op_sel_hi:[1,0,1] neg_lo:[0,1,0] neg_hi:[0,1,0]
	v_pk_fma_f32 v[82:83], v[30:31], v[94:95], v[82:83] op_sel_hi:[1,0,1] neg_lo:[0,1,0] neg_hi:[0,1,0]
	v_cndmask_b32_e64 v96, v96, v95, s[26:27]
	v_pk_fma_f32 v[2:3], v[2:3], v[48:49], v[84:85]
	v_pk_fma_f32 v[0:1], v[0:1], v[46:47], v[82:83]
	ds_read_b128 v[70:73], v98 offset:32768
	ds_read_b32 v78, v100 offset:33536
	s_waitcnt lgkmcnt(6)
	v_pk_mul_f32 v[86:87], v[2:3], v[20:21]
	v_pk_mul_f32 v[4:5], v[2:3], v[64:65]
	v_pk_fma_f32 v[86:87], v[0:1], v[18:19], v[86:87]
	v_pk_fma_f32 v[4:5], v[0:1], v[62:63], v[4:5]
	v_pk_mul_f32 v[84:85], v[76:77], v[80:81] op_sel_hi:[1,0]
	v_add_f32_e32 v94, v86, v87
	v_add_f32_e32 v95, v4, v5
	v_pk_mul_f32 v[82:83], v[74:75], v[80:81] op_sel_hi:[1,0]
	ds_read_b128 v[58:61], v98 offset:33600
	v_add_f32_dpp v94, v94, v94 quad_perm:[1,0,3,2] row_mask:0xf bank_mask:0xf bound_ctrl:1
	v_add_f32_dpp v95, v95, v95 quad_perm:[1,0,3,2] row_mask:0xf bank_mask:0xf bound_ctrl:1
	ds_read_b128 v[10:13], v98 offset:34368
	v_add_f32_dpp v94, v94, v94 quad_perm:[2,3,0,1] row_mask:0xf bank_mask:0xf bound_ctrl:1
	v_add_f32_dpp v95, v95, v95 quad_perm:[2,3,0,1] row_mask:0xf bank_mask:0xf bound_ctrl:1
	ds_read_b128 v[26:29], v98 offset:34624
	v_add_f32_dpp v94, v94, v94 row_half_mirror row_mask:0xf bank_mask:0xf bound_ctrl:1
	v_add_f32_dpp v95, v95, v95 row_half_mirror row_mask:0xf bank_mask:0xf bound_ctrl:1
	ds_read_b128 v[42:45], v98 offset:33856
	v_add_f32_dpp v94, v94, v94 row_mirror row_mask:0xf bank_mask:0xf bound_ctrl:1
	v_add_f32_dpp v95, v95, v95 row_mirror row_mask:0xf bank_mask:0xf bound_ctrl:1
	v_pk_fma_f32 v[84:85], v[36:37], v[94:95], v[84:85] op_sel_hi:[1,0,1] neg_lo:[0,1,0] neg_hi:[0,1,0]
	v_pk_fma_f32 v[82:83], v[34:35], v[94:95], v[82:83] op_sel_hi:[1,0,1] neg_lo:[0,1,0] neg_hi:[0,1,0]
	v_cndmask_b32_e64 v96, v96, v95, s[28:29]
	v_pk_fma_f32 v[2:3], v[2:3], v[52:53], v[84:85]
	v_pk_fma_f32 v[0:1], v[0:1], v[50:51], v[82:83]
	ds_read_b128 v[74:77], v98 offset:34112
	ds_read_b32 v80, v100 offset:34880
	s_waitcnt lgkmcnt(6)
	v_pk_mul_f32 v[86:87], v[2:3], v[8:9]
	v_pk_mul_f32 v[4:5], v[2:3], v[68:69]
	v_pk_fma_f32 v[86:87], v[0:1], v[6:7], v[86:87]
	v_pk_fma_f32 v[4:5], v[0:1], v[66:67], v[4:5]
	v_pk_mul_f32 v[84:85], v[72:73], v[78:79] op_sel_hi:[1,0]
	v_add_f32_e32 v94, v86, v87
	v_add_f32_e32 v95, v4, v5
	v_pk_mul_f32 v[82:83], v[70:71], v[78:79] op_sel_hi:[1,0]
	ds_read_b128 v[62:65], v98 offset:34944
	v_add_f32_dpp v94, v94, v94 quad_perm:[1,0,3,2] row_mask:0xf bank_mask:0xf bound_ctrl:1
	v_add_f32_dpp v95, v95, v95 quad_perm:[1,0,3,2] row_mask:0xf bank_mask:0xf bound_ctrl:1
	ds_read_b128 v[14:17], v98 offset:35712
	v_add_f32_dpp v94, v94, v94 quad_perm:[2,3,0,1] row_mask:0xf bank_mask:0xf bound_ctrl:1
	v_add_f32_dpp v95, v95, v95 quad_perm:[2,3,0,1] row_mask:0xf bank_mask:0xf bound_ctrl:1
	ds_read_b128 v[30:33], v98 offset:35968
	v_add_f32_dpp v94, v94, v94 row_half_mirror row_mask:0xf bank_mask:0xf bound_ctrl:1
	v_add_f32_dpp v95, v95, v95 row_half_mirror row_mask:0xf bank_mask:0xf bound_ctrl:1
	ds_read_b128 v[46:49], v98 offset:35200
	v_add_f32_dpp v94, v94, v94 row_mirror row_mask:0xf bank_mask:0xf bound_ctrl:1
	v_add_f32_dpp v95, v95, v95 row_mirror row_mask:0xf bank_mask:0xf bound_ctrl:1
	v_pk_fma_f32 v[84:85], v[24:25], v[94:95], v[84:85] op_sel_hi:[1,0,1] neg_lo:[0,1,0] neg_hi:[0,1,0]
	v_pk_fma_f32 v[82:83], v[22:23], v[94:95], v[82:83] op_sel_hi:[1,0,1] neg_lo:[0,1,0] neg_hi:[0,1,0]
	v_cndmask_b32_e64 v96, v96, v95, s[30:31]
	v_pk_fma_f32 v[2:3], v[2:3], v[40:41], v[84:85]
	v_pk_fma_f32 v[0:1], v[0:1], v[38:39], v[82:83]
	ds_read_b128 v[70:73], v98 offset:35456
	ds_read_b32 v78, v100 offset:36224
	s_waitcnt lgkmcnt(6)
	v_pk_mul_f32 v[86:87], v[2:3], v[12:13]
	v_pk_mul_f32 v[4:5], v[2:3], v[56:57]
	v_pk_fma_f32 v[86:87], v[0:1], v[10:11], v[86:87]
	v_pk_fma_f32 v[4:5], v[0:1], v[54:55], v[4:5]
	v_pk_mul_f32 v[84:85], v[76:77], v[80:81] op_sel_hi:[1,0]
	v_add_f32_e32 v94, v86, v87
	v_add_f32_e32 v95, v4, v5
	v_pk_mul_f32 v[82:83], v[74:75], v[80:81] op_sel_hi:[1,0]
	ds_read_b128 v[66:69], v98 offset:36288
	v_add_f32_dpp v94, v94, v94 quad_perm:[1,0,3,2] row_mask:0xf bank_mask:0xf bound_ctrl:1
	v_add_f32_dpp v95, v95, v95 quad_perm:[1,0,3,2] row_mask:0xf bank_mask:0xf bound_ctrl:1
	ds_read_b128 v[18:21], v98 offset:37056
	v_add_f32_dpp v94, v94, v94 quad_perm:[2,3,0,1] row_mask:0xf bank_mask:0xf bound_ctrl:1
	v_add_f32_dpp v95, v95, v95 quad_perm:[2,3,0,1] row_mask:0xf bank_mask:0xf bound_ctrl:1
	ds_read_b128 v[34:37], v98 offset:37312
	v_add_f32_dpp v94, v94, v94 row_half_mirror row_mask:0xf bank_mask:0xf bound_ctrl:1
	v_add_f32_dpp v95, v95, v95 row_half_mirror row_mask:0xf bank_mask:0xf bound_ctrl:1
	ds_read_b128 v[50:53], v98 offset:36544
	v_add_f32_dpp v94, v94, v94 row_mirror row_mask:0xf bank_mask:0xf bound_ctrl:1
	v_add_f32_dpp v95, v95, v95 row_mirror row_mask:0xf bank_mask:0xf bound_ctrl:1
	v_pk_fma_f32 v[84:85], v[28:29], v[94:95], v[84:85] op_sel_hi:[1,0,1] neg_lo:[0,1,0] neg_hi:[0,1,0]
	v_pk_fma_f32 v[82:83], v[26:27], v[94:95], v[82:83] op_sel_hi:[1,0,1] neg_lo:[0,1,0] neg_hi:[0,1,0]
	v_cndmask_b32_e64 v96, v96, v95, s[34:35]
	v_pk_fma_f32 v[2:3], v[2:3], v[44:45], v[84:85]
	v_pk_fma_f32 v[0:1], v[0:1], v[42:43], v[82:83]
	ds_read_b128 v[74:77], v98 offset:36800
	ds_read_b32 v80, v100 offset:37568
	s_waitcnt lgkmcnt(6)
	v_pk_mul_f32 v[86:87], v[2:3], v[16:17]
	v_pk_mul_f32 v[4:5], v[2:3], v[60:61]
	v_pk_fma_f32 v[86:87], v[0:1], v[14:15], v[86:87]
	v_pk_fma_f32 v[4:5], v[0:1], v[58:59], v[4:5]
	v_pk_mul_f32 v[84:85], v[72:73], v[78:79] op_sel_hi:[1,0]
	v_add_f32_e32 v94, v86, v87
	v_add_f32_e32 v95, v4, v5
	v_pk_mul_f32 v[82:83], v[70:71], v[78:79] op_sel_hi:[1,0]
	ds_read_b128 v[54:57], v98 offset:37632
	v_add_f32_dpp v94, v94, v94 quad_perm:[1,0,3,2] row_mask:0xf bank_mask:0xf bound_ctrl:1
	v_add_f32_dpp v95, v95, v95 quad_perm:[1,0,3,2] row_mask:0xf bank_mask:0xf bound_ctrl:1
	ds_read_b128 v[6:9], v98 offset:38400
	v_add_f32_dpp v94, v94, v94 quad_perm:[2,3,0,1] row_mask:0xf bank_mask:0xf bound_ctrl:1
	v_add_f32_dpp v95, v95, v95 quad_perm:[2,3,0,1] row_mask:0xf bank_mask:0xf bound_ctrl:1
	ds_read_b128 v[22:25], v98 offset:38656
	v_add_f32_dpp v94, v94, v94 row_half_mirror row_mask:0xf bank_mask:0xf bound_ctrl:1
	v_add_f32_dpp v95, v95, v95 row_half_mirror row_mask:0xf bank_mask:0xf bound_ctrl:1
	ds_read_b128 v[38:41], v98 offset:37888
	v_add_f32_dpp v94, v94, v94 row_mirror row_mask:0xf bank_mask:0xf bound_ctrl:1
	v_add_f32_dpp v95, v95, v95 row_mirror row_mask:0xf bank_mask:0xf bound_ctrl:1
	v_pk_fma_f32 v[84:85], v[32:33], v[94:95], v[84:85] op_sel_hi:[1,0,1] neg_lo:[0,1,0] neg_hi:[0,1,0]
	v_pk_fma_f32 v[82:83], v[30:31], v[94:95], v[82:83] op_sel_hi:[1,0,1] neg_lo:[0,1,0] neg_hi:[0,1,0]
	v_cndmask_b32_e64 v96, v96, v95, s[36:37]
	v_pk_fma_f32 v[2:3], v[2:3], v[48:49], v[84:85]
	v_pk_fma_f32 v[0:1], v[0:1], v[46:47], v[82:83]
	ds_read_b128 v[70:73], v98 offset:38144
	ds_read_b32 v78, v100 offset:38912
	s_waitcnt lgkmcnt(6)
	v_pk_mul_f32 v[86:87], v[2:3], v[20:21]
	v_pk_mul_f32 v[4:5], v[2:3], v[64:65]
	v_pk_fma_f32 v[86:87], v[0:1], v[18:19], v[86:87]
	v_pk_fma_f32 v[4:5], v[0:1], v[62:63], v[4:5]
	v_pk_mul_f32 v[84:85], v[76:77], v[80:81] op_sel_hi:[1,0]
	v_add_f32_e32 v94, v86, v87
	v_add_f32_e32 v95, v4, v5
	v_pk_mul_f32 v[82:83], v[74:75], v[80:81] op_sel_hi:[1,0]
	ds_read_b128 v[58:61], v98 offset:38976
	v_add_f32_dpp v94, v94, v94 quad_perm:[1,0,3,2] row_mask:0xf bank_mask:0xf bound_ctrl:1
	v_add_f32_dpp v95, v95, v95 quad_perm:[1,0,3,2] row_mask:0xf bank_mask:0xf bound_ctrl:1
	ds_read_b128 v[10:13], v98 offset:39744
	v_add_f32_dpp v94, v94, v94 quad_perm:[2,3,0,1] row_mask:0xf bank_mask:0xf bound_ctrl:1
	v_add_f32_dpp v95, v95, v95 quad_perm:[2,3,0,1] row_mask:0xf bank_mask:0xf bound_ctrl:1
	ds_read_b128 v[26:29], v98 offset:40000
	v_add_f32_dpp v94, v94, v94 row_half_mirror row_mask:0xf bank_mask:0xf bound_ctrl:1
	v_add_f32_dpp v95, v95, v95 row_half_mirror row_mask:0xf bank_mask:0xf bound_ctrl:1
	ds_read_b128 v[42:45], v98 offset:39232
	v_add_f32_dpp v94, v94, v94 row_mirror row_mask:0xf bank_mask:0xf bound_ctrl:1
	v_add_f32_dpp v95, v95, v95 row_mirror row_mask:0xf bank_mask:0xf bound_ctrl:1
	v_pk_fma_f32 v[84:85], v[36:37], v[94:95], v[84:85] op_sel_hi:[1,0,1] neg_lo:[0,1,0] neg_hi:[0,1,0]
	v_pk_fma_f32 v[82:83], v[34:35], v[94:95], v[82:83] op_sel_hi:[1,0,1] neg_lo:[0,1,0] neg_hi:[0,1,0]
	v_cndmask_b32_e64 v96, v96, v95, s[38:39]
	v_pk_fma_f32 v[2:3], v[2:3], v[52:53], v[84:85]
	v_pk_fma_f32 v[0:1], v[0:1], v[50:51], v[82:83]
	ds_read_b128 v[74:77], v98 offset:39488
	ds_read_b32 v80, v100 offset:40256
	s_waitcnt lgkmcnt(6)
	v_pk_mul_f32 v[86:87], v[2:3], v[8:9]
	v_pk_mul_f32 v[4:5], v[2:3], v[68:69]
	v_pk_fma_f32 v[86:87], v[0:1], v[6:7], v[86:87]
	v_pk_fma_f32 v[4:5], v[0:1], v[66:67], v[4:5]
	v_pk_mul_f32 v[84:85], v[72:73], v[78:79] op_sel_hi:[1,0]
	v_add_f32_e32 v94, v86, v87
	v_add_f32_e32 v95, v4, v5
	v_pk_mul_f32 v[82:83], v[70:71], v[78:79] op_sel_hi:[1,0]
	ds_read_b128 v[62:65], v98 offset:40320
	v_add_f32_dpp v94, v94, v94 quad_perm:[1,0,3,2] row_mask:0xf bank_mask:0xf bound_ctrl:1
	v_add_f32_dpp v95, v95, v95 quad_perm:[1,0,3,2] row_mask:0xf bank_mask:0xf bound_ctrl:1
	ds_read_b128 v[14:17], v98 offset:41088
	v_add_f32_dpp v94, v94, v94 quad_perm:[2,3,0,1] row_mask:0xf bank_mask:0xf bound_ctrl:1
	v_add_f32_dpp v95, v95, v95 quad_perm:[2,3,0,1] row_mask:0xf bank_mask:0xf bound_ctrl:1
	ds_read_b128 v[30:33], v98 offset:41344
	v_add_f32_dpp v94, v94, v94 row_half_mirror row_mask:0xf bank_mask:0xf bound_ctrl:1
	v_add_f32_dpp v95, v95, v95 row_half_mirror row_mask:0xf bank_mask:0xf bound_ctrl:1
	ds_read_b128 v[46:49], v98 offset:40576
	v_add_f32_dpp v94, v94, v94 row_mirror row_mask:0xf bank_mask:0xf bound_ctrl:1
	v_add_f32_dpp v95, v95, v95 row_mirror row_mask:0xf bank_mask:0xf bound_ctrl:1
	v_pk_fma_f32 v[84:85], v[24:25], v[94:95], v[84:85] op_sel_hi:[1,0,1] neg_lo:[0,1,0] neg_hi:[0,1,0]
	v_pk_fma_f32 v[82:83], v[22:23], v[94:95], v[82:83] op_sel_hi:[1,0,1] neg_lo:[0,1,0] neg_hi:[0,1,0]
	v_cndmask_b32_e64 v96, v96, v95, s[40:41]
	v_pk_fma_f32 v[2:3], v[2:3], v[40:41], v[84:85]
	v_pk_fma_f32 v[0:1], v[0:1], v[38:39], v[82:83]
	ds_read_b128 v[70:73], v98 offset:40832
	ds_read_b32 v78, v100 offset:41600
	s_waitcnt lgkmcnt(6)
; template <int CH>
; __device__ __forceinline__ void scan_unit(const Args& a, int l, int unit, unsigned char* lds) {
;     ...
;         for (int ch = 0; ch < nch; ch += 2) {
;             SC_SCAN(0, ch);
;             __syncthreads();
;             if (ch + 1 < nch) { SC_SCAN(1, ch + 1); __syncthreads(); }
	v_pk_mul_f32 v[86:87], v[2:3], v[12:13]
	v_pk_mul_f32 v[4:5], v[2:3], v[56:57]
	v_pk_fma_f32 v[86:87], v[0:1], v[10:11], v[86:87]
	v_pk_fma_f32 v[4:5], v[0:1], v[54:55], v[4:5]
	v_pk_mul_f32 v[84:85], v[76:77], v[80:81] op_sel_hi:[1,0]
	v_add_f32_e32 v94, v86, v87
	v_add_f32_e32 v95, v4, v5
	v_pk_mul_f32 v[82:83], v[74:75], v[80:81] op_sel_hi:[1,0]
	ds_read_b128 v[66:69], v98 offset:41664
	v_add_f32_dpp v94, v94, v94 quad_perm:[1,0,3,2] row_mask:0xf bank_mask:0xf bound_ctrl:1
	v_add_f32_dpp v95, v95, v95 quad_perm:[1,0,3,2] row_mask:0xf bank_mask:0xf bound_ctrl:1
	ds_read_b128 v[18:21], v98 offset:42432
	v_add_f32_dpp v94, v94, v94 quad_perm:[2,3,0,1] row_mask:0xf bank_mask:0xf bound_ctrl:1
	v_add_f32_dpp v95, v95, v95 quad_perm:[2,3,0,1] row_mask:0xf bank_mask:0xf bound_ctrl:1
	ds_read_b128 v[34:37], v98 offset:42688
	v_add_f32_dpp v94, v94, v94 row_half_mirror row_mask:0xf bank_mask:0xf bound_ctrl:1
	v_add_f32_dpp v95, v95, v95 row_half_mirror row_mask:0xf bank_mask:0xf bound_ctrl:1
	ds_read_b128 v[50:53], v98 offset:41920
	v_add_f32_dpp v94, v94, v94 row_mirror row_mask:0xf bank_mask:0xf bound_ctrl:1
	v_add_f32_dpp v95, v95, v95 row_mirror row_mask:0xf bank_mask:0xf bound_ctrl:1
	v_pk_fma_f32 v[84:85], v[28:29], v[94:95], v[84:85] op_sel_hi:[1,0,1] neg_lo:[0,1,0] neg_hi:[0,1,0]
	v_pk_fma_f32 v[82:83], v[26:27], v[94:95], v[82:83] op_sel_hi:[1,0,1] neg_lo:[0,1,0] neg_hi:[0,1,0]
	v_cndmask_b32_e64 v96, v96, v95, s[42:43]
	v_pk_fma_f32 v[2:3], v[2:3], v[44:45], v[84:85]
	v_pk_fma_f32 v[0:1], v[0:1], v[42:43], v[82:83]
	ds_read_b128 v[74:77], v98 offset:42176
	ds_read_b32 v80, v100 offset:42944
	s_waitcnt lgkmcnt(6)
	v_pk_mul_f32 v[86:87], v[2:3], v[16:17]
	v_pk_mul_f32 v[4:5], v[2:3], v[60:61]
	v_pk_fma_f32 v[86:87], v[0:1], v[14:15], v[86:87]
	v_pk_fma_f32 v[4:5], v[0:1], v[58:59], v[4:5]
	v_pk_mul_f32 v[84:85], v[72:73], v[78:79] op_sel_hi:[1,0]
	v_add_f32_e32 v94, v86, v87
	v_add_f32_e32 v95, v4, v5
	v_pk_mul_f32 v[82:83], v[70:71], v[78:79] op_sel_hi:[1,0]
	s_nop 0
	v_add_f32_dpp v94, v94, v94 quad_perm:[1,0,3,2] row_mask:0xf bank_mask:0xf bound_ctrl:1
	v_add_f32_dpp v95, v95, v95 quad_perm:[1,0,3,2] row_mask:0xf bank_mask:0xf bound_ctrl:1
	s_nop 0
	v_add_f32_dpp v94, v94, v94 quad_perm:[2,3,0,1] row_mask:0xf bank_mask:0xf bound_ctrl:1
	v_add_f32_dpp v95, v95, v95 quad_perm:[2,3,0,1] row_mask:0xf bank_mask:0xf bound_ctrl:1
	s_nop 0
	v_add_f32_dpp v94, v94, v94 row_half_mirror row_mask:0xf bank_mask:0xf bound_ctrl:1
	v_add_f32_dpp v95, v95, v95 row_half_mirror row_mask:0xf bank_mask:0xf bound_ctrl:1
	s_nop 0
	v_add_f32_dpp v94, v94, v94 row_mirror row_mask:0xf bank_mask:0xf bound_ctrl:1
	v_add_f32_dpp v95, v95, v95 row_mirror row_mask:0xf bank_mask:0xf bound_ctrl:1
	v_pk_fma_f32 v[84:85], v[32:33], v[94:95], v[84:85] op_sel_hi:[1,0,1] neg_lo:[0,1,0] neg_hi:[0,1,0]
	v_pk_fma_f32 v[82:83], v[30:31], v[94:95], v[82:83] op_sel_hi:[1,0,1] neg_lo:[0,1,0] neg_hi:[0,1,0]
	v_cndmask_b32_e64 v96, v96, v95, s[44:45]
	v_pk_fma_f32 v[2:3], v[2:3], v[48:49], v[84:85]
	v_pk_fma_f32 v[0:1], v[0:1], v[46:47], v[82:83]
	s_waitcnt lgkmcnt(0)
	s_barrier
	ds_read_b128 v[54:57], v89
	ds_read_b128 v[6:9], v89 offset:768
	ds_read_b128 v[22:25], v89 offset:1024
	ds_read_b128 v[38:41], v89 offset:256
	ds_read_b128 v[70:73], v89 offset:512
	ds_read_b32 v78, v101 offset:1280
	s_waitcnt lgkmcnt(6)
	v_pk_mul_f32 v[86:87], v[2:3], v[20:21]
	v_pk_mul_f32 v[4:5], v[2:3], v[64:65]
	v_pk_fma_f32 v[86:87], v[0:1], v[18:19], v[86:87]
	v_pk_fma_f32 v[4:5], v[0:1], v[62:63], v[4:5]
	v_pk_mul_f32 v[84:85], v[76:77], v[80:81] op_sel_hi:[1,0]
	v_add_f32_e32 v94, v86, v87
	v_add_f32_e32 v95, v4, v5
	v_pk_mul_f32 v[82:83], v[74:75], v[80:81] op_sel_hi:[1,0]
	ds_read_b128 v[58:61], v89 offset:1344
	v_add_f32_dpp v94, v94, v94 quad_perm:[1,0,3,2] row_mask:0xf bank_mask:0xf bound_ctrl:1
	v_add_f32_dpp v95, v95, v95 quad_perm:[1,0,3,2] row_mask:0xf bank_mask:0xf bound_ctrl:1
	ds_read_b128 v[10:13], v89 offset:2112
	v_add_f32_dpp v94, v94, v94 quad_perm:[2,3,0,1] row_mask:0xf bank_mask:0xf bound_ctrl:1
	v_add_f32_dpp v95, v95, v95 quad_perm:[2,3,0,1] row_mask:0xf bank_mask:0xf bound_ctrl:1
	ds_read_b128 v[26:29], v89 offset:2368
	v_add_f32_dpp v94, v94, v94 row_half_mirror row_mask:0xf bank_mask:0xf bound_ctrl:1
	v_add_f32_dpp v95, v95, v95 row_half_mirror row_mask:0xf bank_mask:0xf bound_ctrl:1
	ds_read_b128 v[42:45], v89 offset:1600
	v_add_f32_dpp v94, v94, v94 row_mirror row_mask:0xf bank_mask:0xf bound_ctrl:1
	v_add_f32_dpp v95, v95, v95 row_mirror row_mask:0xf bank_mask:0xf bound_ctrl:1
	v_pk_fma_f32 v[84:85], v[36:37], v[94:95], v[84:85] op_sel_hi:[1,0,1] neg_lo:[0,1,0] neg_hi:[0,1,0]
	v_pk_fma_f32 v[82:83], v[34:35], v[94:95], v[82:83] op_sel_hi:[1,0,1] neg_lo:[0,1,0] neg_hi:[0,1,0]
	v_cndmask_b32_e64 v96, v96, v95, s[14:15]
	v_pk_fma_f32 v[2:3], v[2:3], v[52:53], v[84:85]
	v_pk_fma_f32 v[0:1], v[0:1], v[50:51], v[82:83]
	ds_read_b128 v[74:77], v89 offset:1856
	ds_read_b32 v80, v101 offset:2624
	s_add_i32 s4, s4, 1
	s_cmp_lt_u32 s4, 64
	s_cbranch_scc1 .Lscan_top
	s_setprio 0
	s_waitcnt lgkmcnt(0)
	v_pk_mul_f32 v[4:5], v[2:3], v[68:69]
	s_nop 0
	v_pk_fma_f32 v[4:5], v[0:1], v[66:67], v[4:5]
	s_nop 0
	v_add_f32_e32 v95, v4, v5
	s_nop 1
	v_add_f32_dpp v95, v95, v95 quad_perm:[1,0,3,2] row_mask:0xf bank_mask:0xf bound_ctrl:1
	s_nop 1
	v_add_f32_dpp v95, v95, v95 quad_perm:[2,3,0,1] row_mask:0xf bank_mask:0xf bound_ctrl:1
	s_nop 1
	v_add_f32_dpp v95, v95, v95 row_half_mirror row_mask:0xf bank_mask:0xf bound_ctrl:1
	s_nop 1
	v_add_f32_dpp v95, v95, v95 row_mirror row_mask:0xf bank_mask:0xf bound_ctrl:1
	s_nop 0
	v_cndmask_b32_e64 v96, v96, v95, s[12:13]
	global_store_dword v[90:91], v96, off
	s_mov_b32 s22, s78
